# barrier: leader bumps XGEN before its acquire invalidate (28 sites)
# speedup vs baseline: 1.0016x; 1.0016x over previous
; #define LAS __attribute__((address_space(3)))
; __device__ __forceinline__ int tid_fresh() { int t = threadIdx.x; asm volatile("" : "+v"(t)); return t; }
; __device__ __forceinline__ void xcd_barrier(const XcdBarrier& b) {
;     ...
;             __builtin_amdgcn_fence(__ATOMIC_RELEASE, "agent");
;             asm volatile("s_waitcnt vmcnt(0)" ::: "memory");
;             const unsigned og = xb_add(&bar[XB_TOP], 1u);
;             const unsigned tg = og / nx;
;             if (og + 1u == (tg + 1u) * nx) xb_add(&bar[XB_TOPGEN], 1u);
;             else XB_SPIN(xb_ld(&bar[XB_TOPGEN]) == tg, bar);
;             __builtin_amdgcn_fence(__ATOMIC_ACQUIRE, "agent");
;             xb_add(&bar[XB_XGEN(b.x)], 1u);
;             asm volatile("s_waitcnt vmcnt(0)" ::: "memory");
;         } else {
;             XB_SPIN(xb_ld(&bar[XB_XGEN(b.x)]) == gen, bar);
;             __builtin_amdgcn_fence(__ATOMIC_ACQUIRE, "agent");
;             asm volatile("s_waitcnt vmcnt(0)" ::: "memory");
;         }
;     }
;     __syncthreads();
; __device__ __forceinline__ void ssm_item(const Args& a, LAS unsigned char* wl, int j, int L, bool samp, int n, int g, int lane) {
;     float hr = 0.f, hi = 0.f;
;     if (samp) { hr = a.in[2][((size_t)(j * DB + n) * NG + g) * NP + lane]; hi = a.in[3][((size_t)(j * DB + n) * NG + g) * NP + lane]; }
;     ssm_core<true>(a, wl, j, L, samp, n, g, 0, samp ? DSEQ : SEQ, hr, hi, lane);
;     const size_t so = ((size_t)(j * (samp ? DB : NB) + n) * NG + g) * NP + lane;
;     a.out[(samp ? O_SRS : O_SRP) + so] = hr; a.out[(samp ? O_SIS : O_SIP) + so] = hi;
; }
; template <bool CONV> __device__ __forceinline__ void ph_ssm(const Args& a, LAS unsigned char* lds, int j, int L, int nblk, int b) {
;     const int tid = tid_fresh(); const int wave = __builtin_amdgcn_readfirstlane(tid >> 6), lane = tid & 63;
;     LAS unsigned char* wl = CONV ? (wave < 2 ? lds + wave * SSM_WLDS : lds + 2 * SSM_WLDS + (wave - 2) * CONV_LDS) : lds + wave * SSM_WLDS;
;     if (wave < 2) { for (int it = b * 2 + wave; it < NB * NG; it += nblk * 2) ssm_item(a, wl, j, L, false, it / NG, it % NG, lane); }
;     else { for (int it = b * 6 + (wave - 2); it < DB * NG; it += nblk * 6) ssm_item(a, wl, j, L, true, it / NG, it % NG, lane);
;         if (CONV && (wave & 2)) conv_worker(a, (LAS float*)wl, b * 4 + (wave & 1) + ((wave >> 2) << 1), nblk * 4, lane); }
.LBB0_114:
	s_or_b64 exec, exec, s[4:5]
	s_mov_b64 s[4:5], exec
	v_mbcnt_lo_u32_b32 v1, s4, 0
	v_mbcnt_hi_u32_b32 v1, s5, v1
	v_cmp_eq_u32_e32 vcc, 0, v1
	s_and_saveexec_b64 s[8:9], vcc
	s_cbranch_execz .LBB0_116
	s_bcnt1_i32_b64 s0, s[4:5]
	v_mov_b32_e32 v1, 0x2000
	v_mov_b32_e32 v2, s0
	global_atomic_add v1, v2, s[6:7] offset:1024
.LBB0_116:
	s_or_b64 exec, exec, s[8:9]
	s_waitcnt vmcnt(0)
	buffer_inv sc1
	s_waitcnt vmcnt(0)
.LBB0_117:
	s_or_b64 exec, exec, s[2:3]
	s_waitcnt lgkmcnt(0)
	v_mov_b32_e32 v1, v0
	s_barrier
	s_add_i32 s0, 0, 0xffffe000
	v_readfirstlane_b32 s26, v1
	s_ashr_i32 s39, s26, 6
	s_cmp_lt_i32 s39, 2
	s_movk_i32 s1, 0x3100
	s_cselect_b32 s1, s1, 0x4100
	s_cselect_b32 s0, 0, s0
	s_mul_i32 s1, s1, s39
	s_add_i32 s33, s0, s1
	v_and_b32_e32 v130, 63, v1
	s_cmp_gt_i32 s39, 1
	s_mov_b64 s[2:3], -1
	s_cbranch_scc0 .LBB0_278
	s_mul_i32 s2, s90, 6
	s_add_i32 s2, s2, s39
	s_add_i32 s27, s2, -2
	s_cmpk_gt_i32 s27, 0xfff
	s_cbranch_scc1 .LBB0_123
	v_and_b32_e32 v64, 15, v1
	v_mov_b32_e32 v7, s33
	s_movk_i32 s2, 0x210
	v_mad_u32_u24 v14, v64, s2, v7
	s_load_dwordx4 s[12:15], s[86:87], 0xf0
	s_load_dwordx4 s[8:11], s[86:87], 0x8
	s_load_dwordx2 s[2:3], s[86:87], 0x18
	v_mov_b32_e32 v63, 0
	v_lshrrev_b32_e32 v5, 4, v130
	v_lshlrev_b32_e32 v2, 13, v64
	v_mov_b32_e32 v3, v63
	v_mul_u32_u24_e32 v13, 0x210, v64
	v_mul_i32_i24_e32 v16, 0xfffffdf4, v64
	s_waitcnt lgkmcnt(0)
	v_lshl_add_u64 v[74:75], s[8:9], 0, v[2:3]
	v_add3_u32 v2, v13, v16, s1
	v_lshlrev_b32_e32 v3, 8, v5
	v_lshlrev_b32_e32 v11, 6, v64
	v_lshlrev_b32_e32 v15, 5, v5
	s_load_dwordx2 s[4:5], s[86:87], 0x70
	v_add3_u32 v2, v2, v3, s0
	v_lshlrev_b32_e32 v8, 4, v130
	v_mov_b32_e32 v9, v63
	v_add_u32_e32 v90, 0x2100, v2
	v_add_u32_e32 v2, s1, v11
	v_and_b32_e32 v3, 32, v15
	v_lshrrev_b32_e32 v4, 1, v130
	v_lshl_add_u64 v[8:9], s[14:15], 0, v[8:9]
	s_mov_b64 s[6:7], 0x2fb22000
	s_add_u32 s8, s12, 0x7480000
	v_add3_u32 v2, v2, v3, s0
	v_lshlrev_b32_e32 v62, 3, v130
	v_and_b32_e32 v4, 8, v4
	v_lshlrev_b32_e32 v6, 2, v64
	v_lshl_add_u64 v[66:67], v[8:9], 0, s[6:7]
	s_mov_b64 s[6:7], 0x2fd22000
	s_addc_u32 s9, s13, 0
	v_add_u32_e32 v91, 0x2100, v2
	v_lshlrev_b32_e32 v2, 10, v1
	v_lshl_add_u32 v10, v4, 2, s33
	v_add_u32_e32 v12, s33, v6
	v_mul_u32_u24_e32 v17, 0x840, v5
	v_lshl_add_u64 v[68:69], v[8:9], 0, s[6:7]
	v_lshl_add_u64 v[8:9], s[14:15], 0, v[62:63]
	s_mov_b64 s[6:7], 0x2f900000
	v_mov_b32_e32 v7, v63
	s_add_u32 s16, s12, 0x7680000
	v_and_b32_e32 v62, 0xc000, v2
	s_mov_b32 s12, 0
	v_cmp_gt_u32_e32 vcc, 32, v130
	v_lshl_add_u32 v65, v130, 2, s33
	s_mul_i32 s28, s89, 6
	v_lshl_add_u64 v[70:71], v[8:9], 0, s[6:7]
	s_waitcnt lgkmcnt(0)
	v_lshl_add_u64 v[72:73], s[4:5], 0, v[6:7]
	s_addc_u32 s17, s13, 0
	v_lshl_add_u64 v[76:77], s[14:15], 0, v[62:63]
	s_movk_i32 s29, 0x1000
	v_lshlrev_b32_e32 v62, 2, v4
	s_mov_b64 s[18:19], 0x60000
	s_mov_b32 s30, 0x60000
	s_mov_b64 s[20:21], 0x40000
	s_mov_b32 s31, 0x40000
	s_mov_b64 s[22:23], 0x20000
	s_mov_b32 s34, 0x20000
	v_add_u32_e32 v92, v10, v11
	s_mov_b32 s13, s12
	s_mov_b32 s14, s12
	s_mov_b32 s15, s12
	v_add_u32_e32 v93, v12, v17
	v_add_u32_e32 v94, v14, v15
	s_movk_i32 s35, 0x7fff
	s_mov_b32 s36, 0x2f101000
	s_mov_b32 s37, 0x2f103000

; template <class Epi, class Sched, bool ABLK = false, bool ALIGN_EPI = true, bool SP2 = true, bool BBLK = true>
; __device__ __forceinline__ void gemm_phase(LAS unsigned char* lds, const Gemm g, const Sched& S, const Epi& E) {
;     const int tid = tid_fresh(), wid = __builtin_amdgcn_readfirstlane(tid >> 6), lane = tid & 63, wr = wid >> 2, wc = wid & 3, fr = lane & 15, fq = lane >> 4;
;     unsigned voffA[2], voffB[2];
; #pragma unroll
;     for (int i = 0; i < 2; ++i) { int R, C; stage_rc(tid * 16 + i * 8192, R, C); const int r32 = Epi::PERM ? perm32(R & 31) : (R & 31);
;         const int Rb = Epi::ADJ ? 64 * (R >> 5) + r32 : (R & ~31) + r32;
;         voffA[i] = (unsigned)(R * (ABLK ? 64 : g.lda) + C) * 2u; voffB[i] = BBLK ? (unsigned)(R * 64 + C) * 2u : (unsigned)(Rb * g.ldb + C) * 2u; }
;     const size_t kstep = (size_t)(BK * 2);
;     const size_t hstepA = (size_t)HALF * (ABLK ? 64 : g.lda) * 2, hstepB = BBLK ? (size_t)16384 : (size_t)(Epi::ADJ ? 32 : HALF) * g.ldb * 2;
;     const size_t tstepB = BBLK ? ((size_t)g.ldb / 64) * 32768 : (size_t)BM * g.ldb * 2;
;     const size_t kstepB = BBLK ? (size_t)32768 : kstep;
;     auto b_k0 = [&](int k0) -> size_t { return BBLK ? (size_t)(k0 / BK) * 32768 : (size_t)k0 * 2; };
;     const unsigned ldsw = (unsigned)wid * 1024u;
;     const int aoff = lds_byte(wr * 64 + fr, fq * 8), boff = lds_byte(wc * 32 + fr, fq * 8);
;     ...
;     Unit cur, nxt; int ui = 0;
;     if (!S.next(0, cur)) return;
;     f32x4 acc[2][2][4][2];
; #pragma unroll
;     for (int a = 0; a < 2; ++a)
; #pragma unroll
;         for (int b = 0; b < 2; ++b)
; #pragma unroll
;             for (int m = 0; m < 4; ++m)
; #pragma unroll
;                 for (int n = 0; n < 2; ++n) acc[a][b][m][n] = (f32x4){0.f, 0.f, 0.f, 0.f};
;     bf16x8 At[4][2], B0[2][2], B1[2][2];
;     auto a_unit = [&](const Unit& u) -> const char* { return ABLK ? (const char*)g.A + (size_t)u.pm * ((size_t)g.lda / 64) * 32768 : (const char*)g.A + (size_t)u.pm * 2 * hstepA; };
;     auto a_tile = [&](const char* ub, int tau) -> const char* { return ub + (size_t)tau * (ABLK ? (size_t)32768 : kstep); };
;     const char* uA = a_unit(cur); int tbA = cur.k0 / BK;
;     const char* cA = a_tile(uA, tbA); const char* cB = (const char*)g.Bt + (size_t)cur.pn * tstepB + b_k0(cur.k0);
;     S.a_ready(cur);
;     if constexpr (SP2) {
.LBB0_340:
	s_or_b64 exec, exec, s[8:9]
	s_waitcnt vmcnt(0)
	buffer_inv sc1
	s_waitcnt vmcnt(0)
.LBB0_341:
	s_or_b64 exec, exec, s[2:3]
	s_add_u32 s16, s68, 0x1e100000
	s_addc_u32 s17, s69, 0
	s_and_b32 s91, s90, 7
	s_ashr_i32 s70, s90, 3
	s_cmpk_lt_i32 s70, 0x50
	s_waitcnt vmcnt(22)
	v_mov_b32_e32 v6, v0
	s_cselect_b64 s[0:1], -1, 0
	s_waitcnt lgkmcnt(0)
	s_barrier
	v_writelane_b32 v252, s0, 12
	s_cmpk_gt_i32 s70, 0x4f
	v_readfirstlane_b32 s4, v6
	v_writelane_b32 v252, s1, 13
	s_cbranch_scc1 .LBB0_357
	v_lshlrev_b32_e32 v1, 4, v6
	v_add_u32_e32 v2, 0x2000, v1
	v_ashrrev_i32_e32 v3, 31, v2
	v_lshrrev_b32_e32 v3, 22, v3
	v_add_u32_e32 v3, v2, v3
	v_ashrrev_i32_e32 v7, 10, v3
	v_mul_i32_i24_e32 v4, 0x400, v7
	v_sub_u32_e32 v2, v2, v4
	v_lshrrev_b32_e32 v4, 4, v2
	v_bitop3_b32 v2, v4, v2, 32 bitop3:0x6c
	v_ashrrev_i32_e32 v4, 31, v2
	v_lshrrev_b32_e32 v4, 26, v4
	v_add_u32_e32 v4, v2, v4
	v_ashrrev_i32_e32 v8, 6, v4
	v_and_b32_e32 v4, 0xc0, v4
	v_sub_u32_e32 v2, v2, v4
	v_mov_b32_e32 v4, 1
	v_lshlrev_b32_e32 v3, 5, v7
	v_ashrrev_i16_sdwa v2, v4, sext(v2) dst_sel:DWORD dst_unused:UNUSED_PAD src0_sel:DWORD src1_sel:BYTE_0
	v_and_b32_e32 v3, 32, v3
	v_bfe_i32 v9, v2, 0, 16
	v_add_u32_e32 v2, v3, v9
	v_lshlrev_b32_e32 v3, 3, v7
	v_and_b32_e32 v3, -16, v3
	v_add_u32_e32 v3, v8, v3
	v_lshlrev_b32_e32 v5, 7, v3
	v_lshl_add_u32 v130, v2, 1, v5
	s_movk_i32 s7, 0xf80
	v_mad_u64_u32 v[132:133], s[2:3], v3, s7, v[130:131]
	v_bfe_i32 v3, v6, 27, 1
	v_lshrrev_b32_e32 v3, 22, v3
	v_add_u32_e32 v3, v1, v3
	v_and_b32_e32 v3, 0xfffffc00, v3
	v_sub_u32_e32 v1, v1, v3
	v_lshrrev_b32_e32 v3, 4, v1
	v_bitop3_b32 v3, v3, v1, 32 bitop3:0x6c
	v_ashrrev_i32_e32 v1, 31, v1
	v_lshrrev_b32_e32 v1, 26, v1
	v_ashrrev_i32_e32 v2, 31, v6
	v_add_u32_e32 v1, v3, v1
	v_lshrrev_b32_e32 v2, 26, v2
	s_waitcnt vmcnt(21)
	v_ashrrev_i32_e32 v11, 6, v1
	v_add_u32_e32 v2, v6, v2
	v_mul_i32_i24_e32 v1, 64, v11
	v_ashrrev_i32_e32 v10, 6, v2
	v_sub_u32_e32 v1, v3, v1
	v_lshlrev_b32_e32 v2, 5, v10
	v_ashrrev_i16_sdwa v1, v4, sext(v1) dst_sel:DWORD dst_unused:UNUSED_PAD src0_sel:DWORD src1_sel:BYTE_0
	v_and_b32_e32 v2, 32, v2
	v_bfe_i32 v12, v1, 0, 16
	v_add_u32_e32 v1, v2, v12
	v_lshlrev_b32_e32 v2, 3, v10
	v_and_b32_e32 v2, -16, v2
	s_add_u32 s0, s68, 0x100000
	v_add_u32_e32 v2, v11, v2
	s_addc_u32 s1, s69, 0
	s_ashr_i32 s6, s4, 6
	v_lshlrev_b32_e32 v3, 7, v2
	s_ashr_i32 s5, s4, 8
	s_lshl_b32 s33, s6, 10
	v_lshl_add_u32 v134, v1, 1, v3
	s_add_u32 s36, s68, 0x2d100000
	v_mad_u64_u32 v[136:137], s[2:3], v2, s7, v[134:135]
	s_addc_u32 s37, s69, 0
	s_lshr_b32 s2, s70, 31
	s_add_i32 s2, s70, s2
	s_ashr_i32 s20, s2, 1
	s_sub_i32 s2, s91, s20
	s_lshl_b32 s2, s2, 1
	s_add_i32 s22, s2, s70
	s_ashr_i32 s21, s20, 31
	s_ashr_i32 s23, s22, 31
	s_lshl_b64 s[2:3], s[20:21], 20
	s_lshl_b64 s[8:9], s[22:23], 20
	s_add_u32 s26, s0, s8
	s_addc_u32 s27, s1, s9
	s_add_i32 s21, s33, 0
	s_add_i32 m0, s21, 0x10000
	v_mov_b32_e32 v135, 0
	global_load_lds_dwordx4 v134, s[26:27]
	s_add_i32 m0, s21, 0x12000
	s_add_u32 s8, s26, 0x4000
	global_load_lds_dwordx4 v130, s[26:27]
	s_addc_u32 s9, s27, 0
	s_add_i32 m0, s21, 0x14000
	v_mov_b32_e32 v137, v135
	global_load_lds_dwordx4 v134, s[8:9]
	s_add_i32 m0, s21, 0x16000
	s_add_u32 s24, s36, s2
	s_addc_u32 s25, s37, s3
	s_add_i32 s23, s21, 0x2000
	global_load_lds_dwordx4 v130, s[8:9]
	s_mov_b32 m0, s21
	s_add_u32 s2, s24, 0x80000
	global_load_lds_dwordx4 v136, s[24:25]
	s_mov_b32 m0, s23
	s_addc_u32 s3, s25, 0
	s_add_i32 s39, s21, 0x4000
	global_load_lds_dwordx4 v132, s[24:25]
	s_mov_b32 m0, s39
	s_add_i32 s40, s21, 0x6000
	global_load_lds_dwordx4 v136, s[2:3]
	s_mov_b32 m0, s40
	v_mov_b32_e32 v133, v135
	global_load_lds_dwordx4 v132, s[2:3]
	s_cmp_eq_u32 s5, 1
	s_mov_b32 s41, 0
	v_mov_b32_e32 v131, v135
	v_lshl_add_u64 v[2:3], s[24:25], 0, v[136:137]
	s_cselect_b64 s[2:3], -1, 0
	s_cmp_lg_u32 s5, 1
	v_lshl_add_u64 v[4:5], s[24:25], 0, v[132:133]
	s_cbranch_scc1 .LBB0_344
	s_barrier

; __device__ __forceinline__ int tid_fresh() { int t = threadIdx.x; asm volatile("" : "+v"(t)); return t; }
; __device__ __forceinline__ void ph_ln(const Args& a, int L, int which, bool final_, bool split, bool wr_x, bool res_inputs, int nblk, int b) {
;     unsigned char* ws = a.ws; const bf16_t* P = (const bf16_t*)(ws + WS_SCR + SCR_PART);
;     const bf16_t* Z = (const bf16_t*)(ws + WS_Z); float* Xo = final_ ? a.out : (float*)(ws + WS_X); bf16_t* XB = (bf16_t*)(ws + WS_XB);
;     auto lo = [](unsigned w) -> float { return __builtin_bit_cast(float, w << 16); }; auto hi = [](unsigned w) -> float { return __builtin_bit_cast(float, w & 0xffff0000u); };
;     const float* gam = a.in[which ? 26 : 24] + (size_t)L * D; const float* bet = a.in[which ? 27 : 25] + (size_t)L * D;
;     const int tid = tid_fresh(); const int lane = tid & 63, gw = b * 8 + (tid >> 6), ngw = nblk * 8;
;     f32x4 gg[4][2], bb[4][2];
; #pragma unroll
;     for (int j = 0; j < 4; ++j)
; #pragma unroll
;         for (int h = 0; h < 2; ++h) { gg[j][h] = *(const f32x4*)(gam + 512 * j + 8 * lane + 4 * h); bb[j][h] = *(const f32x4*)(bet + 512 * j + 8 * lane + 4 * h); }
;     u32x4 zc[4], xc[4];
;     auto ldrow = [&](int r) { const u32x4* zr = (const u32x4*)(Z + (size_t)r * D) + lane;
; #pragma unroll
;         for (int j = 0; j < 4; ++j) zc[j] = zr[64 * j];
;         if (!res_inputs) { const u32x4* xr = (const u32x4*)(XB + (size_t)r * D) + lane;
; #pragma unroll
;             for (int j = 0; j < 4; ++j) xc[j] = xr[64 * j]; } };
;     if (gw < M) ldrow(gw);
;     for (int r = gw; r < M; r += ngw) {
;         float v[4][8];
; #pragma unroll
;         for (int j = 0; j < 4; ++j)
; #pragma unroll
;             for (int e = 0; e < 4; ++e) { v[j][2 * e] = lo(zc[j][e]); v[j][2 * e + 1] = hi(zc[j][e]); }
;         if (!res_inputs) {
; #pragma unroll
;             for (int j = 0; j < 4; ++j)
; #pragma unroll
;                 for (int e = 0; e < 4; ++e) { v[j][2 * e] += ALPHA * lo(xc[j][e]); v[j][2 * e + 1] += ALPHA * hi(xc[j][e]); } }
;         if (r + ngw < M) ldrow(r + ngw);
.LBB0_408:
	s_or_b64 exec, exec, s[8:9]
	s_waitcnt vmcnt(0)
	buffer_inv sc1
	s_waitcnt vmcnt(0)
.LBB0_409:
	s_or_b64 exec, exec, s[2:3]
	s_waitcnt lgkmcnt(0)
	v_mov_b32_e32 v1, v0
	s_barrier
	s_lshl_b32 s94, s90, 3
	v_ashrrev_i32_e32 v66, 6, v1
	v_add_u32_e32 v68, s94, v66
	s_movk_i32 s0, 0x2800
	s_lshl_b32 s74, s89, 3
	v_cmp_gt_i32_e32 vcc, s0, v68
	s_and_saveexec_b64 s[2:3], vcc
	s_cbranch_execz .LBB0_414
	s_load_dwordx4 s[12:15], s[86:87], 0xc0
	s_load_dwordx4 s[8:11], s[86:87], 0x0
	v_ashrrev_i32_e32 v69, 31, v68
	v_lshlrev_b64 v[2:3], 12, v[68:69]
	v_and_b32_e32 v69, 63, v1
	v_mov_b32_e32 v101, 0
	v_lshlrev_b32_e32 v100, 5, v69
	s_waitcnt lgkmcnt(0)
	v_lshl_add_u64 v[10:11], s[14:15], 0, v[100:101]
	s_movk_i32 s1, 0x1000
	v_add_co_u32_e32 v24, vcc, s1, v10
	v_lshl_add_u64 v[26:27], s[12:13], 0, v[100:101]
	s_nop 0
	v_addc_co_u32_e32 v25, vcc, 0, v11, vcc
	s_mov_b64 s[18:19], 0x1800
	v_add_co_u32_e32 v72, vcc, s1, v26
	s_mov_b64 s[20:21], 0x1000
	v_lshl_add_u64 v[2:3], s[68:69], 0, v[2:3]
	v_lshlrev_b32_e32 v98, 4, v69
	v_mov_b32_e32 v99, v101
	v_lshl_add_u64 v[22:23], v[10:11], 0, s[18:19]
	v_lshl_add_u64 v[70:71], v[26:27], 0, s[18:19]
	v_addc_co_u32_e32 v73, vcc, 0, v27, vcc
	v_lshl_add_u64 v[28:29], v[10:11], 0, s[20:21]
	v_lshl_add_u64 v[62:63], v[2:3], 0, v[98:99]
	global_load_dwordx4 v[2:5], v[24:25], off offset:2048
	global_load_dwordx4 v[6:9], v[72:73], off offset:2048
	global_load_dwordx4 v[10:13], v[22:23], off offset:16
	global_load_dwordx4 v[14:17], v[24:25], off
	global_load_dwordx4 v[18:21], v[28:29], off offset:16
	v_lshl_add_u64 v[74:75], v[26:27], 0, s[20:21]
	global_load_dwordx4 v[22:25], v[70:71], off offset:16
	global_load_dwordx4 v[26:29], v[72:73], off
	global_load_dwordx4 v[30:33], v100, s[14:15] offset:2048
	global_load_dwordx4 v[34:37], v100, s[12:13] offset:2048
	global_load_dwordx4 v[38:41], v100, s[14:15] offset:2064
	global_load_dwordx4 v[42:45], v100, s[12:13] offset:2064
	global_load_dwordx4 v[46:49], v100, s[14:15]
	global_load_dwordx4 v[50:53], v100, s[12:13]
	global_load_dwordx4 v[54:57], v100, s[14:15] offset:16
	global_load_dwordx4 v[58:61], v100, s[12:13] offset:16
	s_mov_b64 s[4:5], 0x1e100000
	v_lshl_add_u64 v[64:65], v[62:63], 0, s[4:5]
	s_mov_b32 s4, 0x1e100000
	v_add_co_u32_e32 v70, vcc, s4, v62
	global_load_dwordx4 v[90:93], v[64:65], off offset:1024
	global_load_dwordx4 v[86:89], v[64:65], off offset:2048
	global_load_dwordx4 v[82:85], v[64:65], off offset:3072
	v_addc_co_u32_e32 v71, vcc, 0, v63, vcc
	global_load_dwordx4 v[94:97], v[70:71], off
	global_load_dwordx4 v[62:65], v[74:75], off offset:16
	v_add_u32_e32 v68, s74, v68
	v_ashrrev_i32_e32 v67, 31, v66
	s_ashr_i32 s95, s94, 31
	v_lshlrev_b32_e32 v70, 1, v69
	v_ashrrev_i32_e32 v69, 31, v68
	v_lshl_add_u64 v[106:107], v[66:67], 0, s[94:95]
	v_lshlrev_b64 v[66:67], 12, v[68:69]
	v_lshlrev_b64 v[68:69], 12, v[106:107]
	s_mov_b64 s[4:5], 0x1b900800
	v_lshl_add_u64 v[102:103], s[68:69], 0, v[66:67]
	v_lshl_add_u64 v[66:67], s[68:69], 0, v[68:69]
	s_ashr_i32 s75, s74, 31
	v_lshl_add_u64 v[104:105], v[66:67], 0, s[4:5]
	v_lshlrev_b32_e32 v100, 4, v70
	s_mov_b64 s[12:13], 0
	s_movk_i32 s15, 0x2000
	s_mov_b32 s14, 0x3fd744fd
	v_mov_b32_e32 v1, 0x3727c5ac
	s_mov_b32 s24, 0xf800000
	v_mov_b32_e32 v108, 0x260
	s_movk_i32 s25, 0x27ff
	s_lshl_b64 s[22:23], s[74:75], 12
	s_waitcnt vmcnt(4)
	v_mov_b64_e32 v[74:75], v[90:91]
	s_waitcnt vmcnt(3)
	v_mov_b64_e32 v[70:71], v[86:87]
	s_waitcnt vmcnt(2)
	v_mov_b64_e32 v[66:67], v[82:83]
	v_mov_b64_e32 v[68:69], v[84:85]
	s_waitcnt vmcnt(1)
	v_mov_b64_e32 v[78:79], v[94:95]
	v_mov_b64_e32 v[72:73], v[88:89]
	v_mov_b64_e32 v[76:77], v[92:93]
	v_mov_b64_e32 v[80:81], v[96:97]
	s_branch .LBB0_412

; template <class Epi, class Sched, bool ABLK = false, bool ALIGN_EPI = true, bool SP2 = true, bool BBLK = true>
; __device__ __forceinline__ void gemm_phase(LAS unsigned char* lds, const Gemm g, const Sched& S, const Epi& E) {
;     const int tid = tid_fresh(), wid = __builtin_amdgcn_readfirstlane(tid >> 6), lane = tid & 63, wr = wid >> 2, wc = wid & 3, fr = lane & 15, fq = lane >> 4;
;     unsigned voffA[2], voffB[2];
; #pragma unroll
;     for (int i = 0; i < 2; ++i) { int R, C; stage_rc(tid * 16 + i * 8192, R, C); const int r32 = Epi::PERM ? perm32(R & 31) : (R & 31);
;         const int Rb = Epi::ADJ ? 64 * (R >> 5) + r32 : (R & ~31) + r32;
;         voffA[i] = (unsigned)(R * (ABLK ? 64 : g.lda) + C) * 2u; voffB[i] = BBLK ? (unsigned)(R * 64 + C) * 2u : (unsigned)(Rb * g.ldb + C) * 2u; }
;     const size_t kstep = (size_t)(BK * 2);
;     const size_t hstepA = (size_t)HALF * (ABLK ? 64 : g.lda) * 2, hstepB = BBLK ? (size_t)16384 : (size_t)(Epi::ADJ ? 32 : HALF) * g.ldb * 2;
;     const size_t tstepB = BBLK ? ((size_t)g.ldb / 64) * 32768 : (size_t)BM * g.ldb * 2;
;     const size_t kstepB = BBLK ? (size_t)32768 : kstep;
;     auto b_k0 = [&](int k0) -> size_t { return BBLK ? (size_t)(k0 / BK) * 32768 : (size_t)k0 * 2; };
;     const unsigned ldsw = (unsigned)wid * 1024u;
;     const int aoff = lds_byte(wr * 64 + fr, fq * 8), boff = lds_byte(wc * 32 + fr, fq * 8);
;     ...
;     Unit cur, nxt; int ui = 0;
;     if (!S.next(0, cur)) return;
;     f32x4 acc[2][2][4][2];
; #pragma unroll
;     for (int a = 0; a < 2; ++a)
; #pragma unroll
;         for (int b = 0; b < 2; ++b)
; #pragma unroll
;             for (int m = 0; m < 4; ++m)
; #pragma unroll
;                 for (int n = 0; n < 2; ++n) acc[a][b][m][n] = (f32x4){0.f, 0.f, 0.f, 0.f};
;     bf16x8 At[4][2], B0[2][2], B1[2][2];
;     auto a_unit = [&](const Unit& u) -> const char* { return ABLK ? (const char*)g.A + (size_t)u.pm * ((size_t)g.lda / 64) * 32768 : (const char*)g.A + (size_t)u.pm * 2 * hstepA; };
; template <int L> __device__ __forceinline__ void do_layer(const Args& a, LAS unsigned char* lds, const XcdBarrier& bar, int G, int b) {
;     ...
;     { pg8::Gemm g{XB, (const bf16_t*)(ws + WS_WF1) + (size_t)L * FF * D, D, D}; pg8::BStatOrder S; S.init(M, FF, D, b);
;       EpiFfn1 E{H}; pg8::gemm_phase<EpiFfn1, pg8::BStatOrder>(lds, g, S, E); }
.LBB0_465:
	s_or_b64 exec, exec, s[8:9]
	s_waitcnt vmcnt(0)
	buffer_inv sc1
	s_waitcnt vmcnt(0)
.LBB0_466:
	s_or_b64 exec, exec, s[2:3]
	s_add_u32 s1, s68, 0x23100000
	s_addc_u32 s33, s69, 0
	s_cmpk_lt_i32 s70, 0xa0
	s_waitcnt lgkmcnt(0)
	v_mov_b32_e32 v1, v0
	s_cselect_b64 s[2:3], -1, 0
	s_barrier
	v_writelane_b32 v252, s2, 14
	s_cmpk_gt_i32 s70, 0x9f
	v_readfirstlane_b32 s6, v1
	v_writelane_b32 v252, s3, 15
	s_cbranch_scc1 .LBB0_482
	v_lshlrev_b32_e32 v2, 4, v1
	v_add_u32_e32 v3, 0x2000, v2
	v_ashrrev_i32_e32 v4, 31, v3
	v_lshrrev_b32_e32 v4, 22, v4
	v_add_u32_e32 v4, v3, v4
	v_ashrrev_i32_e32 v6, 10, v4
	v_mul_i32_i24_e32 v5, 0x400, v6
	v_sub_u32_e32 v3, v3, v5
	v_lshrrev_b32_e32 v5, 4, v3
	v_bitop3_b32 v3, v5, v3, 32 bitop3:0x6c
	v_ashrrev_i32_e32 v5, 31, v3
	v_lshrrev_b32_e32 v5, 26, v5
	v_add_u32_e32 v5, v3, v5
	v_ashrrev_i32_e32 v7, 6, v5
	v_and_b32_e32 v5, 0xc0, v5
	v_sub_u32_e32 v3, v3, v5
	v_mov_b32_e32 v5, 1
	v_lshlrev_b32_e32 v4, 5, v6
	v_ashrrev_i16_sdwa v3, v5, sext(v3) dst_sel:DWORD dst_unused:UNUSED_PAD src0_sel:DWORD src1_sel:BYTE_0
	v_and_b32_e32 v4, 32, v4
	v_bfe_i32 v8, v3, 0, 16
	v_add_u32_e32 v3, v4, v8
	v_lshlrev_b32_e32 v4, 3, v6
	v_and_b32_e32 v4, -16, v4
	v_add_u32_e32 v4, v7, v4
	v_lshlrev_b32_e32 v9, 7, v4
	v_lshl_add_u32 v130, v3, 1, v9
	s_movk_i32 s4, 0xf80
	v_mad_u64_u32 v[132:133], s[2:3], v4, s4, v[130:131]
	v_bfe_i32 v4, v1, 27, 1
	v_lshrrev_b32_e32 v4, 22, v4
	v_add_u32_e32 v4, v2, v4
	v_and_b32_e32 v4, 0xfffffc00, v4
	v_sub_u32_e32 v2, v2, v4
	v_lshrrev_b32_e32 v4, 4, v2
	v_bitop3_b32 v4, v4, v2, 32 bitop3:0x6c
	v_ashrrev_i32_e32 v2, 31, v2
	v_lshrrev_b32_e32 v2, 26, v2
	v_ashrrev_i32_e32 v3, 31, v1
	v_add_u32_e32 v2, v4, v2
	v_lshrrev_b32_e32 v3, 26, v3
	v_ashrrev_i32_e32 v10, 6, v2
	v_add_u32_e32 v3, v1, v3
	v_mul_i32_i24_e32 v2, 64, v10
	v_ashrrev_i32_e32 v9, 6, v3
	v_sub_u32_e32 v2, v4, v2
	v_lshlrev_b32_e32 v3, 5, v9
	v_ashrrev_i16_sdwa v2, v5, sext(v2) dst_sel:DWORD dst_unused:UNUSED_PAD src0_sel:DWORD src1_sel:BYTE_0
	v_and_b32_e32 v3, 32, v3
	v_bfe_i32 v11, v2, 0, 16
	v_add_u32_e32 v2, v3, v11
	v_lshlrev_b32_e32 v3, 3, v9
	v_and_b32_e32 v3, -16, v3
	s_add_u32 s0, s68, 0x6900000
	v_add_u32_e32 v3, v10, v3
	s_addc_u32 s39, s69, 0
	s_ashr_i32 s8, s6, 6
	v_lshlrev_b32_e32 v4, 7, v3
	s_ashr_i32 s7, s6, 8
	s_lshl_b32 s40, s8, 10
	v_lshl_add_u32 v134, v2, 1, v4
	s_add_u32 s41, s68, 0x1b900000
	v_mad_u64_u32 v[136:137], s[2:3], v3, s4, v[134:135]
	s_addc_u32 s42, s69, 0
	s_lshr_b32 s2, s70, 30
	s_add_i32 s2, s70, s2
	s_ashr_i32 s22, s2, 2
	s_sub_i32 s2, s91, s22
	s_lshl_b32 s2, s2, 2
	s_add_i32 s24, s2, s70
	s_ashr_i32 s23, s22, 31
	s_ashr_i32 s25, s24, 31
	s_lshl_b64 s[2:3], s[22:23], 20
	s_lshl_b64 s[4:5], s[24:25], 20
	s_add_u32 s28, s0, s4
	s_addc_u32 s29, s39, s5
	s_add_i32 s25, s40, 0
	s_add_i32 m0, s25, 0x10000
	v_mov_b32_e32 v139, 0
	global_load_lds_dwordx4 v134, s[28:29]
	s_add_i32 m0, s25, 0x12000
	s_add_u32 s4, s28, 0x4000
	global_load_lds_dwordx4 v130, s[28:29]
	s_addc_u32 s5, s29, 0
	s_add_i32 m0, s25, 0x14000
	v_mov_b32_e32 v137, v139
	global_load_lds_dwordx4 v134, s[4:5]
	s_add_i32 m0, s25, 0x16000
	s_add_u32 s26, s41, s2
	s_addc_u32 s27, s42, s3
	s_add_i32 s43, s25, 0x2000
	global_load_lds_dwordx4 v130, s[4:5]
	s_mov_b32 m0, s25
	s_add_u32 s2, s26, 0x80000
	global_load_lds_dwordx4 v136, s[26:27]
	s_mov_b32 m0, s43
	s_addc_u32 s3, s27, 0
	s_add_i32 s46, s25, 0x4000
	global_load_lds_dwordx4 v132, s[26:27]
	s_mov_b32 m0, s46
	s_add_i32 s47, s25, 0x6000
	global_load_lds_dwordx4 v136, s[2:3]
	s_mov_b32 m0, s47
	v_mov_b32_e32 v133, v139
	global_load_lds_dwordx4 v132, s[2:3]
	s_cmp_eq_u32 s7, 1
	s_mov_b32 s48, 0
	v_mov_b32_e32 v135, v139
	v_mov_b32_e32 v131, v139
	s_mov_b64 s[4:5], 0x4000
	v_lshl_add_u64 v[2:3], s[26:27], 0, v[136:137]
	s_cselect_b64 s[2:3], -1, 0
	s_cmp_lg_u32 s7, 1
	v_lshl_add_u64 v[4:5], s[26:27], 0, v[132:133]
	s_cbranch_scc1 .LBB0_469
	s_barrier

;     __host__ __device__ bool next(int r, Unit& u) const {
;         const int gidx = 4 * x + (i >> 3);
;         if (r == 0) { u.pm = gidx; u.pn = i & 7; u.k0 = 0; u.nt = ntf; u.part = 0; return true; }
;         if (r == 1) { const int part = gidx & 3; u.pm = 32 + (gidx >> 2); u.pn = i & 7; u.nt = ntf >> 2; u.k0 = part * (ntf >> 2) * BK; u.part = part; return true; }
;         return false;
;     }
; template <int L> __device__ __forceinline__ void do_layer(const Args& a, LAS unsigned char* lds, const XcdBarrier& bar, int G, int b) {
;     ...
;     { pg8::Gemm g{H, (const bf16_t*)(ws + WS_WF2) + (size_t)L * FF * D, FF, FF}; pg8::SplitOrder S; S.init(FF, b);
;       EpiRes E{Z, PS}; pg8::gemm_phase<EpiRes, pg8::SplitOrder, true>(lds, g, S, E); }
.LBB0_533:
	s_or_b64 exec, exec, s[8:9]
	s_waitcnt vmcnt(0)
	buffer_inv sc1
	s_waitcnt vmcnt(0)
.LBB0_534:
	s_or_b64 exec, exec, s[2:3]
	v_mov_b32_e32 v6, v0
	s_waitcnt lgkmcnt(0)
	s_barrier
	s_add_u32 s39, s68, 0xe900000
	v_bfe_i32 v3, v6, 27, 1
	v_lshlrev_b32_e32 v1, 4, v6
	v_lshrrev_b32_e32 v3, 22, v3
	v_add_u32_e32 v3, v1, v3
	v_and_b32_e32 v3, 0xfffffc00, v3
	v_sub_u32_e32 v3, v1, v3
	v_lshrrev_b32_e32 v4, 4, v3
	v_bitop3_b32 v4, v4, v3, 32 bitop3:0x6c
	v_ashrrev_i32_e32 v3, 31, v3
	v_lshrrev_b32_e32 v3, 26, v3
	v_ashrrev_i32_e32 v2, 31, v6
	v_add_u32_e32 v3, v4, v3
	v_lshrrev_b32_e32 v2, 26, v2
	v_ashrrev_i32_e32 v3, 6, v3
	v_add_u32_e32 v2, v6, v2
	v_mul_i32_i24_e32 v8, 64, v3
	v_ashrrev_i32_e32 v2, 6, v2
	v_sub_u32_e32 v4, v4, v8
	v_mov_b32_e32 v8, 1
	v_lshlrev_b32_e32 v5, 3, v2
	v_lshlrev_b32_e32 v7, 5, v2
	v_ashrrev_i16_sdwa v4, v8, sext(v4) dst_sel:DWORD dst_unused:UNUSED_PAD src0_sel:DWORD src1_sel:BYTE_0
	v_and_b32_e32 v5, 0x1fffff0, v5
	v_and_b32_e32 v7, 32, v7
	v_bfe_i32 v4, v4, 0, 16
	v_add_u32_e32 v7, v7, v4
	v_add_lshl_u32 v5, v3, v5, 7
	v_add_u32_e32 v1, 0x2000, v1
	v_lshl_add_u32 v130, v7, 1, v5
	v_ashrrev_i32_e32 v5, 31, v1
	v_lshrrev_b32_e32 v5, 22, v5
	v_add_u32_e32 v5, v1, v5
	v_ashrrev_i32_e32 v5, 10, v5
	v_mul_i32_i24_e32 v7, 0x400, v5
	v_sub_u32_e32 v1, v1, v7
	v_lshrrev_b32_e32 v7, 4, v1
	v_bitop3_b32 v1, v7, v1, 32 bitop3:0x6c
	v_lshlrev_b32_e32 v7, 3, v5
	s_addc_u32 s50, s69, 0
	v_and_b32_e32 v9, 0x1fffff0, v7
	v_ashrrev_i32_e32 v7, 31, v1
	s_lshl_b32 s2, s91, 2
	s_ashr_i32 s3, s90, 6
	v_readfirstlane_b32 s0, v6
	v_lshrrev_b32_e32 v7, 26, v7
	s_add_i32 s82, s2, s3
	s_ashr_i32 s5, s0, 6
	v_add_u32_e32 v10, v1, v7
	s_bfe_u32 s78, s90, 0x30003
	s_ashr_i32 s83, s82, 31
	v_ashrrev_i32_e32 v7, 6, v10
	v_and_b32_e32 v10, 0xc0, v10
	s_ashr_i32 s4, s0, 8
	s_lshl_b32 s51, s5, 10
	s_lshl_b64 s[6:7], s[82:83], 22
	s_lshl_b32 s2, s78, 22
	v_sub_u32_e32 v1, v1, v10
	s_add_u32 s40, s39, s2
	v_lshlrev_b32_e32 v11, 5, v5
	v_ashrrev_i16_sdwa v1, v8, sext(v1) dst_sel:DWORD dst_unused:UNUSED_PAD src0_sel:DWORD src1_sel:BYTE_0
	s_addc_u32 s41, s50, 0
	s_add_i32 s52, s51, 0
	v_and_b32_e32 v11, 32, v11
	v_bfe_i32 v8, v1, 0, 16
	s_add_i32 m0, s52, 0x10000
	v_add_u32_e32 v1, v11, v8
	v_add_lshl_u32 v9, v7, v9, 7
	global_load_lds_dwordx4 v130, s[40:41]
	s_add_i32 m0, s52, 0x12000
	v_lshl_add_u32 v132, v1, 1, v9
	v_writelane_b32 v252, s2, 16
	s_add_u32 s2, s40, 0x4000
	global_load_lds_dwordx4 v132, s[40:41]
	s_addc_u32 s3, s41, 0
	s_add_i32 m0, s52, 0x14000
	v_mov_b32_e32 v131, 0
	global_load_lds_dwordx4 v130, s[2:3]
	s_add_i32 m0, s52, 0x16000
	s_add_u32 s42, s1, s6
	v_writelane_b32 v252, s6, 17
	s_addc_u32 s43, s33, s7
	s_add_i32 s53, s52, 0x2000
	global_load_lds_dwordx4 v132, s[2:3]
	s_mov_b32 m0, s52
	s_add_u32 s2, s42, 0x4000
	global_load_lds_dwordx4 v130, s[42:43]
	s_mov_b32 m0, s53
	s_addc_u32 s3, s43, 0
	s_add_i32 s54, s52, 0x4000
	global_load_lds_dwordx4 v132, s[42:43]
	s_mov_b32 m0, s54
	s_add_i32 s55, s52, 0x6000
	global_load_lds_dwordx4 v130, s[2:3]
	s_mov_b32 m0, s55
	s_cmp_eq_u32 s4, 1
	global_load_lds_dwordx4 v132, s[2:3]
	s_mov_b32 s58, 0
	s_cselect_b64 s[2:3], -1, 0
	s_cmp_lg_u32 s4, 1
	v_mov_b32_e32 v133, v131
	v_writelane_b32 v252, s7, 18
	s_cbranch_scc1 .LBB0_536
	s_barrier

; __device__ __forceinline__ void ph_ln(const Args& a, int L, int which, bool final_, bool split, bool wr_x, bool res_inputs, int nblk, int b) {
;     unsigned char* ws = a.ws; const bf16_t* P = (const bf16_t*)(ws + WS_SCR + SCR_PART);
;     const bf16_t* Z = (const bf16_t*)(ws + WS_Z); float* Xo = final_ ? a.out : (float*)(ws + WS_X); bf16_t* XB = (bf16_t*)(ws + WS_XB);
;     auto lo = [](unsigned w) -> float { return __builtin_bit_cast(float, w << 16); }; auto hi = [](unsigned w) -> float { return __builtin_bit_cast(float, w & 0xffff0000u); };
;     const float* gam = a.in[which ? 26 : 24] + (size_t)L * D; const float* bet = a.in[which ? 27 : 25] + (size_t)L * D;
;     const int tid = tid_fresh(); const int lane = tid & 63, gw = b * 8 + (tid >> 6), ngw = nblk * 8;
;     f32x4 gg[4][2], bb[4][2];
; #pragma unroll
;     for (int j = 0; j < 4; ++j)
; #pragma unroll
;         for (int h = 0; h < 2; ++h) { gg[j][h] = *(const f32x4*)(gam + 512 * j + 8 * lane + 4 * h); bb[j][h] = *(const f32x4*)(bet + 512 * j + 8 * lane + 4 * h); }
;     u32x4 zc[4], xc[4];
;     auto ldrow = [&](int r) { const u32x4* zr = (const u32x4*)(Z + (size_t)r * D) + lane;
; #pragma unroll
;         for (int j = 0; j < 4; ++j) zc[j] = zr[64 * j];
;         if (!res_inputs) { const u32x4* xr = (const u32x4*)(XB + (size_t)r * D) + lane;
; #pragma unroll
;             for (int j = 0; j < 4; ++j) xc[j] = xr[64 * j]; } };
;     if (gw < M) ldrow(gw);
;     for (int r = gw; r < M; r += ngw) {
;         float v[4][8];
; #pragma unroll
;         for (int j = 0; j < 4; ++j)
; #pragma unroll
;             for (int e = 0; e < 4; ++e) { v[j][2 * e] = lo(zc[j][e]); v[j][2 * e + 1] = hi(zc[j][e]); }
;         if (!res_inputs) {
; #pragma unroll
;             for (int j = 0; j < 4; ++j)
; #pragma unroll
;                 for (int e = 0; e < 4; ++e) { v[j][2 * e] += ALPHA * lo(xc[j][e]); v[j][2 * e + 1] += ALPHA * hi(xc[j][e]); } }
;         if (r + ngw < M) ldrow(r + ngw);
;         if (split && r >= MP) {
; #pragma unroll
;             for (int p = 0; p < 3; ++p) { const u32x4* pr = (const u32x4*)(P + ((size_t)p * MS + (r - MP)) * D) + lane;
; #pragma unroll
;                 for (int j = 0; j < 4; ++j) { const u32x4 w = pr[64 * j];
; #pragma unroll
;                     for (int e = 0; e < 4; ++e) { v[j][2 * e] += lo(w[e]); v[j][2 * e + 1] += hi(w[e]); } } } }
.LBB0_595:
	s_or_b64 exec, exec, s[4:5]
	s_mov_b64 s[4:5], exec
	v_mbcnt_lo_u32_b32 v1, s4, 0
	v_mbcnt_hi_u32_b32 v1, s5, v1
	v_cmp_eq_u32_e32 vcc, 0, v1
	s_and_saveexec_b64 s[8:9], vcc
	s_cbranch_execz .LBB0_597
	s_bcnt1_i32_b64 s1, s[4:5]
	v_mov_b32_e32 v1, 0x2000
	v_mov_b32_e32 v2, s1
	global_atomic_add v1, v2, s[6:7] offset:1024
.LBB0_597:
	s_or_b64 exec, exec, s[8:9]
	s_waitcnt vmcnt(0)
	buffer_inv sc1
	s_waitcnt vmcnt(0)
.LBB0_598:
	s_or_b64 exec, exec, s[2:3]
	s_waitcnt lgkmcnt(0)
	v_mov_b32_e32 v1, v0
	s_barrier
	s_movk_i32 s1, 0x2800
	v_ashrrev_i32_e32 v66, 6, v1
	v_add_u32_e32 v156, s94, v66
	v_cmp_gt_i32_e32 vcc, s1, v156
	s_and_saveexec_b64 s[2:3], vcc
	s_cbranch_execz .LBB0_605
	s_load_dwordx4 s[8:11], s[86:87], 0xd0
	v_and_b32_e32 v1, 63, v1
	v_mov_b32_e32 v131, 0
	v_lshlrev_b32_e32 v130, 5, v1
	s_mov_b64 s[4:5], 0x1800
	s_waitcnt lgkmcnt(0)
	v_lshl_add_u64 v[10:11], s[10:11], 0, v[130:131]
	v_add_co_u32_e32 v24, vcc, 0x1000, v10
	v_lshl_add_u64 v[26:27], s[8:9], 0, v[130:131]
	s_nop 0
	v_addc_co_u32_e32 v25, vcc, 0, v11, vcc
	v_lshl_add_u64 v[22:23], v[10:11], 0, s[4:5]
	v_lshl_add_u64 v[50:51], v[26:27], 0, s[4:5]
	v_add_co_u32_e32 v52, vcc, 0x1000, v26
	s_mov_b64 s[4:5], 0x1000
	s_nop 0
	v_addc_co_u32_e32 v53, vcc, 0, v27, vcc
	v_lshl_add_u64 v[28:29], v[10:11], 0, s[4:5]
	v_ashrrev_i32_e32 v157, 31, v156
	global_load_dwordx4 v[2:5], v[24:25], off offset:2048
	global_load_dwordx4 v[6:9], v[52:53], off offset:2048
	global_load_dwordx4 v[10:13], v[22:23], off offset:16
	global_load_dwordx4 v[14:17], v[24:25], off
	global_load_dwordx4 v[18:21], v[28:29], off offset:16
	v_lshl_add_u64 v[54:55], v[26:27], 0, s[4:5]
	global_load_dwordx4 v[22:25], v[50:51], off offset:16
	global_load_dwordx4 v[26:29], v[52:53], off
	global_load_dwordx4 v[30:33], v[54:55], off offset:16
	global_load_dwordx4 v[34:37], v130, s[10:11] offset:2048
	global_load_dwordx4 v[38:41], v130, s[8:9] offset:2048
	global_load_dwordx4 v[42:45], v130, s[10:11] offset:2064
	global_load_dwordx4 v[46:49], v130, s[8:9] offset:2064
	v_lshlrev_b64 v[50:51], 12, v[156:157]
	v_lshlrev_b32_e32 v132, 4, v1
	v_mov_b32_e32 v133, v131
	v_lshl_add_u64 v[50:51], s[68:69], 0, v[50:51]
	v_lshl_add_u64 v[50:51], v[50:51], 0, v[132:133]
	s_mov_b64 s[4:5], 0x1e100000
	v_lshl_add_u64 v[52:53], v[50:51], 0, s[4:5]
	s_mov_b32 s4, 0x1e100000
	v_add_co_u32_e32 v54, vcc, s4, v50
	s_mov_b64 s[4:5], 0x1b900000
	s_nop 0
	v_addc_co_u32_e32 v55, vcc, 0, v51, vcc
	global_load_dwordx4 v[114:117], v[52:53], off offset:1024
	global_load_dwordx4 v[106:109], v[52:53], off offset:2048
	global_load_dwordx4 v[122:125], v[54:55], off
	global_load_dwordx4 v[98:101], v[52:53], off offset:3072
	v_lshl_add_u64 v[68:69], v[50:51], 0, s[4:5]
	s_mov_b32 s4, 0x1b900000
	v_add_co_u32_e32 v70, vcc, s4, v50
	s_mov_b64 s[4:5], 0x3c900000
	s_nop 0
	v_addc_co_u32_e32 v71, vcc, 0, v51, vcc
	global_load_dwordx4 v[118:121], v[68:69], off offset:1024
	global_load_dwordx4 v[110:113], v[68:69], off offset:2048
	global_load_dwordx4 v[126:129], v[70:71], off
	global_load_dwordx4 v[102:105], v[68:69], off offset:3072
	global_load_dwordx4 v[50:53], v130, s[10:11]
	global_load_dwordx4 v[54:57], v130, s[8:9]
	global_load_dwordx4 v[58:61], v130, s[10:11] offset:16
	global_load_dwordx4 v[62:65], v130, s[8:9] offset:16
	v_lshl_add_u64 v[68:69], s[68:69], 0, v[132:133]
	v_ashrrev_i32_e32 v67, 31, v66
	s_ashr_i32 s95, s94, 31
	v_lshl_add_u64 v[134:135], v[68:69], 0, s[4:5]
	v_add_u32_e32 v68, s74, v156
	v_lshl_add_u64 v[66:67], v[66:67], 0, s[94:95]
	v_ashrrev_i32_e32 v69, 31, v68
	v_lshlrev_b64 v[66:67], 12, v[66:67]
	v_lshlrev_b64 v[68:69], 12, v[68:69]
	v_lshl_add_u64 v[66:67], s[68:69], 0, v[66:67]
	s_mov_b64 s[4:5], 0x1b900800
	v_lshl_add_u64 v[136:137], s[68:69], 0, v[68:69]
	s_ashr_i32 s75, s74, 31
	v_lshl_add_u64 v[138:139], v[66:67], 0, s[4:5]
	s_lshl_b64 s[10:11], s[74:75], 12
	s_mov_b64 s[12:13], 0
	s_movk_i32 s15, 0x27ff
	s_mov_b32 s14, 0x3fd744fd
	s_movk_i32 s16, 0x1fff
	s_mov_b32 s17, 0x800000
	s_mov_b32 s18, 0x1000000
	v_mov_b32_e32 v1, 0x3727c5ac
	s_mov_b32 s19, 0xf800000
	v_mov_b32_e32 v157, 0x260
	s_waitcnt vmcnt(11)
	v_mov_b64_e32 v[74:75], v[114:115]
	s_waitcnt vmcnt(10)
	v_mov_b64_e32 v[70:71], v[106:107]
	s_waitcnt vmcnt(9)
	v_mov_b64_e32 v[78:79], v[122:123]
	s_waitcnt vmcnt(8)
	v_mov_b64_e32 v[66:67], v[98:99]
	s_waitcnt vmcnt(7)
	v_mov_b64_e32 v[90:91], v[118:119]
	s_waitcnt vmcnt(6)
	v_mov_b64_e32 v[86:87], v[110:111]
	s_waitcnt vmcnt(5)
	v_mov_b64_e32 v[94:95], v[126:127]
	s_waitcnt vmcnt(4)
	v_mov_b64_e32 v[82:83], v[102:103]
	v_mov_b64_e32 v[68:69], v[100:101]
	v_mov_b64_e32 v[72:73], v[108:109]
	v_mov_b64_e32 v[76:77], v[116:117]
	v_mov_b64_e32 v[80:81], v[124:125]
	v_mov_b64_e32 v[84:85], v[104:105]
	v_mov_b64_e32 v[88:89], v[112:113]
	v_mov_b64_e32 v[92:93], v[120:121]
	v_mov_b64_e32 v[96:97], v[128:129]
	s_branch .LBB0_601

;     __host__ __device__ bool next(int r, Unit& u) const {
;         const int q = r * 32 + j; if (q >= nM * tpx) return false;
;         u.pm = q / tpx; u.pn = x * tpx + (q - u.pm * tpx); u.k0 = 0; u.nt = nt; u.part = 0; return true;
;     }
; template <int L> __device__ __forceinline__ void do_layer(const Args& a, LAS unsigned char* lds, const XcdBarrier& bar, int G, int b) {
;     ...
;         { pg8::Gemm g{XB, (const bf16_t*)(ws + WS_WQKV), D, D}; pg8::BStatOrder S; S.init(M, 6144, D, b);
;           EpiQkv E{H, a.out}; pg8::gemm_phase<EpiQkv, pg8::BStatOrder>(lds, g, S, E); }
.LBB0_656:
	s_or_b64 exec, exec, s[8:9]
	s_waitcnt vmcnt(0)
	buffer_inv sc1
	s_waitcnt vmcnt(0)
.LBB0_657:
	s_or_b64 exec, exec, s[2:3]
	s_load_dwordx4 s[4:7], s[86:87], 0xf0
	s_waitcnt lgkmcnt(0)
	v_mov_b32_e32 v1, v0
	s_cmpk_lt_i32 s70, 0x78
	s_barrier
	v_writelane_b32 v252, s4, 19
	s_cselect_b64 s[2:3], -1, 0
	s_nop 0
	v_writelane_b32 v252, s5, 20
	v_writelane_b32 v252, s6, 21
	v_writelane_b32 v252, s7, 22
	s_cmpk_gt_i32 s70, 0x77
	v_readfirstlane_b32 s4, v1
	s_cbranch_scc1 .LBB0_659
	s_mul_hi_i32 s1, s70, 0x55555556
	s_lshr_b32 s5, s1, 31
	s_add_i32 s24, s1, s5
	s_sub_i32 s1, s91, s24
	s_mul_i32 s1, s1, 3
	s_add_i32 s8, s1, s70

; #define LAS __attribute__((address_space(3)))
; __device__ __forceinline__ void ph_attn(const Args& a, LAS unsigned char* lds, int nblk, int b) {
;     const int nper = (1536 + nblk - 1) / nblk;
;     for (int i = 0; i < nper; ++i) { const int ii = (b & 1) ? (i + 4) % nper : i; const int u = b + ii * nblk; if (u >= 1536) continue;
;         if (u < 1024) attn_unit2<false>(a, lds, u >> 8, 2 * ((u >> 4) & 15), u & 15);
;         else { const int u2 = u - 1024; attn_unit2<true>(a, lds, u2 >> 4, 8, u2 & 15); }
;     }
; }
.LBB0_761:
	s_or_b64 exec, exec, s[4:5]
	s_mov_b64 s[4:5], exec
	v_mbcnt_lo_u32_b32 v1, s4, 0
	v_mbcnt_hi_u32_b32 v1, s5, v1
	v_cmp_eq_u32_e32 vcc, 0, v1
	s_and_saveexec_b64 s[8:9], vcc
	s_cbranch_execz .LBB0_763
	s_bcnt1_i32_b64 s4, s[4:5]
	v_mov_b32_e32 v1, 0x2000
	v_mov_b32_e32 v2, s4
	global_atomic_add v1, v2, s[6:7] offset:1024
.LBB0_763:
	s_or_b64 exec, exec, s[8:9]
	s_waitcnt vmcnt(0)
	buffer_inv sc1
	s_waitcnt vmcnt(0)
.LBB0_764:
	s_or_b64 exec, exec, s[2:3]
	s_abs_i32 s39, s89
	s_waitcnt lgkmcnt(0)
	v_cvt_f32_u32_e32 v1, s39
	s_sub_i32 s4, 0, s39
	s_add_i32 s2, s89, 0x5ff
	s_ashr_i32 s3, s2, 31
	v_rcp_iflag_f32_e32 v1, v1
	s_abs_i32 s2, s2
	s_ashr_i32 s53, s89, 31
	s_xor_b32 s3, s3, s53
	v_mul_f32_e32 v1, 0x4f7ffffe, v1
	v_cvt_u32_f32_e32 v1, v1
	s_mov_b32 s44, s94
	s_mov_b32 s40, 0
	v_readfirstlane_b32 s58, v1
	s_mul_i32 s4, s4, s58
	s_mul_hi_u32 s4, s58, s4
	s_add_i32 s58, s58, s4
	s_mul_hi_u32 s4, s2, s58
	s_mul_i32 s5, s4, s39
	s_sub_i32 s2, s2, s5
	s_add_i32 s5, s4, 1
	s_sub_i32 s6, s2, s39
	s_cmp_ge_u32 s2, s39
	s_cselect_b32 s4, s5, s4
	s_cselect_b32 s2, s6, s2
	s_add_i32 s5, s4, 1
	s_cmp_ge_u32 s2, s39
	s_cselect_b32 s2, s5, s4
	s_xor_b32 s2, s2, s3
	s_sub_i32 s63, s2, s3
	s_cmp_lt_i32 s63, 1
	v_mbcnt_lo_u32_b32 v1, -1, 0
	s_barrier
	v_writelane_b32 v252, s91, 23
	s_cbranch_scc1 .LBB0_980
	v_cvt_f32_u32_e32 v2, s63
	s_bitcmp1_b32 s90, 0
	s_cselect_b64 s[2:3], -1, 0
	s_add_u32 s64, s68, 0x25900000
	s_addc_u32 s65, s69, 0
	s_add_u32 s66, s68, 0x28100000
	v_rcp_iflag_f32_e32 v2, v2
	s_addc_u32 s67, s69, 0
	s_add_u32 s46, s68, 0x2d100000
	s_addc_u32 s47, s69, 0
	s_add_u32 s48, s68, 0x23100000
	v_mul_f32_e32 v2, 0x4f7ffffe, v2
	s_addc_u32 s49, s69, 0
	v_cvt_u32_f32_e32 v2, v2
	s_add_u32 s75, s86, 32
	s_addc_u32 s76, s87, 0
	s_load_dwordx2 s[50:51], s[86:87], 0x90
	s_add_u32 s77, s86, 40
	s_addc_u32 s79, s87, 0
	s_sub_i32 s4, 0, s63
	v_readfirstlane_b32 s5, v2
	s_mul_i32 s4, s4, s5
	s_mul_hi_u32 s4, s5, s4
	v_cndmask_b32_e64 v2, 0, 1, s[2:3]
	s_add_i32 s81, s5, s4
	v_cmp_ne_u32_e64 s[6:7], 1, v2
	v_mov_b32_e32 v115, 0
	s_add_i32 s84, 0, 0x11c00
	s_movk_i32 s85, 0x110
	s_add_i32 s86, 0, 0x11800
	s_mov_b32 s87, 0xf149f2ca
	s_movk_i32 s88, 0x201
	s_movk_i32 s89, 0xff
	s_mov_b32 s52, 0x3fb8aa3b
	s_mov_b64 s[54:55], 0x400
	s_movk_i32 s90, 0xffc0
	s_movk_i32 s91, 0xffbf
	s_movk_i32 s92, 0x120
	s_movk_i32 s93, 0x4400
	v_mbcnt_hi_u32_b32 v120, -1, v1
	s_mov_b32 s94, 0
	s_branch .LBB0_768

; template <class Epi, class Sched, bool ABLK = false, bool ALIGN_EPI = true, bool SP2 = true, bool BBLK = true>
; __device__ __forceinline__ void gemm_phase(LAS unsigned char* lds, const Gemm g, const Sched& S, const Epi& E) {
;     const int tid = tid_fresh(), wid = __builtin_amdgcn_readfirstlane(tid >> 6), lane = tid & 63, wr = wid >> 2, wc = wid & 3, fr = lane & 15, fq = lane >> 4;
;     unsigned voffA[2], voffB[2];
; #pragma unroll
;     for (int i = 0; i < 2; ++i) { int R, C; stage_rc(tid * 16 + i * 8192, R, C); const int r32 = Epi::PERM ? perm32(R & 31) : (R & 31);
;         const int Rb = Epi::ADJ ? 64 * (R >> 5) + r32 : (R & ~31) + r32;
;         voffA[i] = (unsigned)(R * (ABLK ? 64 : g.lda) + C) * 2u; voffB[i] = BBLK ? (unsigned)(R * 64 + C) * 2u : (unsigned)(Rb * g.ldb + C) * 2u; }
;     const size_t kstep = (size_t)(BK * 2);
;     const size_t hstepA = (size_t)HALF * (ABLK ? 64 : g.lda) * 2, hstepB = BBLK ? (size_t)16384 : (size_t)(Epi::ADJ ? 32 : HALF) * g.ldb * 2;
;     const size_t tstepB = BBLK ? ((size_t)g.ldb / 64) * 32768 : (size_t)BM * g.ldb * 2;
;     const size_t kstepB = BBLK ? (size_t)32768 : kstep;
;     auto b_k0 = [&](int k0) -> size_t { return BBLK ? (size_t)(k0 / BK) * 32768 : (size_t)k0 * 2; };
;     const unsigned ldsw = (unsigned)wid * 1024u;
;     const int aoff = lds_byte(wr * 64 + fr, fq * 8), boff = lds_byte(wc * 32 + fr, fq * 8);
;     ...
;     Unit cur, nxt; int ui = 0;
;     if (!S.next(0, cur)) return;
;     f32x4 acc[2][2][4][2];
; #pragma unroll
;     for (int a = 0; a < 2; ++a)
; #pragma unroll
;         for (int b = 0; b < 2; ++b)
; #pragma unroll
;             for (int m = 0; m < 4; ++m)
; #pragma unroll
;                 for (int n = 0; n < 2; ++n) acc[a][b][m][n] = (f32x4){0.f, 0.f, 0.f, 0.f};
;     bf16x8 At[4][2], B0[2][2], B1[2][2];
;     auto a_unit = [&](const Unit& u) -> const char* { return ABLK ? (const char*)g.A + (size_t)u.pm * ((size_t)g.lda / 64) * 32768 : (const char*)g.A + (size_t)u.pm * 2 * hstepA; };
; template <int L> __device__ __forceinline__ void do_layer(const Args& a, LAS unsigned char* lds, const XcdBarrier& bar, int G, int b) {
;     ...
;         { pg8::Gemm g{Y, (const bf16_t*)(ws + WS_WAO), D, D}; pg8::SplitOrder S; S.init(D, b);
;           EpiRes E{Z, PS}; pg8::gemm_phase<EpiRes, pg8::SplitOrder>(lds, g, S, E); }
.LBB0_1029:
	s_or_b64 exec, exec, s[4:5]
	s_mov_b64 s[4:5], exec
	v_mbcnt_lo_u32_b32 v2, s4, 0
	v_mbcnt_hi_u32_b32 v2, s5, v2
	v_cmp_eq_u32_e32 vcc, 0, v2
	s_and_saveexec_b64 s[8:9], vcc
	s_cbranch_execz .LBB0_1031
	s_bcnt1_i32_b64 s4, s[4:5]
	v_mov_b32_e32 v2, 0x2000
	v_mov_b32_e32 v3, s4
	global_atomic_add v2, v3, s[6:7] offset:1024
.LBB0_1031:
	s_or_b64 exec, exec, s[8:9]
	s_waitcnt vmcnt(0)
	buffer_inv sc1
	s_waitcnt vmcnt(0)
.LBB0_1032:
	s_or_b64 exec, exec, s[2:3]
	s_waitcnt vmcnt(7)
	v_mov_b32_e32 v8, v0
	s_waitcnt lgkmcnt(0)
	s_barrier
	v_readlane_b32 s4, v252, 19
	v_ashrrev_i32_e32 v3, 31, v8
	v_lshrrev_b32_e32 v3, 26, v3
	v_add_u32_e32 v3, v8, v3
	v_ashrrev_i32_e32 v6, 6, v3
	v_bfe_i32 v3, v8, 27, 1
	v_lshlrev_b32_e32 v2, 4, v8
	v_lshrrev_b32_e32 v3, 22, v3
	v_add_u32_e32 v3, v2, v3
	v_and_b32_e32 v3, 0xfffffc00, v3
	v_sub_u32_e32 v3, v2, v3
	v_lshrrev_b32_e32 v4, 4, v3
	v_bitop3_b32 v4, v4, v3, 32 bitop3:0x6c
	v_ashrrev_i32_e32 v3, 31, v3
	v_lshrrev_b32_e32 v3, 26, v3
	v_add_u32_e32 v3, v4, v3
	v_ashrrev_i32_e32 v7, 6, v3
	v_lshlrev_b32_e32 v5, 3, v6
	v_mul_i32_i24_e32 v9, 64, v7
	v_and_b32_e32 v5, -16, v5
	v_sub_u32_e32 v4, v4, v9
	s_waitcnt vmcnt(6)
	v_mov_b32_e32 v12, 1
	v_readlane_b32 s6, v252, 21
	v_add_u32_e32 v3, v7, v5
	v_lshlrev_b32_e32 v5, 5, v6
	v_ashrrev_i16_sdwa v4, v12, sext(v4) dst_sel:DWORD dst_unused:UNUSED_PAD src0_sel:DWORD src1_sel:BYTE_0
	v_readlane_b32 s7, v252, 22
	s_add_u32 s28, s6, 0x2d100000
	v_and_b32_e32 v5, 32, v5
	v_bfe_i32 v9, v4, 0, 16
	s_addc_u32 s29, s7, 0
	v_add_u32_e32 v4, v5, v9
	v_lshlrev_b32_e32 v5, 12, v3
	s_add_u32 s30, s6, 0x3900000
	v_lshl_add_u32 v130, v4, 1, v5
	s_movk_i32 s6, 0xf080
	v_add_u32_e32 v2, 0x2000, v2
	v_mad_u64_u32 v[132:133], s[2:3], v3, s6, v[130:131]
	v_ashrrev_i32_e32 v3, 31, v2
	v_lshrrev_b32_e32 v3, 22, v3
	v_add_u32_e32 v3, v2, v3
	v_ashrrev_i32_e32 v10, 10, v3
	v_mul_i32_i24_e32 v3, 0x400, v10
	v_sub_u32_e32 v2, v2, v3
	v_lshrrev_b32_e32 v3, 4, v2
	v_bitop3_b32 v2, v3, v2, 32 bitop3:0x6c
	v_ashrrev_i32_e32 v4, 31, v2
	v_lshrrev_b32_e32 v4, 26, v4
	v_add_u32_e32 v4, v2, v4
	v_ashrrev_i32_e32 v11, 6, v4
	v_and_b32_e32 v4, 0xc0, v4
	v_lshlrev_b32_e32 v3, 3, v10
	v_sub_u32_e32 v2, v2, v4
	v_and_b32_e32 v3, -16, v3
	v_lshlrev_b32_e32 v5, 5, v10
	v_ashrrev_i16_sdwa v2, v12, sext(v2) dst_sel:DWORD dst_unused:UNUSED_PAD src0_sel:DWORD src1_sel:BYTE_0
	v_add_u32_e32 v3, v11, v3
	v_and_b32_e32 v5, 32, v5
	v_bfe_i32 v12, v2, 0, 16
	v_readlane_b32 s5, v252, 20
	v_readfirstlane_b32 s4, v8
	v_add_u32_e32 v2, v5, v12
	v_lshlrev_b32_e32 v4, 12, v3
	s_addc_u32 s31, s7, 0
	s_ashr_i32 s5, s4, 6
	v_lshl_add_u32 v134, v2, 1, v4
	v_mad_u64_u32 v[136:137], s[2:3], v3, s6, v[134:135]
	s_ashr_i32 s6, s4, 8
	s_lshl_b32 s34, s5, 10
	s_lshl_b64 s[8:9], s[82:83], 20
	s_lshl_b32 s97, s78, 20
	s_add_u32 s20, s30, s97
	s_addc_u32 s21, s31, 0
	s_add_i32 s35, s34, 0
	s_add_i32 m0, s35, 0x10000
	v_mov_b32_e32 v133, 0
	global_load_lds_dwordx4 v132, s[20:21]
	s_add_i32 m0, s35, 0x12000
	s_add_u32 s2, s20, 0x4000
	global_load_lds_dwordx4 v136, s[20:21]
	s_addc_u32 s3, s21, 0
	s_add_i32 m0, s35, 0x14000
	v_mov_b32_e32 v131, v133
	global_load_lds_dwordx4 v132, s[2:3]
	s_add_i32 m0, s35, 0x16000
	s_add_u32 s22, s28, s8
	v_writelane_b32 v252, s8, 24
	s_addc_u32 s23, s29, s9
	s_add_i32 s36, s35, 0x2000
	global_load_lds_dwordx4 v136, s[2:3]
	s_mov_b32 m0, s35
	s_add_u32 s2, s22, 0x80000
	global_load_lds_dwordx4 v130, s[22:23]
	s_mov_b32 m0, s36
	s_addc_u32 s3, s23, 0
	s_add_i32 s37, s35, 0x4000
	global_load_lds_dwordx4 v134, s[22:23]
	s_mov_b32 m0, s37
	s_add_i32 s40, s35, 0x6000
	global_load_lds_dwordx4 v130, s[2:3]
	s_mov_b32 m0, s40
	v_mov_b32_e32 v135, v133
	global_load_lds_dwordx4 v134, s[2:3]
	s_cmp_eq_u32 s6, 1
	s_mov_b32 s46, 32
	s_mov_b32 s43, 0
	v_mov_b32_e32 v137, v133
	v_lshl_add_u64 v[2:3], s[22:23], 0, v[130:131]
	s_cselect_b64 s[2:3], -1, 0
	s_cmp_lg_u32 s6, 1
	v_lshl_add_u64 v[4:5], s[22:23], 0, v[134:135]
	v_writelane_b32 v252, s9, 25
	s_cbranch_scc1 .LBB0_1034
	s_barrier

; __device__ __forceinline__ void ph_ln(const Args& a, int L, int which, bool final_, bool split, bool wr_x, bool res_inputs, int nblk, int b) {
;     unsigned char* ws = a.ws; const bf16_t* P = (const bf16_t*)(ws + WS_SCR + SCR_PART);
;     const bf16_t* Z = (const bf16_t*)(ws + WS_Z); float* Xo = final_ ? a.out : (float*)(ws + WS_X); bf16_t* XB = (bf16_t*)(ws + WS_XB);
;     auto lo = [](unsigned w) -> float { return __builtin_bit_cast(float, w << 16); }; auto hi = [](unsigned w) -> float { return __builtin_bit_cast(float, w & 0xffff0000u); };
;     const float* gam = a.in[which ? 26 : 24] + (size_t)L * D; const float* bet = a.in[which ? 27 : 25] + (size_t)L * D;
;     const int tid = tid_fresh(); const int lane = tid & 63, gw = b * 8 + (tid >> 6), ngw = nblk * 8;
;     f32x4 gg[4][2], bb[4][2];
; #pragma unroll
;     for (int j = 0; j < 4; ++j)
; #pragma unroll
;         for (int h = 0; h < 2; ++h) { gg[j][h] = *(const f32x4*)(gam + 512 * j + 8 * lane + 4 * h); bb[j][h] = *(const f32x4*)(bet + 512 * j + 8 * lane + 4 * h); }
;     u32x4 zc[4], xc[4];
;     auto ldrow = [&](int r) { const u32x4* zr = (const u32x4*)(Z + (size_t)r * D) + lane;
; #pragma unroll
;         for (int j = 0; j < 4; ++j) zc[j] = zr[64 * j];
;         if (!res_inputs) { const u32x4* xr = (const u32x4*)(XB + (size_t)r * D) + lane;
; #pragma unroll
;             for (int j = 0; j < 4; ++j) xc[j] = xr[64 * j]; } };
;     if (gw < M) ldrow(gw);
;     for (int r = gw; r < M; r += ngw) {
;         float v[4][8];
; #pragma unroll
;         for (int j = 0; j < 4; ++j)
; #pragma unroll
;             for (int e = 0; e < 4; ++e) { v[j][2 * e] = lo(zc[j][e]); v[j][2 * e + 1] = hi(zc[j][e]); }
;         if (!res_inputs) {
; #pragma unroll
;             for (int j = 0; j < 4; ++j)
; #pragma unroll
;                 for (int e = 0; e < 4; ++e) { v[j][2 * e] += ALPHA * lo(xc[j][e]); v[j][2 * e + 1] += ALPHA * hi(xc[j][e]); } }
;         if (r + ngw < M) ldrow(r + ngw);
;         if (split && r >= MP) {
; #pragma unroll
;             for (int p = 0; p < 3; ++p) { const u32x4* pr = (const u32x4*)(P + ((size_t)p * MS + (r - MP)) * D) + lane;
; #pragma unroll
;                 for (int j = 0; j < 4; ++j) { const u32x4 w = pr[64 * j];
; #pragma unroll
;                     for (int e = 0; e < 4; ++e) { v[j][2 * e] += lo(w[e]); v[j][2 * e + 1] += hi(w[e]); } } } }
.LBB0_1095:
	s_or_b64 exec, exec, s[8:9]
	s_waitcnt vmcnt(0)
	buffer_inv sc1
	s_waitcnt vmcnt(0)
.LBB0_1096:
	s_or_b64 exec, exec, s[2:3]
	s_waitcnt lgkmcnt(0)
	v_mov_b32_e32 v2, v0
	s_barrier
	s_movk_i32 s17, 0x2800
	v_ashrrev_i32_e32 v66, 6, v2
	v_add_u32_e32 v156, s94, v66
	v_cmp_gt_i32_e32 vcc, s17, v156
	s_and_saveexec_b64 s[2:3], vcc
	s_cbranch_execz .LBB0_1103
	s_load_dwordx4 s[4:7], s[86:87], 0xc0
	v_and_b32_e32 v58, 63, v2
	v_mov_b32_e32 v131, 0
	v_lshlrev_b32_e32 v130, 5, v58
	s_mov_b64 s[8:9], 0x3800
	s_waitcnt lgkmcnt(0)
	v_lshl_add_u64 v[42:43], s[6:7], 0, v[130:131]
	v_add_co_u32_e32 v6, vcc, 0x3000, v42
	v_lshl_add_u64 v[54:55], s[4:5], 0, v[130:131]
	s_nop 0
	v_addc_co_u32_e32 v7, vcc, 0, v43, vcc
	v_add_co_u32_e32 v18, vcc, 0x3000, v54
	s_mov_b64 s[4:5], 0x3000
	s_mov_b64 s[6:7], 0x2000
	v_addc_co_u32_e32 v19, vcc, 0, v55, vcc
	v_lshl_add_u64 v[10:11], v[42:43], 0, s[4:5]
	v_lshl_add_u64 v[22:23], v[54:55], 0, s[4:5]
	s_movk_i32 s4, 0x2000
	v_ashrrev_i32_e32 v157, 31, v156
	v_lshl_add_u64 v[50:51], v[42:43], 0, s[6:7]
	v_lshl_add_u64 v[26:27], v[42:43], 0, s[8:9]
	v_add_co_u32_e32 v42, vcc, s4, v42
	v_lshlrev_b64 v[56:57], 12, v[156:157]
	v_lshl_add_u64 v[34:35], v[54:55], 0, s[8:9]
	v_addc_co_u32_e32 v43, vcc, 0, v43, vcc
	v_lshlrev_b32_e32 v132, 4, v58
	v_mov_b32_e32 v133, v131
	v_lshl_add_u64 v[56:57], s[68:69], 0, v[56:57]
	v_lshl_add_u64 v[62:63], v[54:55], 0, s[6:7]
	global_load_dwordx4 v[2:5], v[6:7], off offset:2048
	s_nop 0
	global_load_dwordx4 v[6:9], v[6:7], off
	s_nop 0
	global_load_dwordx4 v[10:13], v[10:11], off offset:16
	s_nop 0
	global_load_dwordx4 v[14:17], v[18:19], off offset:2048
	s_nop 0
	global_load_dwordx4 v[18:21], v[18:19], off
	s_nop 0
	global_load_dwordx4 v[22:25], v[22:23], off offset:16
	s_nop 0
	global_load_dwordx4 v[26:29], v[26:27], off offset:16
	s_nop 0
	global_load_dwordx4 v[30:33], v[50:51], off offset:2064
	s_nop 0
	global_load_dwordx4 v[34:37], v[34:35], off offset:16
	s_nop 0
	global_load_dwordx4 v[38:41], v[62:63], off offset:2064
	v_add_co_u32_e32 v54, vcc, s4, v54
	v_lshl_add_u64 v[56:57], v[56:57], 0, v[132:133]
	s_mov_b64 s[4:5], 0x1e100000
	v_addc_co_u32_e32 v55, vcc, 0, v55, vcc
	v_lshl_add_u64 v[58:59], v[56:57], 0, s[4:5]
	s_mov_b32 s4, 0x1e100000
	v_add_co_u32_e32 v60, vcc, s4, v56
	s_mov_b64 s[4:5], 0x1b900000
	global_load_dwordx4 v[42:45], v[42:43], off
	s_nop 0
	global_load_dwordx4 v[46:49], v[50:51], off offset:2048
	s_nop 0
	global_load_dwordx4 v[50:53], v[50:51], off offset:16
	v_addc_co_u32_e32 v61, vcc, 0, v57, vcc
	global_load_dwordx4 v[114:117], v[58:59], off offset:1024
	global_load_dwordx4 v[106:109], v[58:59], off offset:2048
	global_load_dwordx4 v[122:125], v[60:61], off
	global_load_dwordx4 v[98:101], v[58:59], off offset:3072
	v_lshl_add_u64 v[58:59], v[56:57], 0, s[4:5]
	s_mov_b32 s4, 0x1b900000
	v_add_co_u32_e32 v56, vcc, s4, v56
	v_lshl_add_u64 v[68:69], s[68:69], 0, v[132:133]
	s_nop 0
	v_addc_co_u32_e32 v57, vcc, 0, v57, vcc
	global_load_dwordx4 v[126:129], v[56:57], off
	global_load_dwordx4 v[102:105], v[58:59], off offset:3072
	global_load_dwordx4 v[118:121], v[58:59], off offset:1024
	global_load_dwordx4 v[110:113], v[58:59], off offset:2048
	s_nop 0
	global_load_dwordx4 v[54:57], v[54:55], off
	s_nop 0
	global_load_dwordx4 v[58:61], v[62:63], off offset:2048
	s_nop 0
	global_load_dwordx4 v[62:65], v[62:63], off offset:16
	s_mov_b64 s[4:5], 0x3c900000
	v_ashrrev_i32_e32 v67, 31, v66
	s_ashr_i32 s95, s94, 31
	v_lshl_add_u64 v[134:135], v[68:69], 0, s[4:5]
	v_add_u32_e32 v68, s74, v156
	v_lshl_add_u64 v[66:67], v[66:67], 0, s[94:95]
	v_ashrrev_i32_e32 v69, 31, v68
	v_lshlrev_b64 v[66:67], 12, v[66:67]
	v_lshlrev_b64 v[68:69], 12, v[68:69]
	v_lshl_add_u64 v[66:67], s[68:69], 0, v[66:67]
	s_mov_b64 s[4:5], 0x1b900800
	v_lshl_add_u64 v[136:137], s[68:69], 0, v[68:69]
	s_ashr_i32 s75, s74, 31
	v_lshl_add_u64 v[138:139], v[66:67], 0, s[4:5]
	s_lshl_b64 s[10:11], s[74:75], 12
	s_mov_b64 s[14:15], 0
	s_movk_i32 s18, 0x27ff
	s_mov_b32 s16, 0x3fd744fd
	s_movk_i32 s19, 0x1fff
	s_mov_b32 s20, 0x800000
	s_mov_b32 s21, 0x1000000
	v_mov_b32_e32 v157, 0x3727c5ac
	s_mov_b32 s22, 0xf800000
	v_mov_b32_e32 v158, 0x260
	s_waitcnt vmcnt(10)
	v_mov_b64_e32 v[74:75], v[114:115]
	s_waitcnt vmcnt(9)
	v_mov_b64_e32 v[70:71], v[106:107]
	s_waitcnt vmcnt(8)
	v_mov_b64_e32 v[78:79], v[122:123]
	s_waitcnt vmcnt(7)
	v_mov_b64_e32 v[66:67], v[98:99]
	v_mov_b64_e32 v[68:69], v[100:101]
	s_waitcnt vmcnt(6)
	v_mov_b64_e32 v[94:95], v[126:127]
	s_waitcnt vmcnt(5)
	v_mov_b64_e32 v[82:83], v[102:103]
	s_waitcnt vmcnt(4)
	v_mov_b64_e32 v[90:91], v[118:119]
	s_waitcnt vmcnt(3)
	v_mov_b64_e32 v[86:87], v[110:111]
	v_mov_b64_e32 v[72:73], v[108:109]
	v_mov_b64_e32 v[76:77], v[116:117]
	v_mov_b64_e32 v[80:81], v[124:125]
	v_mov_b64_e32 v[84:85], v[104:105]
	v_mov_b64_e32 v[88:89], v[112:113]
	v_mov_b64_e32 v[92:93], v[120:121]
	v_mov_b64_e32 v[96:97], v[128:129]
	s_branch .LBB0_1099

; template <class Epi, class Sched, bool ABLK = false, bool ALIGN_EPI = true, bool SP2 = true, bool BBLK = true>
; __device__ __forceinline__ void gemm_phase(LAS unsigned char* lds, const Gemm g, const Sched& S, const Epi& E) {
;     const int tid = tid_fresh(), wid = __builtin_amdgcn_readfirstlane(tid >> 6), lane = tid & 63, wr = wid >> 2, wc = wid & 3, fr = lane & 15, fq = lane >> 4;
;     unsigned voffA[2], voffB[2];
; #pragma unroll
;     for (int i = 0; i < 2; ++i) { int R, C; stage_rc(tid * 16 + i * 8192, R, C); const int r32 = Epi::PERM ? perm32(R & 31) : (R & 31);
;         const int Rb = Epi::ADJ ? 64 * (R >> 5) + r32 : (R & ~31) + r32;
;         voffA[i] = (unsigned)(R * (ABLK ? 64 : g.lda) + C) * 2u; voffB[i] = BBLK ? (unsigned)(R * 64 + C) * 2u : (unsigned)(Rb * g.ldb + C) * 2u; }
;     const size_t kstep = (size_t)(BK * 2);
;     const size_t hstepA = (size_t)HALF * (ABLK ? 64 : g.lda) * 2, hstepB = BBLK ? (size_t)16384 : (size_t)(Epi::ADJ ? 32 : HALF) * g.ldb * 2;
;     const size_t tstepB = BBLK ? ((size_t)g.ldb / 64) * 32768 : (size_t)BM * g.ldb * 2;
;     const size_t kstepB = BBLK ? (size_t)32768 : kstep;
;     auto b_k0 = [&](int k0) -> size_t { return BBLK ? (size_t)(k0 / BK) * 32768 : (size_t)k0 * 2; };
;     const unsigned ldsw = (unsigned)wid * 1024u;
;     const int aoff = lds_byte(wr * 64 + fr, fq * 8), boff = lds_byte(wc * 32 + fr, fq * 8);
;     ...
;     Unit cur, nxt; int ui = 0;
;     if (!S.next(0, cur)) return;
;     f32x4 acc[2][2][4][2];
; #pragma unroll
;     for (int a = 0; a < 2; ++a)
; #pragma unroll
;         for (int b = 0; b < 2; ++b)
; #pragma unroll
;             for (int m = 0; m < 4; ++m)
; #pragma unroll
;                 for (int n = 0; n < 2; ++n) acc[a][b][m][n] = (f32x4){0.f, 0.f, 0.f, 0.f};
;     bf16x8 At[4][2], B0[2][2], B1[2][2];
;     auto a_unit = [&](const Unit& u) -> const char* { return ABLK ? (const char*)g.A + (size_t)u.pm * ((size_t)g.lda / 64) * 32768 : (const char*)g.A + (size_t)u.pm * 2 * hstepA; };
; template <int L> __device__ __forceinline__ void do_layer(const Args& a, LAS unsigned char* lds, const XcdBarrier& bar, int G, int b) {
;     ...
;     { pg8::Gemm g{XB, (const bf16_t*)(ws + WS_WF1) + (size_t)L * FF * D, D, D}; pg8::BStatOrder S; S.init(M, FF, D, b);
;       EpiFfn1 E{H}; pg8::gemm_phase<EpiFfn1, pg8::BStatOrder>(lds, g, S, E); }
.LBB0_1154:
	s_or_b64 exec, exec, s[8:9]
	s_waitcnt vmcnt(0)
	buffer_inv sc1
	s_waitcnt vmcnt(0)
.LBB0_1155:
	s_or_b64 exec, exec, s[2:3]
	v_readlane_b32 s4, v252, 14
	v_readlane_b32 s5, v252, 15
	v_mov_b32_e32 v9, v0
	s_waitcnt lgkmcnt(0)
	v_cndmask_b32_e64 v2, 0, 1, s[4:5]
	v_cmp_ne_u32_e64 s[2:3], 1, v2
	s_barrier
	s_nop 0
	v_writelane_b32 v252, s2, 26
	s_andn2_b64 vcc, exec, s[4:5]
	v_readfirstlane_b32 s6, v9
	v_writelane_b32 v252, s3, 27
	s_cbranch_vccnz .LBB0_1171
	v_lshlrev_b32_e32 v2, 4, v9
	v_add_u32_e32 v3, 0x2000, v2
	v_ashrrev_i32_e32 v4, 31, v3
	v_lshrrev_b32_e32 v4, 22, v4
	v_add_u32_e32 v4, v3, v4
	v_ashrrev_i32_e32 v6, 10, v4
	v_mul_i32_i24_e32 v5, 0x400, v6
	v_sub_u32_e32 v3, v3, v5
	v_lshrrev_b32_e32 v5, 4, v3
	v_bitop3_b32 v3, v5, v3, 32 bitop3:0x6c
	v_ashrrev_i32_e32 v5, 31, v3
	v_lshrrev_b32_e32 v5, 26, v5
	v_add_u32_e32 v5, v3, v5
	v_ashrrev_i32_e32 v7, 6, v5
	v_and_b32_e32 v5, 0xc0, v5
	v_sub_u32_e32 v3, v3, v5
	v_mov_b32_e32 v5, 1
	v_lshlrev_b32_e32 v4, 5, v6
	v_ashrrev_i16_sdwa v3, v5, sext(v3) dst_sel:DWORD dst_unused:UNUSED_PAD src0_sel:DWORD src1_sel:BYTE_0
	v_and_b32_e32 v4, 32, v4
	v_bfe_i32 v8, v3, 0, 16
	v_add_u32_e32 v3, v4, v8
	v_lshlrev_b32_e32 v4, 3, v6
	v_and_b32_e32 v4, -16, v4
	v_add_u32_e32 v4, v7, v4
	v_lshlrev_b32_e32 v10, 7, v4
	v_lshl_add_u32 v130, v3, 1, v10
	s_movk_i32 s4, 0xf80
	v_mad_u64_u32 v[132:133], s[2:3], v4, s4, v[130:131]
	v_bfe_i32 v4, v9, 27, 1
	v_lshrrev_b32_e32 v4, 22, v4
	v_add_u32_e32 v4, v2, v4
	v_and_b32_e32 v4, 0xfffffc00, v4
	v_sub_u32_e32 v2, v2, v4
	v_lshrrev_b32_e32 v4, 4, v2
	v_bitop3_b32 v4, v4, v2, 32 bitop3:0x6c
	v_ashrrev_i32_e32 v2, 31, v2
	v_lshrrev_b32_e32 v2, 26, v2
	v_ashrrev_i32_e32 v3, 31, v9
	v_add_u32_e32 v2, v4, v2
	v_lshrrev_b32_e32 v3, 26, v3
	v_ashrrev_i32_e32 v11, 6, v2
	v_add_u32_e32 v3, v9, v3
	v_mul_i32_i24_e32 v2, 64, v11
	v_ashrrev_i32_e32 v10, 6, v3
	v_sub_u32_e32 v2, v4, v2
	v_lshlrev_b32_e32 v3, 5, v10
	v_ashrrev_i16_sdwa v2, v5, sext(v2) dst_sel:DWORD dst_unused:UNUSED_PAD src0_sel:DWORD src1_sel:BYTE_0
	v_and_b32_e32 v3, 32, v3
	v_bfe_i32 v12, v2, 0, 16
	v_add_u32_e32 v2, v3, v12
	v_lshlrev_b32_e32 v3, 3, v10
	v_and_b32_e32 v3, -16, v3
	v_add_u32_e32 v3, v11, v3
	v_readlane_b32 s8, v252, 19
	v_lshlrev_b32_e32 v4, 7, v3
	v_readlane_b32 s10, v252, 21
	v_lshl_add_u32 v134, v2, 1, v4
	v_readlane_b32 s11, v252, 22
	s_add_u32 s40, s10, 0x8900000
	v_mad_u64_u32 v[136:137], s[2:3], v3, s4, v[134:135]
	s_addc_u32 s41, s11, 0
	s_lshr_b32 s2, s70, 30
	s_add_i32 s2, s70, s2
	s_ashr_i32 s22, s2, 2
	s_sub_i32 s2, s91, s22
	s_lshl_b32 s2, s2, 2
	s_add_i32 s24, s2, s70
	s_ashr_i32 s8, s6, 6
	s_ashr_i32 s23, s22, 31
	s_ashr_i32 s25, s24, 31
	s_ashr_i32 s7, s6, 8
	s_lshl_b32 s42, s8, 10
	s_lshl_b64 s[2:3], s[22:23], 20
	s_lshl_b64 s[4:5], s[24:25], 20
	s_add_u32 s28, s40, s4
	s_addc_u32 s29, s41, s5
	s_add_i32 s25, s42, 0
	s_add_i32 m0, s25, 0x10000
	v_mov_b32_e32 v139, 0
	global_load_lds_dwordx4 v134, s[28:29]
	s_add_i32 m0, s25, 0x12000
	s_add_u32 s4, s28, 0x4000
	global_load_lds_dwordx4 v130, s[28:29]
	s_addc_u32 s5, s29, 0
	s_add_i32 m0, s25, 0x14000
	v_mov_b32_e32 v137, v139
	global_load_lds_dwordx4 v134, s[4:5]
	s_add_i32 m0, s25, 0x16000
	s_add_u32 s26, s59, s2
	s_addc_u32 s27, s62, s3
	s_add_i32 s43, s25, 0x2000
	global_load_lds_dwordx4 v130, s[4:5]
	s_mov_b32 m0, s25
	s_add_u32 s2, s26, 0x80000
	global_load_lds_dwordx4 v136, s[26:27]
	s_mov_b32 m0, s43
	s_addc_u32 s3, s27, 0
	s_add_i32 s44, s25, 0x4000
	global_load_lds_dwordx4 v132, s[26:27]
	s_mov_b32 m0, s44
	s_add_i32 s45, s25, 0x6000
	global_load_lds_dwordx4 v136, s[2:3]
	s_mov_b32 m0, s45
	v_mov_b32_e32 v133, v139
	global_load_lds_dwordx4 v132, s[2:3]
	s_cmp_eq_u32 s7, 1
	s_mov_b32 s46, 0
	v_mov_b32_e32 v135, v139
	v_mov_b32_e32 v131, v139
	s_mov_b64 s[4:5], 0x4000
	v_lshl_add_u64 v[2:3], s[26:27], 0, v[136:137]
	s_cselect_b64 s[2:3], -1, 0
	s_cmp_lg_u32 s7, 1
	v_lshl_add_u64 v[4:5], s[26:27], 0, v[132:133]
	v_readlane_b32 s9, v252, 20
	s_cbranch_scc1 .LBB0_1158
	s_barrier

;     __host__ __device__ bool next(int r, Unit& u) const {
;         const int gidx = 4 * x + (i >> 3);
;         if (r == 0) { u.pm = gidx; u.pn = i & 7; u.k0 = 0; u.nt = ntf; u.part = 0; return true; }
;         if (r == 1) { const int part = gidx & 3; u.pm = 32 + (gidx >> 2); u.pn = i & 7; u.nt = ntf >> 2; u.k0 = part * (ntf >> 2) * BK; u.part = part; return true; }
;         return false;
;     }
; template <int L> __device__ __forceinline__ void do_layer(const Args& a, LAS unsigned char* lds, const XcdBarrier& bar, int G, int b) {
;     ...
;     { pg8::Gemm g{H, (const bf16_t*)(ws + WS_WF2) + (size_t)L * FF * D, FF, FF}; pg8::SplitOrder S; S.init(FF, b);
;       EpiRes E{Z, PS}; pg8::gemm_phase<EpiRes, pg8::SplitOrder, true>(lds, g, S, E); }
.LBB0_1222:
	s_or_b64 exec, exec, s[8:9]
	s_waitcnt vmcnt(0)
	buffer_inv sc1
	s_waitcnt vmcnt(0)
.LBB0_1223:
	s_or_b64 exec, exec, s[2:3]
	v_mov_b32_e32 v4, v0
	s_waitcnt lgkmcnt(0)
	s_barrier
	v_readlane_b32 s4, v252, 19
	v_bfe_i32 v3, v4, 27, 1
	v_lshlrev_b32_e32 v6, 4, v4
	v_lshrrev_b32_e32 v3, 22, v3
	v_add_u32_e32 v3, v6, v3
	v_and_b32_e32 v3, 0xfffffc00, v3
	v_sub_u32_e32 v3, v6, v3
	v_lshrrev_b32_e32 v5, 4, v3
	v_bitop3_b32 v5, v5, v3, 32 bitop3:0x6c
	v_ashrrev_i32_e32 v3, 31, v3
	v_lshrrev_b32_e32 v3, 26, v3
	v_ashrrev_i32_e32 v2, 31, v4
	v_add_u32_e32 v3, v5, v3
	v_lshrrev_b32_e32 v2, 26, v2
	v_ashrrev_i32_e32 v3, 6, v3
	v_add_u32_e32 v2, v4, v2
	v_mul_i32_i24_e32 v9, 64, v3
	v_ashrrev_i32_e32 v2, 6, v2
	v_sub_u32_e32 v5, v5, v9
	v_mov_b32_e32 v9, 1
	v_lshlrev_b32_e32 v7, 3, v2
	v_lshlrev_b32_e32 v8, 5, v2
	v_ashrrev_i16_sdwa v5, v9, sext(v5) dst_sel:DWORD dst_unused:UNUSED_PAD src0_sel:DWORD src1_sel:BYTE_0
	v_and_b32_e32 v7, 0x1fffff0, v7
	v_and_b32_e32 v8, 32, v8
	v_bfe_i32 v5, v5, 0, 16
	v_add_u32_e32 v8, v8, v5
	v_add_lshl_u32 v7, v3, v7, 7
	v_lshl_add_u32 v130, v8, 1, v7
	v_add_u32_e32 v7, 0x2000, v6
	v_ashrrev_i32_e32 v6, 31, v7
	v_lshrrev_b32_e32 v6, 22, v6
	v_add_u32_e32 v6, v7, v6
	v_ashrrev_i32_e32 v6, 10, v6
	v_mul_i32_i24_e32 v8, 0x400, v6
	v_sub_u32_e32 v7, v7, v8
	v_lshrrev_b32_e32 v8, 4, v7
	v_bitop3_b32 v8, v8, v7, 32 bitop3:0x6c
	v_lshlrev_b32_e32 v7, 3, v6
	v_readlane_b32 s6, v252, 21
	v_and_b32_e32 v10, 0x1fffff0, v7
	v_ashrrev_i32_e32 v7, 31, v8
	v_readlane_b32 s5, v252, 20
	v_readlane_b32 s7, v252, 22
	s_add_u32 s30, s6, 0x10900000
	v_readfirstlane_b32 s4, v4
	v_lshrrev_b32_e32 v7, 26, v7
	s_addc_u32 s31, s7, 0
	s_ashr_i32 s5, s4, 6
	v_add_u32_e32 v11, v8, v7
	v_ashrrev_i32_e32 v7, 6, v11
	v_and_b32_e32 v11, 0xc0, v11
	s_ashr_i32 s6, s4, 8
	s_lshl_b32 s34, s5, 10
	v_readlane_b32 s2, v252, 16
	v_sub_u32_e32 v8, v8, v11
	s_add_u32 s22, s30, s2
	v_lshlrev_b32_e32 v12, 5, v6
	v_ashrrev_i16_sdwa v8, v9, sext(v8) dst_sel:DWORD dst_unused:UNUSED_PAD src0_sel:DWORD src1_sel:BYTE_0
	s_addc_u32 s23, s31, 0
	s_add_i32 s35, s34, 0
	v_and_b32_e32 v12, 32, v12
	v_bfe_i32 v8, v8, 0, 16
	s_add_i32 m0, s35, 0x10000
	v_add_u32_e32 v9, v12, v8
	v_add_lshl_u32 v10, v7, v10, 7
	global_load_lds_dwordx4 v130, s[22:23]
	s_add_i32 m0, s35, 0x12000
	v_lshl_add_u32 v132, v9, 1, v10
	s_add_u32 s2, s22, 0x4000
	global_load_lds_dwordx4 v132, s[22:23]
	s_addc_u32 s3, s23, 0
	s_add_i32 m0, s35, 0x14000
	v_mov_b32_e32 v131, 0
	global_load_lds_dwordx4 v130, s[2:3]
	s_add_i32 m0, s35, 0x16000
	s_mov_b32 s43, 0
	global_load_lds_dwordx4 v132, s[2:3]
	v_readlane_b32 s2, v252, 17
	v_readlane_b32 s3, v252, 18
	s_add_u32 s24, s1, s2
	s_addc_u32 s25, s33, s3
	s_add_i32 s36, s35, 0x2000
	s_mov_b32 m0, s35
	s_add_u32 s2, s24, 0x4000
	global_load_lds_dwordx4 v130, s[24:25]
	s_mov_b32 m0, s36
	s_addc_u32 s3, s25, 0
	s_add_i32 s37, s35, 0x4000
	global_load_lds_dwordx4 v132, s[24:25]
	s_mov_b32 m0, s37
	s_add_i32 s40, s35, 0x6000
	global_load_lds_dwordx4 v130, s[2:3]
	s_mov_b32 m0, s40
	s_cmp_eq_u32 s6, 1
	global_load_lds_dwordx4 v132, s[2:3]
	s_cselect_b64 s[2:3], -1, 0
	s_cmp_lg_u32 s6, 1
	v_mov_b32_e32 v133, v131
	s_cbranch_scc1 .LBB0_1225
	s_barrier

; __device__ __forceinline__ void ph_ln(const Args& a, int L, int which, bool final_, bool split, bool wr_x, bool res_inputs, int nblk, int b) {
;     unsigned char* ws = a.ws; const bf16_t* P = (const bf16_t*)(ws + WS_SCR + SCR_PART);
;     const bf16_t* Z = (const bf16_t*)(ws + WS_Z); float* Xo = final_ ? a.out : (float*)(ws + WS_X); bf16_t* XB = (bf16_t*)(ws + WS_XB);
;     auto lo = [](unsigned w) -> float { return __builtin_bit_cast(float, w << 16); }; auto hi = [](unsigned w) -> float { return __builtin_bit_cast(float, w & 0xffff0000u); };
;     const float* gam = a.in[which ? 26 : 24] + (size_t)L * D; const float* bet = a.in[which ? 27 : 25] + (size_t)L * D;
;     const int tid = tid_fresh(); const int lane = tid & 63, gw = b * 8 + (tid >> 6), ngw = nblk * 8;
;     f32x4 gg[4][2], bb[4][2];
; #pragma unroll
;     for (int j = 0; j < 4; ++j)
; #pragma unroll
;         for (int h = 0; h < 2; ++h) { gg[j][h] = *(const f32x4*)(gam + 512 * j + 8 * lane + 4 * h); bb[j][h] = *(const f32x4*)(bet + 512 * j + 8 * lane + 4 * h); }
;     u32x4 zc[4], xc[4];
;     auto ldrow = [&](int r) { const u32x4* zr = (const u32x4*)(Z + (size_t)r * D) + lane;
; #pragma unroll
;         for (int j = 0; j < 4; ++j) zc[j] = zr[64 * j];
;         if (!res_inputs) { const u32x4* xr = (const u32x4*)(XB + (size_t)r * D) + lane;
; #pragma unroll
;             for (int j = 0; j < 4; ++j) xc[j] = xr[64 * j]; } };
;     if (gw < M) ldrow(gw);
;     for (int r = gw; r < M; r += ngw) {
;         float v[4][8];
; #pragma unroll
;         for (int j = 0; j < 4; ++j)
; #pragma unroll
;             for (int e = 0; e < 4; ++e) { v[j][2 * e] = lo(zc[j][e]); v[j][2 * e + 1] = hi(zc[j][e]); }
;         if (!res_inputs) {
; #pragma unroll
;             for (int j = 0; j < 4; ++j)
; #pragma unroll
;                 for (int e = 0; e < 4; ++e) { v[j][2 * e] += ALPHA * lo(xc[j][e]); v[j][2 * e + 1] += ALPHA * hi(xc[j][e]); } }
;         if (r + ngw < M) ldrow(r + ngw);
;         if (split && r >= MP) {
; #pragma unroll
;             for (int p = 0; p < 3; ++p) { const u32x4* pr = (const u32x4*)(P + ((size_t)p * MS + (r - MP)) * D) + lane;
; #pragma unroll
;                 for (int j = 0; j < 4; ++j) { const u32x4 w = pr[64 * j];
; #pragma unroll
;                     for (int e = 0; e < 4; ++e) { v[j][2 * e] += lo(w[e]); v[j][2 * e + 1] += hi(w[e]); } } } }
.LBB0_1284:
	s_or_b64 exec, exec, s[4:5]
	s_mov_b64 s[4:5], exec
	v_mbcnt_lo_u32_b32 v2, s4, 0
	v_mbcnt_hi_u32_b32 v2, s5, v2
	v_cmp_eq_u32_e32 vcc, 0, v2
	s_and_saveexec_b64 s[8:9], vcc
	s_cbranch_execz .LBB0_1286
	s_bcnt1_i32_b64 s1, s[4:5]
	v_mov_b32_e32 v2, 0x2000
	v_mov_b32_e32 v3, s1
	global_atomic_add v2, v3, s[6:7] offset:1024
.LBB0_1286:
	s_or_b64 exec, exec, s[8:9]
	s_waitcnt vmcnt(0)
	buffer_inv sc1
	s_waitcnt vmcnt(0)
.LBB0_1287:
	s_or_b64 exec, exec, s[2:3]
	s_waitcnt lgkmcnt(0)
	v_mov_b32_e32 v2, v0
	s_barrier
	s_movk_i32 s1, 0x2800
	v_ashrrev_i32_e32 v66, 6, v2
	v_add_u32_e32 v156, s94, v66
	v_cmp_gt_i32_e32 vcc, s1, v156
	s_and_saveexec_b64 s[2:3], vcc
	s_cbranch_execz .LBB0_1294
	s_load_dwordx4 s[4:7], s[86:87], 0xd0
	v_and_b32_e32 v56, 63, v2
	v_mov_b32_e32 v131, 0
	v_lshlrev_b32_e32 v130, 5, v56
	s_mov_b64 s[8:9], 0x3800
	s_waitcnt lgkmcnt(0)
	v_lshl_add_u64 v[42:43], s[6:7], 0, v[130:131]
	v_add_co_u32_e32 v6, vcc, 0x3000, v42
	v_lshl_add_u64 v[54:55], s[4:5], 0, v[130:131]
	s_nop 0
	v_addc_co_u32_e32 v7, vcc, 0, v43, vcc
	v_add_co_u32_e32 v48, vcc, 0x3000, v54
	s_mov_b64 s[4:5], 0x3000
	s_mov_b64 s[6:7], 0x2000
	v_addc_co_u32_e32 v49, vcc, 0, v55, vcc
	v_lshl_add_u64 v[10:11], v[42:43], 0, s[4:5]
	v_lshl_add_u64 v[52:53], v[54:55], 0, s[4:5]
	s_movk_i32 s4, 0x2000
	v_lshl_add_u64 v[50:51], v[42:43], 0, s[6:7]
	v_lshl_add_u64 v[44:45], v[42:43], 0, s[8:9]
	v_add_co_u32_e32 v42, vcc, s4, v42
	v_ashrrev_i32_e32 v157, 31, v156
	s_nop 0
	v_addc_co_u32_e32 v43, vcc, 0, v43, vcc
	v_add_co_u32_e32 v70, vcc, s4, v54
	v_lshl_add_u64 v[68:69], v[54:55], 0, s[6:7]
	v_lshl_add_u64 v[46:47], v[54:55], 0, s[8:9]
	v_addc_co_u32_e32 v71, vcc, 0, v55, vcc
	v_lshlrev_b64 v[54:55], 12, v[156:157]
	v_lshlrev_b32_e32 v132, 4, v56
	v_mov_b32_e32 v133, v131
	v_lshl_add_u64 v[54:55], s[68:69], 0, v[54:55]
	global_load_dwordx4 v[2:5], v[6:7], off offset:2048
	s_nop 0
	global_load_dwordx4 v[6:9], v[6:7], off
	s_nop 0
	global_load_dwordx4 v[10:13], v[10:11], off offset:16
	s_nop 0
	global_load_dwordx4 v[14:17], v[48:49], off offset:2048
	global_load_dwordx4 v[18:21], v[48:49], off
	global_load_dwordx4 v[22:25], v[52:53], off offset:16
	global_load_dwordx4 v[26:29], v[44:45], off offset:16
	global_load_dwordx4 v[30:33], v[50:51], off offset:2064
	global_load_dwordx4 v[34:37], v[46:47], off offset:16
	global_load_dwordx4 v[38:41], v[68:69], off offset:2064
	v_lshl_add_u64 v[54:55], v[54:55], 0, v[132:133]
	s_mov_b64 s[4:5], 0x1e100000
	v_lshl_add_u64 v[56:57], v[54:55], 0, s[4:5]
	s_mov_b32 s4, 0x1e100000
	v_add_co_u32_e32 v58, vcc, s4, v54
	s_mov_b64 s[4:5], 0x1b900000
	global_load_dwordx4 v[42:45], v[42:43], off
	s_nop 0
	global_load_dwordx4 v[46:49], v[50:51], off offset:2048
	s_nop 0
	global_load_dwordx4 v[50:53], v[50:51], off offset:16
	v_addc_co_u32_e32 v59, vcc, 0, v55, vcc
	global_load_dwordx4 v[114:117], v[56:57], off offset:1024
	global_load_dwordx4 v[106:109], v[56:57], off offset:2048
	global_load_dwordx4 v[122:125], v[58:59], off
	global_load_dwordx4 v[98:101], v[56:57], off offset:3072
	v_lshl_add_u64 v[72:73], v[54:55], 0, s[4:5]
	s_mov_b32 s4, 0x1b900000
	v_add_co_u32_e32 v54, vcc, s4, v54
	s_mov_b64 s[4:5], 0x3c900000
	s_nop 0
	v_addc_co_u32_e32 v55, vcc, 0, v55, vcc
	global_load_dwordx4 v[126:129], v[54:55], off
	global_load_dwordx4 v[102:105], v[72:73], off offset:3072
	global_load_dwordx4 v[118:121], v[72:73], off offset:1024
	global_load_dwordx4 v[110:113], v[72:73], off offset:2048
	s_nop 0
	global_load_dwordx4 v[54:57], v[70:71], off
	global_load_dwordx4 v[58:61], v[68:69], off offset:2048
	global_load_dwordx4 v[62:65], v[68:69], off offset:16
	v_lshl_add_u64 v[68:69], s[68:69], 0, v[132:133]
	v_ashrrev_i32_e32 v67, 31, v66
	s_ashr_i32 s95, s94, 31
	v_lshl_add_u64 v[134:135], v[68:69], 0, s[4:5]
	v_add_u32_e32 v68, s74, v156
	v_lshl_add_u64 v[66:67], v[66:67], 0, s[94:95]
	v_ashrrev_i32_e32 v69, 31, v68
	v_lshlrev_b64 v[66:67], 12, v[66:67]
	v_lshlrev_b64 v[68:69], 12, v[68:69]
	v_lshl_add_u64 v[66:67], s[68:69], 0, v[66:67]
	s_mov_b64 s[4:5], 0x1b900800
	v_lshl_add_u64 v[136:137], s[68:69], 0, v[68:69]
	s_ashr_i32 s75, s74, 31
	v_lshl_add_u64 v[138:139], v[66:67], 0, s[4:5]
	s_lshl_b64 s[6:7], s[74:75], 12
	s_mov_b64 s[12:13], 0
	s_movk_i32 s15, 0x27ff
	s_mov_b32 s14, 0x3fd744fd
	s_movk_i32 s16, 0x1fff
	s_mov_b32 s17, 0x800000
	s_mov_b32 s18, 0x1000000
	v_mov_b32_e32 v157, 0x3727c5ac
	s_mov_b32 s19, 0xf800000
	v_mov_b32_e32 v158, 0x260
	s_waitcnt vmcnt(10)
	v_mov_b64_e32 v[74:75], v[114:115]
	s_waitcnt vmcnt(9)
	v_mov_b64_e32 v[70:71], v[106:107]
	s_waitcnt vmcnt(8)
	v_mov_b64_e32 v[78:79], v[122:123]
	s_waitcnt vmcnt(7)
	v_mov_b64_e32 v[66:67], v[98:99]
	v_mov_b64_e32 v[68:69], v[100:101]
	s_waitcnt vmcnt(6)
	v_mov_b64_e32 v[94:95], v[126:127]
	s_waitcnt vmcnt(5)
	v_mov_b64_e32 v[82:83], v[102:103]
	s_waitcnt vmcnt(4)
	v_mov_b64_e32 v[90:91], v[118:119]
	s_waitcnt vmcnt(3)
	v_mov_b64_e32 v[86:87], v[110:111]
	v_mov_b64_e32 v[72:73], v[108:109]
	v_mov_b64_e32 v[76:77], v[116:117]
	v_mov_b64_e32 v[80:81], v[124:125]
	v_mov_b64_e32 v[84:85], v[104:105]
	v_mov_b64_e32 v[88:89], v[112:113]
	v_mov_b64_e32 v[92:93], v[120:121]
	v_mov_b64_e32 v[96:97], v[128:129]
	s_branch .LBB0_1290

; template <class Epi, class Sched, bool ABLK = false, bool ALIGN_EPI = true, bool SP2 = true, bool BBLK = true>
; __device__ __forceinline__ void gemm_phase(LAS unsigned char* lds, const Gemm g, const Sched& S, const Epi& E) {
;     const int tid = tid_fresh(), wid = __builtin_amdgcn_readfirstlane(tid >> 6), lane = tid & 63, wr = wid >> 2, wc = wid & 3, fr = lane & 15, fq = lane >> 4;
;     unsigned voffA[2], voffB[2];
; #pragma unroll
;     for (int i = 0; i < 2; ++i) { int R, C; stage_rc(tid * 16 + i * 8192, R, C); const int r32 = Epi::PERM ? perm32(R & 31) : (R & 31);
;         const int Rb = Epi::ADJ ? 64 * (R >> 5) + r32 : (R & ~31) + r32;
;         voffA[i] = (unsigned)(R * (ABLK ? 64 : g.lda) + C) * 2u; voffB[i] = BBLK ? (unsigned)(R * 64 + C) * 2u : (unsigned)(Rb * g.ldb + C) * 2u; }
;     const size_t kstep = (size_t)(BK * 2);
;     const size_t hstepA = (size_t)HALF * (ABLK ? 64 : g.lda) * 2, hstepB = BBLK ? (size_t)16384 : (size_t)(Epi::ADJ ? 32 : HALF) * g.ldb * 2;
;     const size_t tstepB = BBLK ? ((size_t)g.ldb / 64) * 32768 : (size_t)BM * g.ldb * 2;
;     const size_t kstepB = BBLK ? (size_t)32768 : kstep;
;     auto b_k0 = [&](int k0) -> size_t { return BBLK ? (size_t)(k0 / BK) * 32768 : (size_t)k0 * 2; };
;     const unsigned ldsw = (unsigned)wid * 1024u;
;     const int aoff = lds_byte(wr * 64 + fr, fq * 8), boff = lds_byte(wc * 32 + fr, fq * 8);
;     ...
;     Unit cur, nxt; int ui = 0;
;     if (!S.next(0, cur)) return;
;     f32x4 acc[2][2][4][2];
; #pragma unroll
;     for (int a = 0; a < 2; ++a)
; #pragma unroll
;         for (int b = 0; b < 2; ++b)
; #pragma unroll
;             for (int m = 0; m < 4; ++m)
; #pragma unroll
;                 for (int n = 0; n < 2; ++n) acc[a][b][m][n] = (f32x4){0.f, 0.f, 0.f, 0.f};
;     bf16x8 At[4][2], B0[2][2], B1[2][2];
;     auto a_unit = [&](const Unit& u) -> const char* { return ABLK ? (const char*)g.A + (size_t)u.pm * ((size_t)g.lda / 64) * 32768 : (const char*)g.A + (size_t)u.pm * 2 * hstepA; };
; template <int L> __device__ __forceinline__ void do_layer(const Args& a, LAS unsigned char* lds, const XcdBarrier& bar, int G, int b) {
;     ...
;         { pg8::Gemm g{XB, (const bf16_t*)(ws + WS_WHIN), D, D}; pg8::BStatOrder S; S.init(M, 8192, D, b);
;           EpiHgrnIn E{H, ZF, (const float*)(ws + WS_PAR + PAR_LB)}; pg8::gemm_phase<EpiHgrnIn, pg8::BStatOrder>(lds, g, S, E); }
.LBB0_1345:
	s_or_b64 exec, exec, s[8:9]
	s_waitcnt vmcnt(0)
	buffer_inv sc1
	s_waitcnt vmcnt(0)
.LBB0_1346:
	s_or_b64 exec, exec, s[2:3]
	s_add_u32 s76, s68, 0x1b900000
	s_addc_u32 s33, s69, 0
	s_add_u32 s90, s68, 0x1e100000
	s_addc_u32 s91, s69, 0
	v_readlane_b32 s2, v252, 26
	s_add_u32 s62, s68, 0x23100000
	v_mov_b32_e32 v9, v0
	v_readlane_b32 s3, v252, 27
	s_waitcnt lgkmcnt(0)
	s_barrier
	s_addc_u32 s83, s69, 0
	s_and_b64 vcc, exec, s[2:3]
	v_readfirstlane_b32 s4, v9
	s_cbranch_vccnz .LBB0_1366
	v_lshlrev_b32_e32 v2, 4, v9
	v_add_u32_e32 v3, 0x2000, v2
	v_ashrrev_i32_e32 v4, 31, v3
	v_lshrrev_b32_e32 v4, 22, v4
	v_add_u32_e32 v4, v3, v4
	v_ashrrev_i32_e32 v6, 10, v4
	v_mul_i32_i24_e32 v5, 0x400, v6
	v_sub_u32_e32 v3, v3, v5
	v_lshrrev_b32_e32 v5, 4, v3
	v_bitop3_b32 v3, v5, v3, 32 bitop3:0x6c
	v_ashrrev_i32_e32 v5, 31, v3
	v_lshrrev_b32_e32 v5, 26, v5
	v_add_u32_e32 v5, v3, v5
	v_ashrrev_i32_e32 v7, 6, v5
	v_and_b32_e32 v5, 0xc0, v5
	v_sub_u32_e32 v3, v3, v5
	v_mov_b32_e32 v5, 1
	v_lshlrev_b32_e32 v4, 5, v6
	v_ashrrev_i16_sdwa v3, v5, sext(v3) dst_sel:DWORD dst_unused:UNUSED_PAD src0_sel:DWORD src1_sel:BYTE_0
	v_and_b32_e32 v4, 32, v4
	v_bfe_i32 v8, v3, 0, 16
	v_add_u32_e32 v3, v4, v8
	v_lshlrev_b32_e32 v4, 3, v6
	v_and_b32_e32 v4, -16, v4
	v_add_u32_e32 v4, v7, v4
	v_lshlrev_b32_e32 v10, 7, v4
	v_lshl_add_u32 v130, v3, 1, v10
	s_movk_i32 s6, 0xf80
	v_mad_u64_u32 v[132:133], s[2:3], v4, s6, v[130:131]
	v_bfe_i32 v4, v9, 27, 1
	v_lshrrev_b32_e32 v4, 22, v4
	v_add_u32_e32 v4, v2, v4
	v_and_b32_e32 v4, 0xfffffc00, v4
	v_sub_u32_e32 v2, v2, v4
	v_lshrrev_b32_e32 v4, 4, v2
	v_bitop3_b32 v4, v4, v2, 32 bitop3:0x6c
	v_ashrrev_i32_e32 v2, 31, v2
	v_lshrrev_b32_e32 v2, 26, v2
	v_ashrrev_i32_e32 v3, 31, v9
	v_add_u32_e32 v2, v4, v2
	v_lshrrev_b32_e32 v3, 26, v3
	v_ashrrev_i32_e32 v11, 6, v2
	v_add_u32_e32 v3, v9, v3
	v_mul_i32_i24_e32 v2, 64, v11
	v_ashrrev_i32_e32 v10, 6, v3
	v_sub_u32_e32 v2, v4, v2
	v_lshlrev_b32_e32 v3, 5, v10
	v_ashrrev_i16_sdwa v2, v5, sext(v2) dst_sel:DWORD dst_unused:UNUSED_PAD src0_sel:DWORD src1_sel:BYTE_0
	v_and_b32_e32 v3, 32, v3
	v_bfe_i32 v12, v2, 0, 16
	v_add_u32_e32 v2, v3, v12
	v_lshlrev_b32_e32 v3, 3, v10
	v_and_b32_e32 v3, -16, v3
	v_add_u32_e32 v3, v11, v3
	v_lshlrev_b32_e32 v4, 7, v3
	v_lshl_add_u32 v134, v2, 1, v4
	s_add_u32 s1, s68, 0x4100000
	v_mad_u64_u32 v[136:137], s[2:3], v3, s6, v[134:135]
	s_addc_u32 s48, s69, 0
	s_lshr_b32 s2, s70, 30
	s_add_i32 s2, s70, s2
	s_ashr_i32 s34, s2, 2
	v_readlane_b32 s2, v252, 23
	s_sub_i32 s2, s2, s34
	s_lshl_b32 s2, s2, 2
	s_add_i32 s30, s2, s70
	s_ashr_i32 s8, s4, 6
	s_ashr_i32 s35, s34, 31
	s_ashr_i32 s31, s30, 31
	s_ashr_i32 s5, s4, 8
	s_lshl_b32 s49, s8, 10
	s_lshl_b64 s[2:3], s[34:35], 20
	s_lshl_b64 s[6:7], s[30:31], 20
	s_add_u32 s40, s1, s6
	s_addc_u32 s41, s48, s7
	s_add_i32 s31, s49, 0
	s_add_i32 m0, s31, 0x10000
	v_mov_b32_e32 v139, 0
	global_load_lds_dwordx4 v134, s[40:41]
	s_add_i32 m0, s31, 0x12000
	s_add_u32 s6, s40, 0x4000
	global_load_lds_dwordx4 v130, s[40:41]
	s_addc_u32 s7, s41, 0
	s_add_i32 m0, s31, 0x14000
	v_mov_b32_e32 v137, v139
	global_load_lds_dwordx4 v134, s[6:7]
	s_add_i32 m0, s31, 0x16000
	s_add_u32 s36, s76, s2
	s_addc_u32 s37, s33, s3
	s_add_i32 s35, s31, 0x2000
	global_load_lds_dwordx4 v130, s[6:7]
	s_mov_b32 m0, s31
	s_add_u32 s2, s36, 0x80000
	global_load_lds_dwordx4 v136, s[36:37]
	s_mov_b32 m0, s35
	s_addc_u32 s3, s37, 0
	s_add_i32 s50, s31, 0x4000
	global_load_lds_dwordx4 v132, s[36:37]
	s_mov_b32 m0, s50
	s_add_i32 s51, s31, 0x6000
	global_load_lds_dwordx4 v136, s[2:3]
	s_mov_b32 m0, s51
	v_mov_b32_e32 v133, v139
	global_load_lds_dwordx4 v132, s[2:3]
	s_cmp_eq_u32 s5, 1
	s_mov_b32 s52, 0
	v_mov_b32_e32 v135, v139
	v_mov_b32_e32 v131, v139
	v_lshl_add_u64 v[4:5], s[36:37], 0, v[136:137]
	v_lshl_add_u64 v[2:3], s[36:37], 0, v[132:133]
	s_cselect_b64 s[2:3], -1, 0
	s_cmp_lg_u32 s5, 1
	s_mov_b64 s[6:7], 0x80000
	s_cbranch_scc1 .LBB0_1349
	s_barrier

; __device__ __forceinline__ void ph_hgrn_x(const Args& a, LAS unsigned char* lds, int nblk, int b) {
;     unsigned char* ws = a.ws; const bf16_t* Ib = (const bf16_t*)(ws + WS_H) + (size_t)M * D; const unsigned short* F = (const unsigned short*)(ws + WS_Z);
;     const int tid = tid_fresh(), wave = __builtin_amdgcn_readfirstlane(tid >> 6), lane = tid & 63, G4 = lane >> 4, c = lane & 15;
;     const int nun = (2560 - b + nblk - 1) / nblk;
;     __syncthreads();
;     if (wave >= 4) {
;         auto prepare = [&](int u, int buf) {
;             bool samp; int n, h, ch; size_t row0; hg_decode(u, samp, n, h, ch, row0);
;             LAS unsigned char* bb = lds + buf * HX2_BUF;
;             if (wave == 4) {
;                 const unsigned short* Fp = F + row0 * D + h * 128 + 2 * lane; float r0 = 1.f, r1 = 1.f;
;                 unsigned fv[64];
; #pragma unroll
;                 for (int j = 0; j < 64; ++j) fv[j] = *(const unsigned*)(Fp + (size_t)j * D);
; #pragma unroll
;                 for (int j = 63; j >= 0; --j) { const f32x2 g = uph2(fv[j]);
;                     *(LAS unsigned*)(bb + HX2_KH + (j * HG_S + 2 * lane) * 2) = pk2(g[0] * r0, g[1] * r1); r0 *= 1.0f - g[0]; r1 *= 1.0f - g[1]; }
;                 *(LAS f32x2*)(bb + HX2_DK + 8 * lane) = (f32x2){r0, r1};
;                 if (!samp) *(f32x2*)((float*)(ws + WS_SCR + SCR_DK) + (size_t)u * 128 + 2 * lane) = (f32x2){r0, r1};
;             } else if (wave < 7) {
;                 const int t2 = tid - 320, r = t2 >> 1, hf = t2 & 1; const u32x4* src = (const u32x4*)(Ib + (row0 + r) * D + h * 128 + 64 * hf);
;                 LAS u32x4* dst = (LAS u32x4*)(bb + HX2_IS + (r * HG_S + 64 * hf) * 2); u32x4 v[8];
; #pragma unroll
;                 for (int i = 0; i < 8; ++i) v[i] = src[i];
; #pragma unroll
;                 for (int i = 0; i < 8; ++i) dst[i] = v[i];
;             }
;         };
;         prepare(b, 0);
;         __syncthreads();
;         for (int i = 0; i < nun; ++i) { if (i + 1 < nun) prepare(b + (i + 1) * nblk, (i + 1) & 1); __syncthreads(); }
;         return;
;     }
;     __syncthreads();
;     for (int i = 0; i < nun; ++i) {
;         const int u = b + i * nblk; bool samp; int n, h, ch; size_t row0; hg_decode(u, samp, n, h, ch, row0);
;         const LAS unsigned char* bb = lds + (i & 1) * HX2_BUF; const LAS float* dk = (const LAS float*)(bb + HX2_DK);
.LBB0_1417:
	s_or_b64 exec, exec, s[8:9]
	s_waitcnt vmcnt(0)
	buffer_inv sc1
	s_waitcnt vmcnt(0)
.LBB0_1418:
	s_or_b64 exec, exec, s[2:3]
	v_mov_b32_e32 v40, v0
	s_waitcnt lgkmcnt(0)
	s_barrier
	v_readlane_b32 s2, v252, 10
	v_readfirstlane_b32 s1, v40
	s_ashr_i32 s20, s1, 6
	s_sub_i32 s1, s89, s2
	s_add_i32 s2, s1, 0x9ff
	s_sub_i32 s1, 0xfffff601, s1
	v_readlane_b32 s3, v252, 11
	s_max_i32 s1, s2, s1
	s_ashr_i32 s3, s2, 31
	s_mul_hi_u32 s2, s1, s58
	s_mul_i32 s4, s2, s39
	s_sub_i32 s1, s1, s4
	s_xor_b32 s3, s3, s53
	s_add_i32 s4, s2, 1
	s_sub_i32 s5, s1, s39
	s_cmp_ge_u32 s1, s39
	s_cselect_b32 s2, s4, s2
	s_cselect_b32 s1, s5, s1
	s_add_i32 s4, s2, 1
	s_cmp_ge_u32 s1, s39
	s_cselect_b32 s1, s4, s2
	s_xor_b32 s1, s1, s3
	s_sub_i32 s18, s1, s3
	v_and_b32_e32 v19, 63, v40
	s_cmp_lt_i32 s20, 4
	s_mov_b64 s[2:3], -1
	s_barrier
	s_cbranch_scc0 .LBB0_1489
	s_cmp_lt_i32 s18, 1
	s_barrier
	s_cbranch_scc1 .LBB0_1488
	v_lshrrev_b32_e32 v2, 4, v19
	s_lshl_b32 s2, s20, 13
	s_add_i32 s2, s2, 0
	v_lshlrev_b32_e32 v7, 3, v2
	v_bfe_u32 v3, v40, 2, 2
	v_lshlrev_b32_e32 v4, 2, v40
	s_add_i32 s8, s2, 0x11400
	v_or_b32_e32 v3, v7, v3
	s_lshl_b32 s2, s20, 5
	v_and_b32_e32 v4, 12, v4
	s_movk_i32 s3, 0x88
	v_mad_u32_u24 v4, v3, s3, v4
	s_ashr_i32 s3, s2, 31
	s_lshl_b64 s[4:5], s[2:3], 8
	v_lshlrev_b32_e32 v5, 3, v19
	s_add_u32 s4, s68, s4
	v_and_b32_e32 v11, 0x78, v5
	v_mov_b32_e32 v21, 0
	s_addc_u32 s5, s69, s5
	v_lshlrev_b32_e32 v20, 1, v11
	v_lshlrev_b32_e32 v18, 2, v2
	v_lshl_add_u64 v[2:3], s[4:5], 0, v[20:21]
	s_mov_b64 s[4:5], 0x30100000
	s_movk_i32 s9, 0x78
	v_lshl_add_u64 v[22:23], v[2:3], 0, s[4:5]
	v_mov_b32_e32 v2, 0x180
	v_and_b32_e32 v6, 0x180, v5
	v_bitop3_b32 v2, v5, s9, v2 bitop3:0xe0
	v_lshlrev_b32_e32 v2, 1, v2
	v_or_b32_e32 v8, 0x800, v6
	s_load_dwordx2 s[10:11], s[86:87], 0x30
	s_load_dwordx2 s[4:5], s[86:87], 0xf0
	v_or_b32_e32 v15, 0x400, v2
	v_or_b32_e32 v16, 0x800, v2
	v_or_b32_e32 v17, 0xc00, v2
	v_or_b32_e32 v2, v8, v11
	v_or_b32_e32 v10, 0xa00, v6
	v_lshlrev_b32_e32 v24, 1, v2
	v_or_b32_e32 v2, v10, v11
	v_or_b32_e32 v12, 0xc00, v6
	s_or_b32 s6, s2, 16
	v_lshlrev_b32_e32 v25, 1, v2
	v_or_b32_e32 v2, v12, v11
	v_or_b32_e32 v14, 0xe00, v6
	v_and_b32_e32 v41, 15, v40
	s_ashr_i32 s7, s6, 31
	v_lshlrev_b32_e32 v27, 1, v2
	v_or_b32_e32 v2, v14, v11
	v_lshl_add_u32 v9, v41, 8, s8
	v_lshlrev_b32_e32 v13, 4, v19
	v_lshlrev_b32_e32 v11, 1, v2
	s_waitcnt lgkmcnt(0)
	s_add_u32 s12, s4, 0x9880000
	s_mov_b32 s1, 0
	v_lshlrev_b32_e32 v42, 1, v4
	v_add_lshl_u32 v43, v4, s2, 1
	v_add_lshl_u32 v44, v4, s6, 1
	s_addc_u32 s13, s5, 0
	s_lshl_b32 s19, s2, 2
	v_mov_b32_e32 v2, v21
	v_mov_b32_e32 v3, v21
	v_mov_b32_e32 v4, v21
	v_mov_b32_e32 v5, v21
	v_add_u32_e32 v45, s8, v13
	v_lshlrev_b32_e32 v20, 1, v6
	v_add_u32_e32 v46, s8, v15
	v_add_u32_e32 v47, s8, v16
	v_add_u32_e32 v48, s8, v17
	v_add_u32_e32 v49, s8, v24
	v_lshlrev_b32_e32 v24, 1, v8
	v_add_u32_e32 v50, s8, v25
	v_lshlrev_b32_e32 v26, 1, v10
	v_add_u32_e32 v51, s8, v27
	v_lshlrev_b32_e32 v28, 1, v12
	v_add_u32_e32 v52, s8, v11
	v_lshlrev_b32_e32 v30, 1, v14
	v_add_u32_e32 v53, v9, v7
	v_readlane_b32 s14, v252, 10
	v_readlane_b32 s15, v252, 11
	s_branch .LBB0_1422

; __device__ __forceinline__ int tid_fresh() { int t = threadIdx.x; asm volatile("" : "+v"(t)); return t; }
; __device__ __forceinline__ void ph_hgrn_y(const Args& a, int nblk, int b) {
;     unsigned char* ws = a.ws; const bf16_t* DS = (const bf16_t*)(ws + WS_SCR + SCR_DS); const float* DK = (const float*)(ws + WS_SCR + SCR_DK); bf16_t* SP = (bf16_t*)(ws + WS_SCR + SCR_SP);
;     const int nth = nblk * 512;
;     const int tid = tid_fresh();
;     for (int e4 = b * 512 + tid; e4 < 64 * 4096; e4 += nth) {
;         const int pr = e4 >> 12, off = (e4 & 4095) * 4, k = off >> 7;
;         f32x4 S = (f32x4){0.f, 0.f, 0.f, 0.f};
; #pragma unroll 1
;         for (int c8 = 0; c8 < 32; c8 += 8) {
;             f32x4 d[8]; float dk[8];
; #pragma unroll
;             for (int i = 0; i < 8; ++i) { const size_t u = (size_t)pr * 32 + c8 + i; const u32x2 w = *(const u32x2*)(DS + u * 16384 + off);
;                 d[i] = (f32x4){__builtin_bit_cast(float, w.x << 16), __builtin_bit_cast(float, w.x & 0xffff0000u), __builtin_bit_cast(float, w.y << 16), __builtin_bit_cast(float, w.y & 0xffff0000u)}; dk[i] = DK[u * 128 + k]; }
.LBB0_1567:
	s_or_b64 exec, exec, s[8:9]
	s_waitcnt vmcnt(0)
	buffer_inv sc1
	s_waitcnt vmcnt(0)
.LBB0_1568:
	s_or_b64 exec, exec, s[2:3]
	s_waitcnt lgkmcnt(0)
	v_mov_b32_e32 v2, v0
	s_barrier
	s_mov_b32 s1, 0x40000
	v_add_u32_e32 v16, s96, v2
	v_cmp_gt_i32_e32 vcc, s1, v16
	s_and_saveexec_b64 s[2:3], vcc
	s_cbranch_execz .LBB0_1573
	s_load_dwordx2 s[4:5], s[86:87], 0xf0
	v_lshlrev_b32_e32 v2, 2, v2
	v_readlane_b32 s8, v252, 10
	v_readlane_b32 s9, v252, 11
	s_mov_b64 s[6:7], 0
	v_lshl_add_u32 v17, s8, 11, v2
	s_waitcnt lgkmcnt(0)
	s_add_u32 s8, s4, 0x7080000
	s_addc_u32 s9, s5, 0
	s_lshl_b32 s1, s89, 11
	s_movk_i32 s4, 0x7ff8
	s_mov_b32 s5, 0x34200000
	s_mov_b32 s14, 0x34208000
	s_mov_b32 s15, 0x34210000
	s_mov_b32 s16, 0x34218000
	s_mov_b32 s17, 0x34220000
	s_mov_b32 s18, 0x34228000
	s_mov_b32 s19, 0x34230000
	s_mov_b32 s20, 0x34238000
	s_mov_b64 s[10:11], 0x1000
	s_mov_b64 s[12:13], 0x40000
	v_mov_b32_e32 v7, 0
	s_mov_b32 s21, 0x3ffff

; #define LAS __attribute__((address_space(3)))
; __device__ __forceinline__ int tid_fresh() { int t = threadIdx.x; asm volatile("" : "+v"(t)); return t; }
; __device__ __forceinline__ void ph_hgrn_z(const Args& a, LAS unsigned char* lds, int nblk, int b) {
;     unsigned char* ws = a.ws; const bf16_t* Qb = (const bf16_t*)(ws + WS_H); const bf16_t* Ib = Qb + (size_t)M * D; const bf16_t* Gb = Ib + (size_t)M * D; const unsigned short* F = (const unsigned short*)(ws + WS_Z);
;     bf16_t* Y = (bf16_t*)(ws + WS_Y); const bf16_t* SP = (const bf16_t*)(ws + WS_SCR + SCR_SP);
;     const int tid = tid_fresh(), wave = __builtin_amdgcn_readfirstlane(tid >> 6), lane = tid & 63, G4 = lane >> 4, c = lane & 15, kp = tid & 63, tq = tid >> 6;
;     LAS float* part = (LAS float*)(lds + HGZ_PART); LAS float* red = (LAS float*)(lds + HGZ_RED);
;     const int mt = wave;
;     unsigned fF[8]; unsigned fQ[8]; u32x4 fI[2]; f32x4 fS[8];
;     auto ldunit = [&](int u2) { bool s2; int n2, h2, c2; size_t r2; hg_decode(u2, s2, n2, h2, c2, r2); hg_loadf(F + r2 * D + h2 * 128, kp, tq, fF);
; #pragma unroll
;         for (int j = 0; j < 8; ++j) fQ[j] = *(const unsigned*)(Qb + (r2 + 8 * tq + j) * D + h2 * 128 + 2 * kp);
;         const u32x4* src = (const u32x4*)(Ib + (r2 + (tid >> 3)) * D + h2 * 128 + 16 * (tid & 7)); fI[0] = src[0]; fI[1] = src[1];
;         const int r = tid >> 2, cq = tid & 3;
;         if (!s2) { const u32x4* sp = (const u32x4*)(SP + (size_t)u2 * 16384 + r * 128 + 32 * cq);
; #pragma unroll
;             for (int i = 0; i < 4; ++i) fS[i] = __builtin_bit_cast(f32x4, sp[i]); }
;         else { const f32x4* sp = (const f32x4*)(a.in[6] + (((size_t)n2 * NH + h2) * 128 + r) * 128 + 32 * cq);
; #pragma unroll
;             for (int i = 0; i < 8; ++i) fS[i] = sp[i]; } };
;     __syncthreads();
;     if (tid < 128) red[tid] = a.in[22][tid];
;     if (b < 2560) ldunit(b);
.LBB0_1624:
	s_or_b64 exec, exec, s[8:9]
	s_waitcnt vmcnt(0)
	buffer_inv sc1
	s_waitcnt vmcnt(0)
.LBB0_1625:
	s_or_b64 exec, exec, s[2:3]
	v_mov_b32_e32 v42, v0
	s_movk_i32 s1, 0x80
	s_waitcnt lgkmcnt(0)
	s_barrier
	s_nop 0
	v_readfirstlane_b32 s14, v42
	v_cmp_gt_i32_e32 vcc, s1, v42
	s_barrier
	s_and_saveexec_b64 s[2:3], vcc
	s_cbranch_execz .LBB0_1627
	s_load_dwordx2 s[4:5], s[86:87], 0xb0
	v_ashrrev_i32_e32 v43, 31, v42
	s_waitcnt lgkmcnt(0)
	v_lshl_add_u64 v[2:3], v[42:43], 2, s[4:5]
	global_load_dword v2, v[2:3], off
	v_lshl_add_u32 v3, v42, 2, 0
	v_add_u32_e32 v3, 0x1a800, v3
	s_waitcnt vmcnt(0)
	ds_write_b32 v3, v2

; template <class Epi, class Sched, bool ABLK = false, bool ALIGN_EPI = true, bool SP2 = true, bool BBLK = true>
; __device__ __forceinline__ void gemm_phase(LAS unsigned char* lds, const Gemm g, const Sched& S, const Epi& E) {
;     const int tid = tid_fresh(), wid = __builtin_amdgcn_readfirstlane(tid >> 6), lane = tid & 63, wr = wid >> 2, wc = wid & 3, fr = lane & 15, fq = lane >> 4;
;     unsigned voffA[2], voffB[2];
; #pragma unroll
;     for (int i = 0; i < 2; ++i) { int R, C; stage_rc(tid * 16 + i * 8192, R, C); const int r32 = Epi::PERM ? perm32(R & 31) : (R & 31);
;         const int Rb = Epi::ADJ ? 64 * (R >> 5) + r32 : (R & ~31) + r32;
;         voffA[i] = (unsigned)(R * (ABLK ? 64 : g.lda) + C) * 2u; voffB[i] = BBLK ? (unsigned)(R * 64 + C) * 2u : (unsigned)(Rb * g.ldb + C) * 2u; }
;     const size_t kstep = (size_t)(BK * 2);
;     const size_t hstepA = (size_t)HALF * (ABLK ? 64 : g.lda) * 2, hstepB = BBLK ? (size_t)16384 : (size_t)(Epi::ADJ ? 32 : HALF) * g.ldb * 2;
;     const size_t tstepB = BBLK ? ((size_t)g.ldb / 64) * 32768 : (size_t)BM * g.ldb * 2;
;     const size_t kstepB = BBLK ? (size_t)32768 : kstep;
;     auto b_k0 = [&](int k0) -> size_t { return BBLK ? (size_t)(k0 / BK) * 32768 : (size_t)k0 * 2; };
;     const unsigned ldsw = (unsigned)wid * 1024u;
;     const int aoff = lds_byte(wr * 64 + fr, fq * 8), boff = lds_byte(wc * 32 + fr, fq * 8);
;     ...
;     Unit cur, nxt; int ui = 0;
;     if (!S.next(0, cur)) return;
;     f32x4 acc[2][2][4][2];
; #pragma unroll
;     for (int a = 0; a < 2; ++a)
; #pragma unroll
;         for (int b = 0; b < 2; ++b)
; #pragma unroll
;             for (int m = 0; m < 4; ++m)
; #pragma unroll
;                 for (int n = 0; n < 2; ++n) acc[a][b][m][n] = (f32x4){0.f, 0.f, 0.f, 0.f};
;     bf16x8 At[4][2], B0[2][2], B1[2][2];
;     auto a_unit = [&](const Unit& u) -> const char* { return ABLK ? (const char*)g.A + (size_t)u.pm * ((size_t)g.lda / 64) * 32768 : (const char*)g.A + (size_t)u.pm * 2 * hstepA; };
; template <int L> __device__ __forceinline__ void do_layer(const Args& a, LAS unsigned char* lds, const XcdBarrier& bar, int G, int b) {
;     ...
;         { pg8::Gemm g{Y, (const bf16_t*)(ws + WS_WHO), D, D}; pg8::SplitOrder S; S.init(D, b);
;           EpiRes E{Z, PS}; pg8::gemm_phase<EpiRes, pg8::SplitOrder>(lds, g, S, E); }
.LBB0_1709:
	s_or_b64 exec, exec, s[8:9]
	s_waitcnt vmcnt(0)
	buffer_inv sc1
	s_waitcnt vmcnt(0)
.LBB0_1710:
	s_or_b64 exec, exec, s[2:3]
	s_waitcnt vmcnt(2)
	v_mov_b32_e32 v7, v0
	s_waitcnt lgkmcnt(0)
	s_barrier
	s_movk_i32 s6, 0xf080
	v_ashrrev_i32_e32 v2, 31, v7
	v_lshrrev_b32_e32 v2, 26, v2
	v_add_u32_e32 v2, v7, v2
	v_ashrrev_i32_e32 v6, 6, v2
	v_bfe_i32 v2, v7, 27, 1
	v_lshlrev_b32_e32 v1, 4, v7
	v_lshrrev_b32_e32 v2, 22, v2
	v_add_u32_e32 v2, v1, v2
	v_and_b32_e32 v2, 0xfffffc00, v2
	v_sub_u32_e32 v2, v1, v2
	v_lshrrev_b32_e32 v3, 4, v2
	v_bitop3_b32 v3, v3, v2, 32 bitop3:0x6c
	v_ashrrev_i32_e32 v2, 31, v2
	v_lshrrev_b32_e32 v2, 26, v2
	v_add_u32_e32 v2, v3, v2
	v_ashrrev_i32_e32 v8, 6, v2
	v_lshlrev_b32_e32 v4, 3, v6
	v_mul_i32_i24_e32 v5, 64, v8
	v_and_b32_e32 v4, -16, v4
	v_sub_u32_e32 v3, v3, v5
	v_mov_b32_e32 v5, 1
	v_add_u32_e32 v2, v8, v4
	v_lshlrev_b32_e32 v4, 5, v6
	v_ashrrev_i16_sdwa v3, v5, sext(v3) dst_sel:DWORD dst_unused:UNUSED_PAD src0_sel:DWORD src1_sel:BYTE_0
	v_and_b32_e32 v4, 32, v4
	v_bfe_i32 v9, v3, 0, 16
	v_add_u32_e32 v3, v4, v9
	v_lshlrev_b32_e32 v4, 12, v2
	v_lshl_add_u32 v130, v3, 1, v4
	v_add_u32_e32 v1, 0x2000, v1
	v_mad_u64_u32 v[132:133], s[2:3], v2, s6, v[130:131]
	v_ashrrev_i32_e32 v2, 31, v1
	v_lshrrev_b32_e32 v2, 22, v2
	v_add_u32_e32 v2, v1, v2
	s_waitcnt vmcnt(1)
	v_ashrrev_i32_e32 v10, 10, v2
	v_mul_i32_i24_e32 v2, 0x400, v10
	v_sub_u32_e32 v1, v1, v2
	v_lshrrev_b32_e32 v2, 4, v1
	v_bitop3_b32 v1, v2, v1, 32 bitop3:0x6c
	v_ashrrev_i32_e32 v3, 31, v1
	v_lshrrev_b32_e32 v3, 26, v3
	v_add_u32_e32 v3, v1, v3
	v_ashrrev_i32_e32 v11, 6, v3
	v_and_b32_e32 v3, 0xc0, v3
	v_lshlrev_b32_e32 v2, 3, v10
	v_sub_u32_e32 v1, v1, v3
	s_add_u32 s1, s68, 0x2d100000
	v_and_b32_e32 v2, -16, v2
	v_lshlrev_b32_e32 v4, 5, v10
	v_ashrrev_i16_sdwa v1, v5, sext(v1) dst_sel:DWORD dst_unused:UNUSED_PAD src0_sel:DWORD src1_sel:BYTE_0
	s_addc_u32 s36, s69, 0
	v_add_u32_e32 v2, v11, v2
	v_and_b32_e32 v4, 32, v4
	v_bfe_i32 v12, v1, 0, 16
	s_add_u32 s37, s68, 0x6100000
	v_readfirstlane_b32 s4, v7
	v_add_u32_e32 v1, v4, v12
	v_lshlrev_b32_e32 v3, 12, v2
	s_addc_u32 s38, s69, 0
	s_ashr_i32 s5, s4, 6
	v_lshl_add_u32 v134, v1, 1, v3
	v_mad_u64_u32 v[136:137], s[2:3], v2, s6, v[134:135]
	s_ashr_i32 s6, s4, 8
	s_lshl_b32 s39, s5, 10
	s_add_u32 s26, s37, s97
	s_addc_u32 s27, s38, 0
	s_add_i32 s40, s39, 0
	s_add_i32 m0, s40, 0x10000
	v_mov_b32_e32 v133, 0
	global_load_lds_dwordx4 v132, s[26:27]
	s_add_i32 m0, s40, 0x12000
	s_add_u32 s2, s26, 0x4000
	global_load_lds_dwordx4 v136, s[26:27]
	s_addc_u32 s3, s27, 0
	s_add_i32 m0, s40, 0x14000
	v_mov_b32_e32 v131, v133
	global_load_lds_dwordx4 v132, s[2:3]
	s_add_i32 m0, s40, 0x16000
	v_mov_b32_e32 v135, v133
	global_load_lds_dwordx4 v136, s[2:3]
	v_readlane_b32 s2, v252, 24
	v_readlane_b32 s3, v252, 25
	s_add_u32 s28, s1, s2
	s_addc_u32 s29, s36, s3
	s_add_i32 s41, s40, 0x2000
	s_mov_b32 m0, s40
	s_add_u32 s2, s28, 0x80000
	global_load_lds_dwordx4 v130, s[28:29]
	s_mov_b32 m0, s41
	s_addc_u32 s3, s29, 0
	s_add_i32 s42, s40, 0x4000
	global_load_lds_dwordx4 v134, s[28:29]
	s_mov_b32 m0, s42
	s_add_i32 s43, s40, 0x6000
	global_load_lds_dwordx4 v130, s[2:3]
	s_mov_b32 m0, s43
	s_cmp_eq_u32 s6, 1
	global_load_lds_dwordx4 v134, s[2:3]
	s_mov_b32 s47, 32
	s_mov_b32 s46, 0
	v_mov_b32_e32 v137, v133
	v_lshl_add_u64 v[2:3], s[28:29], 0, v[130:131]
	s_cselect_b64 s[2:3], -1, 0
	s_cmp_lg_u32 s6, 1
	v_lshl_add_u64 v[4:5], s[28:29], 0, v[134:135]
	s_cbranch_scc1 .LBB0_1712
	s_barrier

; __device__ __forceinline__ void ph_ln(const Args& a, int L, int which, bool final_, bool split, bool wr_x, bool res_inputs, int nblk, int b) {
;     unsigned char* ws = a.ws; const bf16_t* P = (const bf16_t*)(ws + WS_SCR + SCR_PART);
;     const bf16_t* Z = (const bf16_t*)(ws + WS_Z); float* Xo = final_ ? a.out : (float*)(ws + WS_X); bf16_t* XB = (bf16_t*)(ws + WS_XB);
;     auto lo = [](unsigned w) -> float { return __builtin_bit_cast(float, w << 16); }; auto hi = [](unsigned w) -> float { return __builtin_bit_cast(float, w & 0xffff0000u); };
;     const float* gam = a.in[which ? 26 : 24] + (size_t)L * D; const float* bet = a.in[which ? 27 : 25] + (size_t)L * D;
;     const int tid = tid_fresh(); const int lane = tid & 63, gw = b * 8 + (tid >> 6), ngw = nblk * 8;
;     f32x4 gg[4][2], bb[4][2];
; #pragma unroll
;     for (int j = 0; j < 4; ++j)
; #pragma unroll
;         for (int h = 0; h < 2; ++h) { gg[j][h] = *(const f32x4*)(gam + 512 * j + 8 * lane + 4 * h); bb[j][h] = *(const f32x4*)(bet + 512 * j + 8 * lane + 4 * h); }
;     u32x4 zc[4], xc[4];
;     auto ldrow = [&](int r) { const u32x4* zr = (const u32x4*)(Z + (size_t)r * D) + lane;
; #pragma unroll
;         for (int j = 0; j < 4; ++j) zc[j] = zr[64 * j];
;         if (!res_inputs) { const u32x4* xr = (const u32x4*)(XB + (size_t)r * D) + lane;
; #pragma unroll
;             for (int j = 0; j < 4; ++j) xc[j] = xr[64 * j]; } };
;     if (gw < M) ldrow(gw);
;     for (int r = gw; r < M; r += ngw) {
;         float v[4][8];
; #pragma unroll
;         for (int j = 0; j < 4; ++j)
; #pragma unroll
;             for (int e = 0; e < 4; ++e) { v[j][2 * e] = lo(zc[j][e]); v[j][2 * e + 1] = hi(zc[j][e]); }
;         if (!res_inputs) {
; #pragma unroll
;             for (int j = 0; j < 4; ++j)
; #pragma unroll
;                 for (int e = 0; e < 4; ++e) { v[j][2 * e] += ALPHA * lo(xc[j][e]); v[j][2 * e + 1] += ALPHA * hi(xc[j][e]); } }
;         if (r + ngw < M) ldrow(r + ngw);
;         if (split && r >= MP) {
; #pragma unroll
;             for (int p = 0; p < 3; ++p) { const u32x4* pr = (const u32x4*)(P + ((size_t)p * MS + (r - MP)) * D) + lane;
; #pragma unroll
;                 for (int j = 0; j < 4; ++j) { const u32x4 w = pr[64 * j];
; #pragma unroll
;                     for (int e = 0; e < 4; ++e) { v[j][2 * e] += lo(w[e]); v[j][2 * e + 1] += hi(w[e]); } } } }
.LBB0_1773:
	s_or_b64 exec, exec, s[8:9]
	s_waitcnt vmcnt(0)
	buffer_inv sc1
	s_waitcnt vmcnt(0)
.LBB0_1774:
	s_or_b64 exec, exec, s[2:3]
	s_waitcnt lgkmcnt(0)
	v_mov_b32_e32 v1, v0
	s_barrier
	s_movk_i32 s1, 0x2800
	v_ashrrev_i32_e32 v66, 6, v1
	v_add_u32_e32 v156, s94, v66
	v_cmp_gt_i32_e32 vcc, s1, v156
	s_and_saveexec_b64 s[2:3], vcc
	s_cbranch_execz .LBB0_1781
	s_load_dwordx4 s[4:7], s[86:87], 0xc0
	v_and_b32_e32 v1, 63, v1
	v_mov_b32_e32 v131, 0
	v_lshlrev_b32_e32 v130, 5, v1
	s_mov_b64 s[8:9], 0x5800
	s_waitcnt lgkmcnt(0)
	v_lshl_add_u64 v[42:43], s[6:7], 0, v[130:131]
	v_add_co_u32_e32 v6, vcc, 0x5000, v42
	v_lshl_add_u64 v[56:57], s[4:5], 0, v[130:131]
	s_nop 0
	v_addc_co_u32_e32 v7, vcc, 0, v43, vcc
	v_add_co_u32_e32 v48, vcc, 0x5000, v56
	s_mov_b64 s[4:5], 0x5000
	s_mov_b64 s[6:7], 0x4000
	v_addc_co_u32_e32 v49, vcc, 0, v57, vcc
	v_lshl_add_u64 v[10:11], v[42:43], 0, s[4:5]
	v_lshl_add_u64 v[50:51], v[56:57], 0, s[4:5]
	s_movk_i32 s4, 0x4000
	v_lshl_add_u64 v[54:55], v[42:43], 0, s[6:7]
	v_lshl_add_u64 v[44:45], v[42:43], 0, s[8:9]
	v_add_co_u32_e32 v42, vcc, s4, v42
	v_lshl_add_u64 v[46:47], v[56:57], 0, s[8:9]
	s_nop 0
	v_addc_co_u32_e32 v43, vcc, 0, v43, vcc
	v_ashrrev_i32_e32 v157, 31, v156
	v_lshl_add_u64 v[68:69], v[56:57], 0, s[6:7]
	global_load_dwordx4 v[2:5], v[6:7], off offset:2048
	s_nop 0
	global_load_dwordx4 v[6:9], v[6:7], off
	s_nop 0
	global_load_dwordx4 v[10:13], v[10:11], off offset:16
	s_nop 0
	global_load_dwordx4 v[14:17], v[48:49], off offset:2048
	global_load_dwordx4 v[18:21], v[48:49], off
	global_load_dwordx4 v[22:25], v[50:51], off offset:16
	global_load_dwordx4 v[26:29], v[44:45], off offset:16
	global_load_dwordx4 v[30:33], v[54:55], off offset:2064
	global_load_dwordx4 v[34:37], v[46:47], off offset:16
	global_load_dwordx4 v[38:41], v[68:69], off offset:2064
	s_nop 0
	global_load_dwordx4 v[42:45], v[42:43], off
	s_nop 0
	global_load_dwordx4 v[46:49], v[54:55], off offset:2048
	global_load_dwordx4 v[50:53], v[54:55], off offset:16
	v_lshlrev_b64 v[54:55], 12, v[156:157]
	v_lshlrev_b32_e32 v132, 4, v1
	v_mov_b32_e32 v133, v131
	v_lshl_add_u64 v[54:55], s[68:69], 0, v[54:55]
	v_add_co_u32_e32 v70, vcc, s4, v56
	v_lshl_add_u64 v[54:55], v[54:55], 0, v[132:133]
	s_mov_b64 s[4:5], 0x1e100000
	v_addc_co_u32_e32 v71, vcc, 0, v57, vcc
	v_lshl_add_u64 v[56:57], v[54:55], 0, s[4:5]
	s_mov_b32 s4, 0x1e100000
	v_add_co_u32_e32 v58, vcc, s4, v54
	s_mov_b64 s[4:5], 0x1b900000
	s_nop 0
	v_addc_co_u32_e32 v59, vcc, 0, v55, vcc
	global_load_dwordx4 v[114:117], v[56:57], off offset:1024
	global_load_dwordx4 v[106:109], v[56:57], off offset:2048
	global_load_dwordx4 v[122:125], v[58:59], off
	global_load_dwordx4 v[98:101], v[56:57], off offset:3072
	v_lshl_add_u64 v[72:73], v[54:55], 0, s[4:5]
	s_mov_b32 s4, 0x1b900000
	v_add_co_u32_e32 v54, vcc, s4, v54
	s_mov_b64 s[4:5], 0x3c900000
	s_nop 0
	v_addc_co_u32_e32 v55, vcc, 0, v55, vcc
	global_load_dwordx4 v[126:129], v[54:55], off
	global_load_dwordx4 v[102:105], v[72:73], off offset:3072
	global_load_dwordx4 v[118:121], v[72:73], off offset:1024
	global_load_dwordx4 v[110:113], v[72:73], off offset:2048
	s_nop 0
	global_load_dwordx4 v[54:57], v[70:71], off
	global_load_dwordx4 v[58:61], v[68:69], off offset:2048
	global_load_dwordx4 v[62:65], v[68:69], off offset:16
	v_lshl_add_u64 v[68:69], s[68:69], 0, v[132:133]
	v_ashrrev_i32_e32 v67, 31, v66
	s_ashr_i32 s95, s94, 31
	v_lshl_add_u64 v[134:135], v[68:69], 0, s[4:5]
	v_add_u32_e32 v68, s74, v156
	v_lshl_add_u64 v[66:67], v[66:67], 0, s[94:95]
	v_ashrrev_i32_e32 v69, 31, v68
	v_lshlrev_b64 v[66:67], 12, v[66:67]
	v_lshlrev_b64 v[68:69], 12, v[68:69]
	v_lshl_add_u64 v[66:67], s[68:69], 0, v[66:67]
	s_mov_b64 s[4:5], 0x1b900800
	v_lshl_add_u64 v[136:137], s[68:69], 0, v[68:69]
	s_ashr_i32 s75, s74, 31
	v_lshl_add_u64 v[138:139], v[66:67], 0, s[4:5]
	s_lshl_b64 s[6:7], s[74:75], 12
	s_mov_b64 s[14:15], 0
	s_movk_i32 s17, 0x27ff
	s_mov_b32 s16, 0x3fd744fd
	s_movk_i32 s18, 0x1fff
	s_mov_b32 s19, 0x800000
	s_mov_b32 s20, 0x1000000
	v_mov_b32_e32 v1, 0x3727c5ac
	s_mov_b32 s21, 0xf800000
	v_mov_b32_e32 v157, 0x260
	s_waitcnt vmcnt(10)
	v_mov_b64_e32 v[74:75], v[114:115]
	s_waitcnt vmcnt(9)
	v_mov_b64_e32 v[70:71], v[106:107]
	s_waitcnt vmcnt(8)
	v_mov_b64_e32 v[78:79], v[122:123]
	s_waitcnt vmcnt(7)
	v_mov_b64_e32 v[66:67], v[98:99]
	v_mov_b64_e32 v[68:69], v[100:101]
	s_waitcnt vmcnt(6)
	v_mov_b64_e32 v[94:95], v[126:127]
	s_waitcnt vmcnt(5)
	v_mov_b64_e32 v[82:83], v[102:103]
	s_waitcnt vmcnt(4)
	v_mov_b64_e32 v[90:91], v[118:119]
	s_waitcnt vmcnt(3)
	v_mov_b64_e32 v[86:87], v[110:111]
	v_mov_b64_e32 v[72:73], v[108:109]
	v_mov_b64_e32 v[76:77], v[116:117]
	v_mov_b64_e32 v[80:81], v[124:125]
	v_mov_b64_e32 v[84:85], v[104:105]
	v_mov_b64_e32 v[88:89], v[112:113]
	v_mov_b64_e32 v[92:93], v[120:121]
	v_mov_b64_e32 v[96:97], v[128:129]
	s_branch .LBB0_1777

; template <class Epi, class Sched, bool ABLK = false, bool ALIGN_EPI = true, bool SP2 = true, bool BBLK = true>
; __device__ __forceinline__ void gemm_phase(LAS unsigned char* lds, const Gemm g, const Sched& S, const Epi& E) {
;     const int tid = tid_fresh(), wid = __builtin_amdgcn_readfirstlane(tid >> 6), lane = tid & 63, wr = wid >> 2, wc = wid & 3, fr = lane & 15, fq = lane >> 4;
;     unsigned voffA[2], voffB[2];
; #pragma unroll
;     for (int i = 0; i < 2; ++i) { int R, C; stage_rc(tid * 16 + i * 8192, R, C); const int r32 = Epi::PERM ? perm32(R & 31) : (R & 31);
;         const int Rb = Epi::ADJ ? 64 * (R >> 5) + r32 : (R & ~31) + r32;
;         voffA[i] = (unsigned)(R * (ABLK ? 64 : g.lda) + C) * 2u; voffB[i] = BBLK ? (unsigned)(R * 64 + C) * 2u : (unsigned)(Rb * g.ldb + C) * 2u; }
;     const size_t kstep = (size_t)(BK * 2);
;     const size_t hstepA = (size_t)HALF * (ABLK ? 64 : g.lda) * 2, hstepB = BBLK ? (size_t)16384 : (size_t)(Epi::ADJ ? 32 : HALF) * g.ldb * 2;
;     const size_t tstepB = BBLK ? ((size_t)g.ldb / 64) * 32768 : (size_t)BM * g.ldb * 2;
;     const size_t kstepB = BBLK ? (size_t)32768 : kstep;
;     auto b_k0 = [&](int k0) -> size_t { return BBLK ? (size_t)(k0 / BK) * 32768 : (size_t)k0 * 2; };
;     const unsigned ldsw = (unsigned)wid * 1024u;
;     const int aoff = lds_byte(wr * 64 + fr, fq * 8), boff = lds_byte(wc * 32 + fr, fq * 8);
;     ...
;     Unit cur, nxt; int ui = 0;
;     if (!S.next(0, cur)) return;
;     f32x4 acc[2][2][4][2];
; #pragma unroll
;     for (int a = 0; a < 2; ++a)
; #pragma unroll
;         for (int b = 0; b < 2; ++b)
; #pragma unroll
;             for (int m = 0; m < 4; ++m)
; #pragma unroll
;                 for (int n = 0; n < 2; ++n) acc[a][b][m][n] = (f32x4){0.f, 0.f, 0.f, 0.f};
;     bf16x8 At[4][2], B0[2][2], B1[2][2];
;     auto a_unit = [&](const Unit& u) -> const char* { return ABLK ? (const char*)g.A + (size_t)u.pm * ((size_t)g.lda / 64) * 32768 : (const char*)g.A + (size_t)u.pm * 2 * hstepA; };
; template <int L> __device__ __forceinline__ void do_layer(const Args& a, LAS unsigned char* lds, const XcdBarrier& bar, int G, int b) {
;     ...
;     { pg8::Gemm g{XB, (const bf16_t*)(ws + WS_WF1) + (size_t)L * FF * D, D, D}; pg8::BStatOrder S; S.init(M, FF, D, b);
;       EpiFfn1 E{H}; pg8::gemm_phase<EpiFfn1, pg8::BStatOrder>(lds, g, S, E); }
.LBB0_1832:
	s_or_b64 exec, exec, s[8:9]
	s_waitcnt vmcnt(0)
	buffer_inv sc1
	s_waitcnt vmcnt(0)
.LBB0_1833:
	s_or_b64 exec, exec, s[2:3]
	v_readlane_b32 s2, v252, 26
	s_waitcnt lgkmcnt(0)
	v_mov_b32_e32 v1, v0
	v_readlane_b32 s3, v252, 27
	s_barrier
	s_and_b64 vcc, exec, s[2:3]
	v_readfirstlane_b32 s6, v1
	s_cbranch_vccnz .LBB0_1849
	v_lshlrev_b32_e32 v2, 4, v1
	v_add_u32_e32 v3, 0x2000, v2
	v_ashrrev_i32_e32 v4, 31, v3
	v_lshrrev_b32_e32 v4, 22, v4
	v_add_u32_e32 v4, v3, v4
	v_ashrrev_i32_e32 v6, 10, v4
	v_mul_i32_i24_e32 v5, 0x400, v6
	v_sub_u32_e32 v3, v3, v5
	v_lshrrev_b32_e32 v5, 4, v3
	v_bitop3_b32 v3, v5, v3, 32 bitop3:0x6c
	v_ashrrev_i32_e32 v5, 31, v3
	v_lshrrev_b32_e32 v5, 26, v5
	v_add_u32_e32 v5, v3, v5
	v_ashrrev_i32_e32 v7, 6, v5
	v_and_b32_e32 v5, 0xc0, v5
	v_sub_u32_e32 v3, v3, v5
	v_mov_b32_e32 v5, 1
	v_lshlrev_b32_e32 v4, 5, v6
	v_ashrrev_i16_sdwa v3, v5, sext(v3) dst_sel:DWORD dst_unused:UNUSED_PAD src0_sel:DWORD src1_sel:BYTE_0
	v_and_b32_e32 v4, 32, v4
	v_bfe_i32 v8, v3, 0, 16
	v_add_u32_e32 v3, v4, v8
	v_lshlrev_b32_e32 v4, 3, v6
	v_and_b32_e32 v4, -16, v4
	v_add_u32_e32 v4, v7, v4
	v_lshlrev_b32_e32 v9, 7, v4
	v_lshl_add_u32 v130, v3, 1, v9
	s_movk_i32 s4, 0xf80
	v_mad_u64_u32 v[132:133], s[2:3], v4, s4, v[130:131]
	v_bfe_i32 v4, v1, 27, 1
	v_lshrrev_b32_e32 v4, 22, v4
	v_add_u32_e32 v4, v2, v4
	v_and_b32_e32 v4, 0xfffffc00, v4
	v_sub_u32_e32 v2, v2, v4
	v_lshrrev_b32_e32 v4, 4, v2
	v_bitop3_b32 v4, v4, v2, 32 bitop3:0x6c
	v_ashrrev_i32_e32 v2, 31, v2
	v_lshrrev_b32_e32 v2, 26, v2
	v_ashrrev_i32_e32 v3, 31, v1
	v_add_u32_e32 v2, v4, v2
	v_lshrrev_b32_e32 v3, 26, v3
	v_ashrrev_i32_e32 v10, 6, v2
	v_add_u32_e32 v3, v1, v3
	v_mul_i32_i24_e32 v2, 64, v10
	v_ashrrev_i32_e32 v9, 6, v3
	v_sub_u32_e32 v2, v4, v2
	v_lshlrev_b32_e32 v3, 5, v9
	v_ashrrev_i16_sdwa v2, v5, sext(v2) dst_sel:DWORD dst_unused:UNUSED_PAD src0_sel:DWORD src1_sel:BYTE_0
	v_and_b32_e32 v3, 32, v3
	v_bfe_i32 v11, v2, 0, 16
	v_add_u32_e32 v2, v3, v11
	v_lshlrev_b32_e32 v3, 3, v9
	v_and_b32_e32 v3, -16, v3
	v_add_u32_e32 v3, v10, v3
	v_lshlrev_b32_e32 v4, 7, v3
	v_lshl_add_u32 v134, v2, 1, v4
	s_add_u32 s1, s68, 0xa900000
	v_mad_u64_u32 v[136:137], s[2:3], v3, s4, v[134:135]
	s_addc_u32 s38, s69, 0
	s_lshr_b32 s2, s70, 30
	s_add_i32 s2, s70, s2
	s_ashr_i32 s22, s2, 2
	v_readlane_b32 s2, v252, 23
	s_sub_i32 s2, s2, s22
	s_lshl_b32 s2, s2, 2
	s_add_i32 s24, s2, s70
	s_ashr_i32 s8, s6, 6
	s_ashr_i32 s23, s22, 31
	s_ashr_i32 s25, s24, 31
	s_ashr_i32 s7, s6, 8
	s_lshl_b32 s39, s8, 10
	s_lshl_b64 s[2:3], s[22:23], 20
	s_lshl_b64 s[4:5], s[24:25], 20
	s_add_u32 s28, s1, s4
	s_addc_u32 s29, s38, s5
	s_add_i32 s25, s39, 0
	s_add_i32 m0, s25, 0x10000
	v_mov_b32_e32 v139, 0
	global_load_lds_dwordx4 v134, s[28:29]
	s_add_i32 m0, s25, 0x12000
	s_add_u32 s4, s28, 0x4000
	global_load_lds_dwordx4 v130, s[28:29]
	s_addc_u32 s5, s29, 0
	s_add_i32 m0, s25, 0x14000
	v_mov_b32_e32 v137, v139
	global_load_lds_dwordx4 v134, s[4:5]
	s_add_i32 m0, s25, 0x16000
	s_add_u32 s26, s76, s2
	s_addc_u32 s27, s33, s3
	s_add_i32 s40, s25, 0x2000
	global_load_lds_dwordx4 v130, s[4:5]
	s_mov_b32 m0, s25
	s_add_u32 s2, s26, 0x80000
	global_load_lds_dwordx4 v136, s[26:27]
	s_mov_b32 m0, s40
	s_addc_u32 s3, s27, 0
	s_add_i32 s41, s25, 0x4000
	global_load_lds_dwordx4 v132, s[26:27]
	s_mov_b32 m0, s41
	s_add_i32 s42, s25, 0x6000
	global_load_lds_dwordx4 v136, s[2:3]
	s_mov_b32 m0, s42
	v_mov_b32_e32 v133, v139
	global_load_lds_dwordx4 v132, s[2:3]
	s_cmp_eq_u32 s7, 1
	s_mov_b32 s43, 0
	v_mov_b32_e32 v135, v139
	v_mov_b32_e32 v131, v139
	s_mov_b64 s[4:5], 0x4000
	v_lshl_add_u64 v[2:3], s[26:27], 0, v[136:137]
	s_cselect_b64 s[2:3], -1, 0
	s_cmp_lg_u32 s7, 1
	v_lshl_add_u64 v[4:5], s[26:27], 0, v[132:133]
	s_cbranch_scc1 .LBB0_1836
	s_barrier

;     __host__ __device__ bool next(int r, Unit& u) const {
;         const int gidx = 4 * x + (i >> 3);
;         if (r == 0) { u.pm = gidx; u.pn = i & 7; u.k0 = 0; u.nt = ntf; u.part = 0; return true; }
;         if (r == 1) { const int part = gidx & 3; u.pm = 32 + (gidx >> 2); u.pn = i & 7; u.nt = ntf >> 2; u.k0 = part * (ntf >> 2) * BK; u.part = part; return true; }
;         return false;
;     }
; template <int L> __device__ __forceinline__ void do_layer(const Args& a, LAS unsigned char* lds, const XcdBarrier& bar, int G, int b) {
;     ...
;     { pg8::Gemm g{H, (const bf16_t*)(ws + WS_WF2) + (size_t)L * FF * D, FF, FF}; pg8::SplitOrder S; S.init(FF, b);
;       EpiRes E{Z, PS}; pg8::gemm_phase<EpiRes, pg8::SplitOrder, true>(lds, g, S, E); }
.LBB0_1900:
	s_or_b64 exec, exec, s[8:9]
	s_waitcnt vmcnt(0)
	buffer_inv sc1
	s_waitcnt vmcnt(0)
.LBB0_1901:
	s_or_b64 exec, exec, s[2:3]
	v_mov_b32_e32 v4, v0
	s_waitcnt lgkmcnt(0)
	s_barrier
	s_add_u32 s1, s68, 0x12900000
	v_bfe_i32 v3, v4, 27, 1
	v_lshlrev_b32_e32 v1, 4, v4
	v_lshrrev_b32_e32 v3, 22, v3
	v_add_u32_e32 v3, v1, v3
	v_and_b32_e32 v3, 0xfffffc00, v3
	v_sub_u32_e32 v3, v1, v3
	v_lshrrev_b32_e32 v5, 4, v3
	v_bitop3_b32 v5, v5, v3, 32 bitop3:0x6c
	v_ashrrev_i32_e32 v3, 31, v3
	v_lshrrev_b32_e32 v3, 26, v3
	v_ashrrev_i32_e32 v2, 31, v4
	v_add_u32_e32 v3, v5, v3
	v_lshrrev_b32_e32 v2, 26, v2
	v_ashrrev_i32_e32 v3, 6, v3
	v_add_u32_e32 v2, v4, v2
	v_mul_i32_i24_e32 v8, 64, v3
	v_ashrrev_i32_e32 v2, 6, v2
	v_sub_u32_e32 v5, v5, v8
	v_mov_b32_e32 v8, 1
	v_lshlrev_b32_e32 v6, 3, v2
	v_lshlrev_b32_e32 v7, 5, v2
	v_ashrrev_i16_sdwa v5, v8, sext(v5) dst_sel:DWORD dst_unused:UNUSED_PAD src0_sel:DWORD src1_sel:BYTE_0
	v_and_b32_e32 v6, 0x1fffff0, v6
	v_and_b32_e32 v7, 32, v7
	v_bfe_i32 v5, v5, 0, 16
	v_add_u32_e32 v7, v7, v5
	v_add_lshl_u32 v6, v3, v6, 7
	v_add_u32_e32 v1, 0x2000, v1
	v_lshl_add_u32 v130, v7, 1, v6
	v_ashrrev_i32_e32 v6, 31, v1
	v_lshrrev_b32_e32 v6, 22, v6
	v_add_u32_e32 v6, v1, v6
	v_ashrrev_i32_e32 v6, 10, v6
	v_mul_i32_i24_e32 v7, 0x400, v6
	v_sub_u32_e32 v1, v1, v7
	v_lshrrev_b32_e32 v7, 4, v1
	v_bitop3_b32 v1, v7, v1, 32 bitop3:0x6c
	v_lshlrev_b32_e32 v7, 3, v6
	v_and_b32_e32 v9, 0x1fffff0, v7
	v_ashrrev_i32_e32 v7, 31, v1
	v_readfirstlane_b32 s4, v4
	v_lshrrev_b32_e32 v7, 26, v7
	s_addc_u32 s33, s69, 0
	s_ashr_i32 s5, s4, 6
	v_add_u32_e32 v10, v1, v7
	v_ashrrev_i32_e32 v7, 6, v10
	v_and_b32_e32 v10, 0xc0, v10
	s_ashr_i32 s6, s4, 8
	s_lshl_b32 s40, s5, 10
	v_readlane_b32 s2, v252, 16
	v_sub_u32_e32 v1, v1, v10
	s_add_u32 s30, s1, s2
	v_lshlrev_b32_e32 v11, 5, v6
	v_ashrrev_i16_sdwa v1, v8, sext(v1) dst_sel:DWORD dst_unused:UNUSED_PAD src0_sel:DWORD src1_sel:BYTE_0
	s_addc_u32 s31, s33, 0
	s_add_i32 s41, s40, 0
	v_and_b32_e32 v11, 32, v11
	v_bfe_i32 v8, v1, 0, 16
	s_add_i32 m0, s41, 0x10000
	v_add_u32_e32 v1, v11, v8
	v_add_lshl_u32 v9, v7, v9, 7
	global_load_lds_dwordx4 v130, s[30:31]
	s_add_i32 m0, s41, 0x12000
	v_lshl_add_u32 v132, v1, 1, v9
	s_add_u32 s2, s30, 0x4000
	global_load_lds_dwordx4 v132, s[30:31]
	s_addc_u32 s3, s31, 0
	s_add_i32 m0, s41, 0x14000
	v_mov_b32_e32 v131, 0
	global_load_lds_dwordx4 v130, s[2:3]
	s_add_i32 m0, s41, 0x16000
	s_mov_b32 s47, 0
	global_load_lds_dwordx4 v132, s[2:3]
	v_readlane_b32 s2, v252, 17
	v_readlane_b32 s3, v252, 18
	s_add_u32 s34, s62, s2
	s_addc_u32 s35, s83, s3
	s_add_i32 s42, s41, 0x2000
	s_mov_b32 m0, s41
	s_add_u32 s2, s34, 0x4000
	global_load_lds_dwordx4 v130, s[34:35]
	s_mov_b32 m0, s42
	s_addc_u32 s3, s35, 0
	s_add_i32 s43, s41, 0x4000
	global_load_lds_dwordx4 v132, s[34:35]
	s_mov_b32 m0, s43
	s_add_i32 s44, s41, 0x6000
	global_load_lds_dwordx4 v130, s[2:3]
	s_mov_b32 m0, s44
	s_cmp_eq_u32 s6, 1
	global_load_lds_dwordx4 v132, s[2:3]
	s_cselect_b64 s[2:3], -1, 0
	s_cmp_lg_u32 s6, 1
	v_mov_b32_e32 v133, v131
	s_cbranch_scc1 .LBB0_1903
	s_barrier

; __device__ __forceinline__ void ph_ln(const Args& a, int L, int which, bool final_, bool split, bool wr_x, bool res_inputs, int nblk, int b) {
;     unsigned char* ws = a.ws; const bf16_t* P = (const bf16_t*)(ws + WS_SCR + SCR_PART);
;     const bf16_t* Z = (const bf16_t*)(ws + WS_Z); float* Xo = final_ ? a.out : (float*)(ws + WS_X); bf16_t* XB = (bf16_t*)(ws + WS_XB);
;     auto lo = [](unsigned w) -> float { return __builtin_bit_cast(float, w << 16); }; auto hi = [](unsigned w) -> float { return __builtin_bit_cast(float, w & 0xffff0000u); };
;     const float* gam = a.in[which ? 26 : 24] + (size_t)L * D; const float* bet = a.in[which ? 27 : 25] + (size_t)L * D;
;     const int tid = tid_fresh(); const int lane = tid & 63, gw = b * 8 + (tid >> 6), ngw = nblk * 8;
;     f32x4 gg[4][2], bb[4][2];
; #pragma unroll
;     for (int j = 0; j < 4; ++j)
; #pragma unroll
;         for (int h = 0; h < 2; ++h) { gg[j][h] = *(const f32x4*)(gam + 512 * j + 8 * lane + 4 * h); bb[j][h] = *(const f32x4*)(bet + 512 * j + 8 * lane + 4 * h); }
;     u32x4 zc[4], xc[4];
;     auto ldrow = [&](int r) { const u32x4* zr = (const u32x4*)(Z + (size_t)r * D) + lane;
; #pragma unroll
;         for (int j = 0; j < 4; ++j) zc[j] = zr[64 * j];
;         if (!res_inputs) { const u32x4* xr = (const u32x4*)(XB + (size_t)r * D) + lane;
; #pragma unroll
;             for (int j = 0; j < 4; ++j) xc[j] = xr[64 * j]; } };
;     if (gw < M) ldrow(gw);
;     for (int r = gw; r < M; r += ngw) {
;         float v[4][8];
; #pragma unroll
;         for (int j = 0; j < 4; ++j)
; #pragma unroll
;             for (int e = 0; e < 4; ++e) { v[j][2 * e] = lo(zc[j][e]); v[j][2 * e + 1] = hi(zc[j][e]); }
;         if (!res_inputs) {
; #pragma unroll
;             for (int j = 0; j < 4; ++j)
; #pragma unroll
;                 for (int e = 0; e < 4; ++e) { v[j][2 * e] += ALPHA * lo(xc[j][e]); v[j][2 * e + 1] += ALPHA * hi(xc[j][e]); } }
;         if (r + ngw < M) ldrow(r + ngw);
;         if (split && r >= MP) {
; #pragma unroll
;             for (int p = 0; p < 3; ++p) { const u32x4* pr = (const u32x4*)(P + ((size_t)p * MS + (r - MP)) * D) + lane;
; #pragma unroll
;                 for (int j = 0; j < 4; ++j) { const u32x4 w = pr[64 * j];
; #pragma unroll
;                     for (int e = 0; e < 4; ++e) { v[j][2 * e] += lo(w[e]); v[j][2 * e + 1] += hi(w[e]); } } } }
.LBB0_1964:
	s_or_b64 exec, exec, s[8:9]
	s_waitcnt vmcnt(0)
	buffer_inv sc1
	s_waitcnt vmcnt(0)
.LBB0_1965:
	s_or_b64 exec, exec, s[2:3]
	s_waitcnt lgkmcnt(0)
	v_mov_b32_e32 v1, v0
	s_barrier
	s_movk_i32 s1, 0x2800
	v_ashrrev_i32_e32 v66, 6, v1
	v_add_u32_e32 v156, s94, v66
	v_cmp_gt_i32_e32 vcc, s1, v156
	s_and_saveexec_b64 s[2:3], vcc
	s_cbranch_execz .LBB0_1972
	s_load_dwordx4 s[4:7], s[86:87], 0xd0
	v_and_b32_e32 v1, 63, v1
	v_mov_b32_e32 v131, 0
	v_lshlrev_b32_e32 v130, 5, v1
	s_mov_b64 s[8:9], 0x5800
	s_waitcnt lgkmcnt(0)
	v_lshl_add_u64 v[42:43], s[6:7], 0, v[130:131]
	v_add_co_u32_e32 v14, vcc, 0x5000, v42
	v_lshl_add_u64 v[56:57], s[4:5], 0, v[130:131]
	s_nop 0
	v_addc_co_u32_e32 v15, vcc, 0, v43, vcc
	v_add_co_u32_e32 v48, vcc, 0x5000, v56
	s_mov_b64 s[4:5], 0x5000
	s_nop 0
	v_addc_co_u32_e32 v49, vcc, 0, v57, vcc
	v_lshl_add_u64 v[16:17], v[42:43], 0, s[4:5]
	v_lshl_add_u64 v[50:51], v[56:57], 0, s[4:5]
	s_movk_i32 s4, 0x4000
	s_mov_b64 s[6:7], 0x4000
	v_add_co_u32_e32 v58, vcc, s4, v42
	v_lshl_add_u64 v[54:55], v[42:43], 0, s[6:7]
	v_lshl_add_u64 v[44:45], v[42:43], 0, s[8:9]
	v_lshl_add_u64 v[46:47], v[56:57], 0, s[8:9]
	v_addc_co_u32_e32 v59, vcc, 0, v43, vcc
	v_ashrrev_i32_e32 v157, 31, v156
	v_lshl_add_u64 v[68:69], v[56:57], 0, s[6:7]
	global_load_dwordx4 v[2:5], v[14:15], off offset:2048
	global_load_dwordx4 v[6:9], v[14:15], off
	global_load_dwordx4 v[10:13], v[16:17], off offset:16
	s_nop 0
	global_load_dwordx4 v[14:17], v[48:49], off offset:2048
	global_load_dwordx4 v[18:21], v[48:49], off
	global_load_dwordx4 v[22:25], v[50:51], off offset:16
	global_load_dwordx4 v[26:29], v[44:45], off offset:16
	global_load_dwordx4 v[30:33], v[54:55], off offset:2064
	global_load_dwordx4 v[34:37], v[46:47], off offset:16
	global_load_dwordx4 v[38:41], v[68:69], off offset:2064
	s_nop 0
	global_load_dwordx4 v[42:45], v[58:59], off
	global_load_dwordx4 v[46:49], v[54:55], off offset:2048
	global_load_dwordx4 v[50:53], v[54:55], off offset:16
	v_lshlrev_b64 v[54:55], 12, v[156:157]
	v_lshlrev_b32_e32 v72, 4, v1
	v_mov_b32_e32 v73, v131
	v_lshl_add_u64 v[54:55], s[68:69], 0, v[54:55]
	v_add_co_u32_e32 v70, vcc, s4, v56
	v_lshl_add_u64 v[54:55], v[54:55], 0, v[72:73]
	s_mov_b64 s[4:5], 0x1e100000
	v_addc_co_u32_e32 v71, vcc, 0, v57, vcc
	v_lshl_add_u64 v[56:57], v[54:55], 0, s[4:5]
	s_mov_b32 s4, 0x1e100000
	v_add_co_u32_e32 v58, vcc, s4, v54
	s_mov_b64 s[4:5], 0x1b900000
	s_nop 0
	v_addc_co_u32_e32 v59, vcc, 0, v55, vcc
	global_load_dwordx4 v[114:117], v[56:57], off offset:1024
	global_load_dwordx4 v[106:109], v[56:57], off offset:2048
	global_load_dwordx4 v[122:125], v[58:59], off
	global_load_dwordx4 v[98:101], v[56:57], off offset:3072
	v_lshl_add_u64 v[74:75], v[54:55], 0, s[4:5]
	s_mov_b32 s4, 0x1b900000
	v_add_co_u32_e32 v76, vcc, s4, v54
	s_mov_b64 s[4:5], 0x3c900000
	s_nop 0
	v_addc_co_u32_e32 v77, vcc, 0, v55, vcc
	global_load_dwordx4 v[126:129], v[76:77], off
	global_load_dwordx4 v[102:105], v[74:75], off offset:3072
	global_load_dwordx4 v[118:121], v[74:75], off offset:1024
	global_load_dwordx4 v[110:113], v[74:75], off offset:2048
	global_load_dwordx4 v[54:57], v[70:71], off
	global_load_dwordx4 v[58:61], v[68:69], off offset:2048
	global_load_dwordx4 v[62:65], v[68:69], off offset:16
	v_lshl_add_u64 v[68:69], s[68:69], 0, v[72:73]
	v_ashrrev_i32_e32 v67, 31, v66
	s_ashr_i32 s95, s94, 31
	v_lshl_add_u64 v[132:133], v[68:69], 0, s[4:5]
	v_lshl_add_u64 v[66:67], v[66:67], 0, s[94:95]
	v_add_u32_e32 v68, s74, v156
	v_lshlrev_b64 v[134:135], 13, v[66:67]
	v_ashrrev_i32_e32 v69, 31, v68
	v_lshlrev_b64 v[66:67], 12, v[66:67]
	v_lshlrev_b64 v[136:137], 12, v[68:69]
	v_or_b32_e32 v66, v66, v72
	s_mov_b64 s[4:5], 0x1b900800
	s_ashr_i32 s75, s74, 31
	v_or_b32_e32 v136, v136, v72
	v_lshl_add_u64 v[138:139], v[66:67], 0, s[4:5]
	v_or_b32_e32 v134, v134, v130
	s_lshl_b64 s[6:7], s[74:75], 13
	s_lshl_b64 s[10:11], s[74:75], 12
	s_mov_b64 s[12:13], 0
	s_movk_i32 s15, 0x27ff
	s_mov_b32 s14, 0x3fd744fd
	s_movk_i32 s16, 0x1fff
	s_mov_b32 s17, 0x800000
	s_mov_b32 s18, 0x1000000
	v_mov_b32_e32 v1, 0x3727c5ac
	s_mov_b32 s19, 0xf800000
	v_mov_b32_e32 v157, 0x260
	s_mov_b32 s20, 0x16900000
	s_mov_b32 s21, 0x16901000
	s_waitcnt vmcnt(10)
	v_mov_b64_e32 v[74:75], v[114:115]
	s_waitcnt vmcnt(9)
	v_mov_b64_e32 v[70:71], v[106:107]
	s_waitcnt vmcnt(8)
	v_mov_b64_e32 v[78:79], v[122:123]
	s_waitcnt vmcnt(7)
	v_mov_b64_e32 v[66:67], v[98:99]
	v_mov_b64_e32 v[68:69], v[100:101]
	s_waitcnt vmcnt(6)
	v_mov_b64_e32 v[94:95], v[126:127]
	s_waitcnt vmcnt(5)
	v_mov_b64_e32 v[82:83], v[102:103]
	s_waitcnt vmcnt(4)
	v_mov_b64_e32 v[90:91], v[118:119]
	s_waitcnt vmcnt(3)
	v_mov_b64_e32 v[86:87], v[110:111]
	v_mov_b64_e32 v[72:73], v[108:109]
	v_mov_b64_e32 v[76:77], v[116:117]
	v_mov_b64_e32 v[80:81], v[124:125]
	v_mov_b64_e32 v[84:85], v[104:105]
	v_mov_b64_e32 v[88:89], v[112:113]
	v_mov_b64_e32 v[92:93], v[120:121]
	v_mov_b64_e32 v[96:97], v[128:129]
	s_branch .LBB0_1968

; #define LAS __attribute__((address_space(3)))
; template <bool FULL>
; __device__ __forceinline__ void ssm_core(const Args& a, LAS unsigned char* wl, int j, int L, bool samp, int n, int g, int tb, int te, float& hr, float& hi, int lane) {
;     unsigned char* ws = a.ws;
;     const size_t rowbase = samp ? (size_t)MP + (size_t)n * DSEQ : (size_t)n * SEQ;
;     const float* xbase = (L == 0) ? (samp ? a.in[1] + (size_t)n * DSEQ * D : a.in[0] + rowbase * D) : (const float*)(ws + WS_X) + rowbase * D;
;     const int G4 = lane >> 4, c = lane & 15;
;     const bf16x8* bfp = (const bf16x8*)(ws + WS_PAR + PAR_BFRAG) + (size_t)(j * NG + g) * 8 * 64 + lane;
;     const bf16x8* cfp = (const bf16x8*)(ws + WS_PAR + PAR_CFRAG) + (size_t)(j * NG + g) * 4 * 64 + lane;
;     bf16x8 Bf[8], Cf[4];
; #pragma unroll
;     for (int i = 0; i < 8; ++i) Bf[i] = bfp[i * 64];
;     if (FULL) {
; #pragma unroll
;         for (int i = 0; i < 4; ++i) Cf[i] = cfp[i * 64]; }
;     const float* ab = (const float*)(ws + WS_PAR + PAR_ABAR) + ((size_t)(j * NG + g) * NP + lane) * 2; const float ar = ab[0], ai = ab[1];
;     const float dsk = a.in[14][(size_t)j * D + g * NQ + c];
;     LAS float* BUs = (LAS float*)wl; LAS float* Us = (LAS float*)(wl + 16 * SSM_BUS * 4);
;     bf16_t* Y = (bf16_t*)(ws + WS_Y);
;     const float* up = xbase + (size_t)c * D + g * NQ + 8 * (G4 & 1);
; template <bool CONV> __device__ __forceinline__ void ph_ssm(const Args& a, LAS unsigned char* lds, int j, int L, int nblk, int b) {
;     const int tid = tid_fresh(); const int wave = __builtin_amdgcn_readfirstlane(tid >> 6), lane = tid & 63;
;     LAS unsigned char* wl = CONV ? (wave < 2 ? lds + wave * SSM_WLDS : lds + 2 * SSM_WLDS + (wave - 2) * CONV_LDS) : lds + wave * SSM_WLDS;
;     if (wave < 2) { for (int it = b * 2 + wave; it < NB * NG; it += nblk * 2) ssm_item(a, wl, j, L, false, it / NG, it % NG, lane); }
;     else { for (int it = b * 6 + (wave - 2); it < DB * NG; it += nblk * 6) ssm_item(a, wl, j, L, true, it / NG, it % NG, lane);
;         if (CONV && (wave & 2)) conv_worker(a, (LAS float*)wl, b * 4 + (wave & 1) + ((wave >> 2) << 1), nblk * 4, lane); }
; template <int L> __device__ __forceinline__ void do_layer(const Args& a, LAS unsigned char* lds, const XcdBarrier& bar, int G, int b) {
;     ...
;         if (L == 0 || G != 256) ph_ssm<L == 0>(a, lds, j, L, G, b); else ph_ssm_split(a, lds, j, L, b);
.LBB0_2023:
	s_or_b64 exec, exec, s[8:9]
	s_waitcnt vmcnt(0)
	buffer_inv sc1
	s_waitcnt vmcnt(0)
.LBB0_2024:
	s_or_b64 exec, exec, s[2:3]
	s_cmpk_eq_i32 s89, 0x100
	s_mov_b64 s[2:3], -1
	s_waitcnt lgkmcnt(0)
	s_barrier
	s_cbranch_scc1 .LBB0_2044
	v_mov_b32_e32 v65, v0
	s_nop 0
	v_readfirstlane_b32 s1, v65
	s_ashr_i32 s1, s1, 6
	s_mul_i32 s30, s1, 0x3100
	s_add_i32 s31, s30, 0
	v_and_b32_e32 v94, 63, v65
	s_cmp_gt_i32 s1, 1
	s_cbranch_scc0 .LBB0_2032
	s_mul_i32 s2, s56, 6
	s_add_i32 s2, s2, s1
	s_add_i32 s33, s2, -2
	s_cmpk_gt_i32 s33, 0xfff
	s_cbranch_scc1 .LBB0_2031
	v_mov_b32_e32 v63, 0
	v_lshrrev_b32_e32 v1, 1, v94
	v_readlane_b32 s16, v252, 19
	v_and_b32_e32 v64, 15, v65
	v_and_b32_e32 v4, 8, v1
	v_mov_b32_e32 v1, s31
	s_movk_i32 s2, 0x210
	v_lshlrev_b32_e32 v8, 4, v94
	v_mov_b32_e32 v9, v63
	v_readlane_b32 s18, v252, 21
	v_readlane_b32 s19, v252, 22
	v_mad_u32_u24 v14, v64, s2, v1
	s_mov_b64 s[2:3], 0x2fb22000
	v_lshl_add_u64 v[8:9], s[18:19], 0, v[8:9]
	v_lshl_add_u64 v[66:67], v[8:9], 0, s[2:3]
	s_mov_b64 s[2:3], 0x2fd22000
	v_lshl_add_u64 v[68:69], v[8:9], 0, s[2:3]
	s_load_dwordx4 s[12:15], s[86:87], 0x10
	s_load_dwordx2 s[2:3], s[86:87], 0x70
	v_lshlrev_b32_e32 v6, 2, v64
	v_mov_b32_e32 v7, v63
	v_lshlrev_b32_e32 v2, 13, v64
	v_mov_b32_e32 v3, v63
	v_add_u32_e32 v12, s31, v6
	s_waitcnt lgkmcnt(0)
	v_lshl_add_u64 v[6:7], s[2:3], 0, v[6:7]
	s_mov_b64 s[2:3], 0x2000
	v_lshrrev_b32_e32 v5, 4, v94
	v_mul_u32_u24_e32 v13, 0x210, v64
	v_mul_i32_i24_e32 v16, 0xfffffdf4, v64
	v_lshl_add_u64 v[72:73], v[6:7], 0, s[2:3]
	v_lshl_add_u64 v[2:3], s[18:19], 0, v[2:3]
	s_mov_b64 s[2:3], 0x16900000
	v_lshl_add_u64 v[74:75], v[2:3], 0, s[2:3]
	v_add3_u32 v2, v13, v16, s30
	v_lshlrev_b32_e32 v3, 8, v5
	v_lshlrev_b32_e32 v11, 6, v64
	v_lshlrev_b32_e32 v15, 5, v5
	v_add3_u32 v2, v2, v3, 0
	v_add_u32_e32 v90, 0x2100, v2
	v_add_u32_e32 v2, s30, v11
	v_and_b32_e32 v3, 32, v15
	v_readlane_b32 s17, v252, 20
	s_add_u32 s2, s16, 0x7480000
	v_add3_u32 v2, v2, v3, 0
	v_lshlrev_b32_e32 v62, 3, v94
	s_addc_u32 s3, s17, 0
	v_add_u32_e32 v91, 0x2100, v2
	v_lshlrev_b32_e32 v2, 10, v65
	v_lshl_add_u32 v10, v4, 2, s31
	v_mul_u32_u24_e32 v17, 0x840, v5
	v_lshl_add_u64 v[8:9], s[18:19], 0, v[62:63]
	s_mov_b64 s[4:5], 0x2f900000
	s_add_u32 s6, s16, 0x7680000
	s_mov_b32 s11, 0
	v_and_b32_e32 v62, 0xc000, v2
	v_cmp_gt_u32_e32 vcc, 32, v94
	v_lshl_add_u32 v1, v94, 2, s31
	s_mul_i32 s34, s89, 6
	v_lshl_add_u64 v[70:71], v[8:9], 0, s[4:5]
	s_addc_u32 s7, s17, 0
	v_lshl_add_u64 v[76:77], s[18:19], 0, v[62:63]
	s_movk_i32 s35, 0x1000
	v_lshlrev_b32_e32 v62, 2, v4
	s_mov_b64 s[20:21], 0x4000000
	s_mov_b64 s[22:23], 0x4060000
	s_mov_b32 s36, 0x4060000
	s_mov_b64 s[24:25], 0x4040000
	s_mov_b32 s37, 0x4040000
	s_mov_b64 s[26:27], 0x4020000
	s_mov_b32 s38, 0x4020000
	s_brev_b32 s39, 32
	v_add_u32_e32 v92, v10, v11
	s_mov_b32 s16, s11
	s_mov_b32 s17, s11
	s_mov_b32 s18, s11
	s_mov_b32 s19, s11
	v_add_u32_e32 v93, v12, v17
	v_add_u32_e32 v95, v14, v15
	s_movk_i32 s40, 0x7fff
	s_mov_b32 s41, 0x2f101000
	s_mov_b32 s42, 0x2f103000

; template <class Epi, class Sched, bool ABLK = false, bool ALIGN_EPI = true, bool SP2 = true, bool BBLK = true>
; __device__ __forceinline__ void gemm_phase(LAS unsigned char* lds, const Gemm g, const Sched& S, const Epi& E) {
;     const int tid = tid_fresh(), wid = __builtin_amdgcn_readfirstlane(tid >> 6), lane = tid & 63, wr = wid >> 2, wc = wid & 3, fr = lane & 15, fq = lane >> 4;
;     unsigned voffA[2], voffB[2];
; #pragma unroll
;     for (int i = 0; i < 2; ++i) { int R, C; stage_rc(tid * 16 + i * 8192, R, C); const int r32 = Epi::PERM ? perm32(R & 31) : (R & 31);
;         const int Rb = Epi::ADJ ? 64 * (R >> 5) + r32 : (R & ~31) + r32;
;         voffA[i] = (unsigned)(R * (ABLK ? 64 : g.lda) + C) * 2u; voffB[i] = BBLK ? (unsigned)(R * 64 + C) * 2u : (unsigned)(Rb * g.ldb + C) * 2u; }
;     const size_t kstep = (size_t)(BK * 2);
;     const size_t hstepA = (size_t)HALF * (ABLK ? 64 : g.lda) * 2, hstepB = BBLK ? (size_t)16384 : (size_t)(Epi::ADJ ? 32 : HALF) * g.ldb * 2;
;     const size_t tstepB = BBLK ? ((size_t)g.ldb / 64) * 32768 : (size_t)BM * g.ldb * 2;
;     const size_t kstepB = BBLK ? (size_t)32768 : kstep;
;     auto b_k0 = [&](int k0) -> size_t { return BBLK ? (size_t)(k0 / BK) * 32768 : (size_t)k0 * 2; };
;     const unsigned ldsw = (unsigned)wid * 1024u;
;     const int aoff = lds_byte(wr * 64 + fr, fq * 8), boff = lds_byte(wc * 32 + fr, fq * 8);
;     ...
;     Unit cur, nxt; int ui = 0;
;     if (!S.next(0, cur)) return;
;     f32x4 acc[2][2][4][2];
; #pragma unroll
;     for (int a = 0; a < 2; ++a)
; #pragma unroll
;         for (int b = 0; b < 2; ++b)
; #pragma unroll
;             for (int m = 0; m < 4; ++m)
; #pragma unroll
;                 for (int n = 0; n < 2; ++n) acc[a][b][m][n] = (f32x4){0.f, 0.f, 0.f, 0.f};
;     bf16x8 At[4][2], B0[2][2], B1[2][2];
;     auto a_unit = [&](const Unit& u) -> const char* { return ABLK ? (const char*)g.A + (size_t)u.pm * ((size_t)g.lda / 64) * 32768 : (const char*)g.A + (size_t)u.pm * 2 * hstepA; };
; template <int L> __device__ __forceinline__ void do_layer(const Args& a, LAS unsigned char* lds, const XcdBarrier& bar, int G, int b) {
;     ...
;         pg8::Gemm g{Y, (const bf16_t*)(ws + WS_WSSM) + (size_t)j * 4096 * D, D, D}; pg8::BStatOrder S; S.init(M, 4096, D, b);
;         EpiSsmGate E{Z}; pg8::gemm_phase<EpiSsmGate, pg8::BStatOrder>(lds, g, S, E);
.LBB0_2128:
	s_or_b64 exec, exec, s[8:9]
	s_waitcnt vmcnt(0)
	buffer_inv sc1
	s_waitcnt vmcnt(0)
.LBB0_2129:
	s_or_b64 exec, exec, s[2:3]
	v_readlane_b32 s2, v252, 12
	s_add_u32 s8, s68, 0x1e100000
	v_mov_b32_e32 v6, v0
	v_readlane_b32 s3, v252, 13
	s_addc_u32 s9, s69, 0
	s_waitcnt lgkmcnt(0)
	s_barrier
	s_andn2_b64 vcc, exec, s[2:3]
	v_readfirstlane_b32 s4, v6
	s_cbranch_vccnz .LBB0_2145
	v_lshlrev_b32_e32 v1, 4, v6
	v_add_u32_e32 v2, 0x2000, v1
	v_ashrrev_i32_e32 v3, 31, v2
	v_lshrrev_b32_e32 v3, 22, v3
	v_add_u32_e32 v3, v2, v3
	v_ashrrev_i32_e32 v7, 10, v3
	v_mul_i32_i24_e32 v4, 0x400, v7
	v_sub_u32_e32 v2, v2, v4
	v_lshrrev_b32_e32 v4, 4, v2
	v_bitop3_b32 v2, v4, v2, 32 bitop3:0x6c
	v_ashrrev_i32_e32 v4, 31, v2
	v_lshrrev_b32_e32 v4, 26, v4
	v_add_u32_e32 v4, v2, v4
	v_ashrrev_i32_e32 v8, 6, v4
	v_and_b32_e32 v4, 0xc0, v4
	v_sub_u32_e32 v2, v2, v4
	v_mov_b32_e32 v4, 1
	v_lshlrev_b32_e32 v3, 5, v7
	v_ashrrev_i16_sdwa v2, v4, sext(v2) dst_sel:DWORD dst_unused:UNUSED_PAD src0_sel:DWORD src1_sel:BYTE_0
	v_and_b32_e32 v3, 32, v3
	v_bfe_i32 v9, v2, 0, 16
	v_add_u32_e32 v2, v3, v9
	v_lshlrev_b32_e32 v3, 3, v7
	v_and_b32_e32 v3, -16, v3
	v_add_u32_e32 v3, v8, v3
	v_lshlrev_b32_e32 v5, 7, v3
	v_lshl_add_u32 v130, v2, 1, v5
	s_movk_i32 s7, 0xf80
	v_mad_u64_u32 v[132:133], s[2:3], v3, s7, v[130:131]
	v_bfe_i32 v3, v6, 27, 1
	v_lshrrev_b32_e32 v3, 22, v3
	v_add_u32_e32 v3, v1, v3
	v_and_b32_e32 v3, 0xfffffc00, v3
	v_sub_u32_e32 v1, v1, v3
	v_lshrrev_b32_e32 v3, 4, v1
	v_bitop3_b32 v3, v3, v1, 32 bitop3:0x6c
	v_ashrrev_i32_e32 v1, 31, v1
	v_lshrrev_b32_e32 v1, 26, v1
	v_ashrrev_i32_e32 v2, 31, v6
	v_add_u32_e32 v1, v3, v1
	v_lshrrev_b32_e32 v2, 26, v2
	v_ashrrev_i32_e32 v11, 6, v1
	v_add_u32_e32 v2, v6, v2
	v_mul_i32_i24_e32 v1, 64, v11
	v_ashrrev_i32_e32 v10, 6, v2
	v_sub_u32_e32 v1, v3, v1
	v_lshlrev_b32_e32 v2, 5, v10
	v_ashrrev_i16_sdwa v1, v4, sext(v1) dst_sel:DWORD dst_unused:UNUSED_PAD src0_sel:DWORD src1_sel:BYTE_0
	v_and_b32_e32 v2, 32, v2
	v_bfe_i32 v12, v1, 0, 16
	v_add_u32_e32 v1, v2, v12
	v_lshlrev_b32_e32 v2, 3, v10
	v_and_b32_e32 v2, -16, v2
	s_add_u32 s1, s68, 0x1100000
	v_add_u32_e32 v2, v11, v2
	s_addc_u32 s33, s69, 0
	s_ashr_i32 s6, s4, 6
	v_lshlrev_b32_e32 v3, 7, v2
	s_ashr_i32 s5, s4, 8
	s_lshl_b32 s36, s6, 10
	v_lshl_add_u32 v134, v1, 1, v3
	s_add_u32 s37, s68, 0x2d100000
	v_mad_u64_u32 v[136:137], s[2:3], v2, s7, v[134:135]
	s_addc_u32 s38, s69, 0
	s_lshr_b32 s2, s70, 31
	s_add_i32 s2, s70, s2
	s_ashr_i32 s20, s2, 1
	s_sub_i32 s2, s63, s20
	s_lshl_b32 s2, s2, 1
	s_add_i32 s22, s2, s70
	s_ashr_i32 s21, s20, 31
	s_ashr_i32 s23, s22, 31
	s_lshl_b64 s[2:3], s[20:21], 20
	s_lshl_b64 s[10:11], s[22:23], 20
	s_add_u32 s26, s1, s10
	s_addc_u32 s27, s33, s11
	s_add_i32 s21, s36, 0
	s_add_i32 m0, s21, 0x10000
	v_mov_b32_e32 v135, 0
	global_load_lds_dwordx4 v134, s[26:27]
	s_add_i32 m0, s21, 0x12000
	s_add_u32 s10, s26, 0x4000
	global_load_lds_dwordx4 v130, s[26:27]
	s_addc_u32 s11, s27, 0
	s_add_i32 m0, s21, 0x14000
	v_mov_b32_e32 v137, v135
	global_load_lds_dwordx4 v134, s[10:11]
	s_add_i32 m0, s21, 0x16000
	s_add_u32 s24, s37, s2
	s_addc_u32 s25, s38, s3
	s_add_i32 s23, s21, 0x2000
	global_load_lds_dwordx4 v130, s[10:11]
	s_mov_b32 m0, s21
	s_add_u32 s2, s24, 0x80000
	global_load_lds_dwordx4 v136, s[24:25]
	s_mov_b32 m0, s23
	s_addc_u32 s3, s25, 0
	s_add_i32 s39, s21, 0x4000
	global_load_lds_dwordx4 v132, s[24:25]
	s_mov_b32 m0, s39
	s_add_i32 s40, s21, 0x6000
	global_load_lds_dwordx4 v136, s[2:3]
	s_mov_b32 m0, s40
	v_mov_b32_e32 v133, v135
	global_load_lds_dwordx4 v132, s[2:3]
	s_cmp_eq_u32 s5, 1
	s_mov_b32 s41, 0
	v_mov_b32_e32 v131, v135
	v_lshl_add_u64 v[2:3], s[24:25], 0, v[136:137]
	s_cselect_b64 s[2:3], -1, 0
	s_cmp_lg_u32 s5, 1
	v_lshl_add_u64 v[4:5], s[24:25], 0, v[132:133]
	s_cbranch_scc1 .LBB0_2132
	s_barrier

; __device__ __forceinline__ int tid_fresh() { int t = threadIdx.x; asm volatile("" : "+v"(t)); return t; }
; __device__ __forceinline__ void ph_ln(const Args& a, int L, int which, bool final_, bool split, bool wr_x, bool res_inputs, int nblk, int b) {
;     unsigned char* ws = a.ws; const bf16_t* P = (const bf16_t*)(ws + WS_SCR + SCR_PART);
;     const bf16_t* Z = (const bf16_t*)(ws + WS_Z); float* Xo = final_ ? a.out : (float*)(ws + WS_X); bf16_t* XB = (bf16_t*)(ws + WS_XB);
;     auto lo = [](unsigned w) -> float { return __builtin_bit_cast(float, w << 16); }; auto hi = [](unsigned w) -> float { return __builtin_bit_cast(float, w & 0xffff0000u); };
;     const float* gam = a.in[which ? 26 : 24] + (size_t)L * D; const float* bet = a.in[which ? 27 : 25] + (size_t)L * D;
;     const int tid = tid_fresh(); const int lane = tid & 63, gw = b * 8 + (tid >> 6), ngw = nblk * 8;
;     f32x4 gg[4][2], bb[4][2];
; #pragma unroll
;     for (int j = 0; j < 4; ++j)
; #pragma unroll
;         for (int h = 0; h < 2; ++h) { gg[j][h] = *(const f32x4*)(gam + 512 * j + 8 * lane + 4 * h); bb[j][h] = *(const f32x4*)(bet + 512 * j + 8 * lane + 4 * h); }
;     u32x4 zc[4], xc[4];
;     auto ldrow = [&](int r) { const u32x4* zr = (const u32x4*)(Z + (size_t)r * D) + lane;
; #pragma unroll
;         for (int j = 0; j < 4; ++j) zc[j] = zr[64 * j];
;         if (!res_inputs) { const u32x4* xr = (const u32x4*)(XB + (size_t)r * D) + lane;
; #pragma unroll
;             for (int j = 0; j < 4; ++j) xc[j] = xr[64 * j]; } };
;     if (gw < M) ldrow(gw);
;     for (int r = gw; r < M; r += ngw) {
;         float v[4][8];
; #pragma unroll
;         for (int j = 0; j < 4; ++j)
; #pragma unroll
;             for (int e = 0; e < 4; ++e) { v[j][2 * e] = lo(zc[j][e]); v[j][2 * e + 1] = hi(zc[j][e]); }
;         if (!res_inputs) {
; #pragma unroll
;             for (int j = 0; j < 4; ++j)
; #pragma unroll
;                 for (int e = 0; e < 4; ++e) { v[j][2 * e] += ALPHA * lo(xc[j][e]); v[j][2 * e + 1] += ALPHA * hi(xc[j][e]); } }
;         if (r + ngw < M) ldrow(r + ngw);
.LBB0_2194:
	s_or_b64 exec, exec, s[4:5]
	s_mov_b64 s[4:5], exec
	v_mbcnt_lo_u32_b32 v1, s4, 0
	v_mbcnt_hi_u32_b32 v1, s5, v1
	v_cmp_eq_u32_e32 vcc, 0, v1
	s_and_saveexec_b64 s[10:11], vcc
	s_cbranch_execz .LBB0_2196
	s_bcnt1_i32_b64 s1, s[4:5]
	v_mov_b32_e32 v1, 0x2000
	v_mov_b32_e32 v2, s1
	global_atomic_add v1, v2, s[6:7] offset:1024
.LBB0_2196:
	s_or_b64 exec, exec, s[10:11]
	s_waitcnt vmcnt(0)
	buffer_inv sc1
	s_waitcnt vmcnt(0)
.LBB0_2197:
	s_or_b64 exec, exec, s[2:3]
	s_waitcnt lgkmcnt(0)
	v_mov_b32_e32 v1, v0
	s_barrier
	s_movk_i32 s1, 0x2800
	v_ashrrev_i32_e32 v66, 6, v1
	v_add_u32_e32 v130, s94, v66
	v_cmp_gt_i32_e32 vcc, s1, v130
	s_and_saveexec_b64 s[6:7], vcc
	s_cbranch_execz .LBB0_2202
	s_load_dwordx4 s[12:15], s[86:87], 0xc0
	v_and_b32_e32 v1, 63, v1
	v_mov_b32_e32 v133, 0
	v_lshlrev_b32_e32 v132, 5, v1
	s_mov_b64 s[2:3], 0x6000
	s_waitcnt lgkmcnt(0)
	v_lshl_add_u64 v[42:43], s[14:15], 0, v[132:133]
	v_add_co_u32_e32 v14, vcc, 0x7000, v42
	v_lshl_add_u64 v[56:57], s[12:13], 0, v[132:133]
	s_nop 0
	v_addc_co_u32_e32 v15, vcc, 0, v43, vcc
	v_lshl_add_u64 v[54:55], v[42:43], 0, s[2:3]
	v_lshl_add_u64 v[68:69], v[56:57], 0, s[2:3]
	v_add_co_u32_e32 v48, vcc, 0x7000, v56
	s_mov_b64 s[2:3], 0x7000
	s_nop 0
	v_addc_co_u32_e32 v49, vcc, 0, v57, vcc
	v_lshl_add_u64 v[16:17], v[42:43], 0, s[2:3]
	v_lshl_add_u64 v[50:51], v[56:57], 0, s[2:3]
	s_movk_i32 s2, 0x6000
	s_mov_b64 s[4:5], 0x7800
	v_add_co_u32_e32 v58, vcc, s2, v42
	v_lshl_add_u64 v[44:45], v[42:43], 0, s[4:5]
	v_lshl_add_u64 v[46:47], v[56:57], 0, s[4:5]
	v_addc_co_u32_e32 v59, vcc, 0, v43, vcc
	v_ashrrev_i32_e32 v131, 31, v130
	global_load_dwordx4 v[2:5], v[14:15], off offset:2048
	global_load_dwordx4 v[6:9], v[14:15], off
	global_load_dwordx4 v[10:13], v[16:17], off offset:16
	s_nop 0
	global_load_dwordx4 v[14:17], v[48:49], off offset:2048
	global_load_dwordx4 v[18:21], v[48:49], off
	global_load_dwordx4 v[22:25], v[50:51], off offset:16
	global_load_dwordx4 v[26:29], v[44:45], off offset:16
	global_load_dwordx4 v[30:33], v[54:55], off offset:2064
	global_load_dwordx4 v[34:37], v[46:47], off offset:16
	global_load_dwordx4 v[38:41], v[68:69], off offset:2064
	s_nop 0
	global_load_dwordx4 v[42:45], v[58:59], off
	global_load_dwordx4 v[46:49], v[54:55], off offset:2048
	global_load_dwordx4 v[50:53], v[54:55], off offset:16
	v_lshlrev_b64 v[54:55], 12, v[130:131]
	v_lshlrev_b32_e32 v134, 4, v1
	v_mov_b32_e32 v135, v133
	v_lshl_add_u64 v[54:55], s[68:69], 0, v[54:55]
	v_add_co_u32_e32 v70, vcc, s2, v56
	v_lshl_add_u64 v[54:55], v[54:55], 0, v[134:135]
	s_mov_b64 s[2:3], 0x1e100000
	v_addc_co_u32_e32 v71, vcc, 0, v57, vcc
	v_lshl_add_u64 v[56:57], v[54:55], 0, s[2:3]
	s_mov_b32 s2, 0x1e100000
	v_add_co_u32_e32 v58, vcc, s2, v54
	s_mov_b64 s[2:3], 0x1b900000
	s_nop 0
	v_addc_co_u32_e32 v59, vcc, 0, v55, vcc
	global_load_dwordx4 v[114:117], v[56:57], off offset:1024
	global_load_dwordx4 v[106:109], v[56:57], off offset:2048
	global_load_dwordx4 v[122:125], v[58:59], off
	global_load_dwordx4 v[98:101], v[56:57], off offset:3072
	v_lshl_add_u64 v[72:73], v[54:55], 0, s[2:3]
	s_mov_b32 s2, 0x1b900000
	v_add_co_u32_e32 v74, vcc, s2, v54
	v_ashrrev_i32_e32 v67, 31, v66
	s_nop 0
	v_addc_co_u32_e32 v75, vcc, 0, v55, vcc
	global_load_dwordx4 v[126:129], v[74:75], off
	global_load_dwordx4 v[102:105], v[72:73], off offset:3072
	global_load_dwordx4 v[118:121], v[72:73], off offset:1024
	global_load_dwordx4 v[110:113], v[72:73], off offset:2048
	global_load_dwordx4 v[54:57], v[70:71], off
	global_load_dwordx4 v[58:61], v[68:69], off offset:2048
	global_load_dwordx4 v[62:65], v[68:69], off offset:16
	s_ashr_i32 s95, s94, 31
	v_lshl_add_u64 v[66:67], v[66:67], 0, s[94:95]
	v_lshlrev_b64 v[66:67], 12, v[66:67]
	v_lshl_add_u64 v[66:67], s[68:69], 0, v[66:67]
	s_mov_b64 s[2:3], 0x1b900800
	v_lshl_add_u64 v[136:137], v[66:67], 0, s[2:3]
	v_add_u32_e32 v66, s74, v130
	v_ashrrev_i32_e32 v67, 31, v66
	v_lshlrev_b64 v[66:67], 12, v[66:67]
	s_ashr_i32 s75, s74, 31
	v_lshl_add_u64 v[138:139], s[68:69], 0, v[66:67]
	s_lshl_b64 s[10:11], s[74:75], 12
	s_mov_b64 s[12:13], 0
	s_movk_i32 s4, 0x27ff
	s_mov_b32 s14, 0x3fd744fd
	v_mov_b32_e32 v1, 0x3727c5ac
	s_mov_b32 s5, 0xf800000
	v_mov_b32_e32 v131, 0x260
	s_waitcnt vmcnt(10)
	v_mov_b64_e32 v[74:75], v[114:115]
	s_waitcnt vmcnt(9)
	v_mov_b64_e32 v[70:71], v[106:107]
	s_waitcnt vmcnt(8)
	v_mov_b64_e32 v[78:79], v[122:123]
	s_waitcnt vmcnt(7)
	v_mov_b64_e32 v[66:67], v[98:99]
	v_mov_b64_e32 v[68:69], v[100:101]
	s_waitcnt vmcnt(6)
	v_mov_b64_e32 v[94:95], v[126:127]
	s_waitcnt vmcnt(5)
	v_mov_b64_e32 v[82:83], v[102:103]
	s_waitcnt vmcnt(4)
	v_mov_b64_e32 v[90:91], v[118:119]
	s_waitcnt vmcnt(3)
	v_mov_b64_e32 v[86:87], v[110:111]
	v_mov_b64_e32 v[72:73], v[108:109]
	v_mov_b64_e32 v[76:77], v[116:117]
	v_mov_b64_e32 v[80:81], v[124:125]
	v_mov_b64_e32 v[84:85], v[104:105]
	v_mov_b64_e32 v[88:89], v[112:113]
	v_mov_b64_e32 v[92:93], v[120:121]
	v_mov_b64_e32 v[96:97], v[128:129]
	s_branch .LBB0_2200

; template <class Epi, class Sched, bool ABLK = false, bool ALIGN_EPI = true, bool SP2 = true, bool BBLK = true>
; __device__ __forceinline__ void gemm_phase(LAS unsigned char* lds, const Gemm g, const Sched& S, const Epi& E) {
;     const int tid = tid_fresh(), wid = __builtin_amdgcn_readfirstlane(tid >> 6), lane = tid & 63, wr = wid >> 2, wc = wid & 3, fr = lane & 15, fq = lane >> 4;
;     unsigned voffA[2], voffB[2];
; #pragma unroll
;     for (int i = 0; i < 2; ++i) { int R, C; stage_rc(tid * 16 + i * 8192, R, C); const int r32 = Epi::PERM ? perm32(R & 31) : (R & 31);
;         const int Rb = Epi::ADJ ? 64 * (R >> 5) + r32 : (R & ~31) + r32;
;         voffA[i] = (unsigned)(R * (ABLK ? 64 : g.lda) + C) * 2u; voffB[i] = BBLK ? (unsigned)(R * 64 + C) * 2u : (unsigned)(Rb * g.ldb + C) * 2u; }
;     const size_t kstep = (size_t)(BK * 2);
;     const size_t hstepA = (size_t)HALF * (ABLK ? 64 : g.lda) * 2, hstepB = BBLK ? (size_t)16384 : (size_t)(Epi::ADJ ? 32 : HALF) * g.ldb * 2;
;     const size_t tstepB = BBLK ? ((size_t)g.ldb / 64) * 32768 : (size_t)BM * g.ldb * 2;
;     const size_t kstepB = BBLK ? (size_t)32768 : kstep;
;     auto b_k0 = [&](int k0) -> size_t { return BBLK ? (size_t)(k0 / BK) * 32768 : (size_t)k0 * 2; };
;     const unsigned ldsw = (unsigned)wid * 1024u;
;     const int aoff = lds_byte(wr * 64 + fr, fq * 8), boff = lds_byte(wc * 32 + fr, fq * 8);
;     ...
;     Unit cur, nxt; int ui = 0;
;     if (!S.next(0, cur)) return;
;     f32x4 acc[2][2][4][2];
; #pragma unroll
;     for (int a = 0; a < 2; ++a)
; #pragma unroll
;         for (int b = 0; b < 2; ++b)
; #pragma unroll
;             for (int m = 0; m < 4; ++m)
; #pragma unroll
;                 for (int n = 0; n < 2; ++n) acc[a][b][m][n] = (f32x4){0.f, 0.f, 0.f, 0.f};
;     bf16x8 At[4][2], B0[2][2], B1[2][2];
;     auto a_unit = [&](const Unit& u) -> const char* { return ABLK ? (const char*)g.A + (size_t)u.pm * ((size_t)g.lda / 64) * 32768 : (const char*)g.A + (size_t)u.pm * 2 * hstepA; };
; template <int L> __device__ __forceinline__ void do_layer(const Args& a, LAS unsigned char* lds, const XcdBarrier& bar, int G, int b) {
;     ...
;     { pg8::Gemm g{XB, (const bf16_t*)(ws + WS_WF1) + (size_t)L * FF * D, D, D}; pg8::BStatOrder S; S.init(M, FF, D, b);
;       EpiFfn1 E{H}; pg8::gemm_phase<EpiFfn1, pg8::BStatOrder>(lds, g, S, E); }
.LBB0_2253:
	s_or_b64 exec, exec, s[10:11]
	s_waitcnt vmcnt(0)
	buffer_inv sc1
	s_waitcnt vmcnt(0)
.LBB0_2254:
	s_or_b64 exec, exec, s[2:3]
	v_readlane_b32 s2, v252, 26
	s_add_u32 s1, s68, 0x23100000
	s_waitcnt lgkmcnt(0)
	v_mov_b32_e32 v1, v0
	v_readlane_b32 s3, v252, 27
	s_addc_u32 s33, s69, 0
	s_barrier
	s_and_b64 vcc, exec, s[2:3]
	v_readfirstlane_b32 s2, v1
	s_cbranch_vccnz .LBB0_2270
	v_lshlrev_b32_e32 v2, 4, v1
	v_add_u32_e32 v3, 0x2000, v2
	v_ashrrev_i32_e32 v4, 31, v3
	v_lshrrev_b32_e32 v4, 22, v4
	v_add_u32_e32 v4, v3, v4
	v_ashrrev_i32_e32 v6, 10, v4
	v_mul_i32_i24_e32 v5, 0x400, v6
	v_sub_u32_e32 v3, v3, v5
	v_lshrrev_b32_e32 v5, 4, v3
	v_bitop3_b32 v3, v5, v3, 32 bitop3:0x6c
	v_ashrrev_i32_e32 v5, 31, v3
	v_lshrrev_b32_e32 v5, 26, v5
	v_add_u32_e32 v5, v3, v5
	v_ashrrev_i32_e32 v7, 6, v5
	v_and_b32_e32 v5, 0xc0, v5
	v_sub_u32_e32 v3, v3, v5
	v_mov_b32_e32 v5, 1
	v_lshlrev_b32_e32 v4, 5, v6
	v_ashrrev_i16_sdwa v3, v5, sext(v3) dst_sel:DWORD dst_unused:UNUSED_PAD src0_sel:DWORD src1_sel:BYTE_0
	v_and_b32_e32 v4, 32, v4
	v_bfe_i32 v8, v3, 0, 16
	v_add_u32_e32 v3, v4, v8
	v_lshlrev_b32_e32 v4, 3, v6
	v_and_b32_e32 v4, -16, v4
	v_add_u32_e32 v4, v7, v4
	v_lshlrev_b32_e32 v9, 7, v4
	v_lshl_add_u32 v130, v3, 1, v9
	s_movk_i32 s6, 0xf80
	v_mad_u64_u32 v[132:133], s[4:5], v4, s6, v[130:131]
	v_bfe_i32 v4, v1, 27, 1
	v_lshrrev_b32_e32 v4, 22, v4
	v_add_u32_e32 v4, v2, v4
	v_and_b32_e32 v4, 0xfffffc00, v4
	v_sub_u32_e32 v2, v2, v4
	v_lshrrev_b32_e32 v4, 4, v2
	v_bitop3_b32 v4, v4, v2, 32 bitop3:0x6c
	v_ashrrev_i32_e32 v2, 31, v2
	v_lshrrev_b32_e32 v2, 26, v2
	v_ashrrev_i32_e32 v3, 31, v1
	v_add_u32_e32 v2, v4, v2
	v_lshrrev_b32_e32 v3, 26, v3
	v_ashrrev_i32_e32 v10, 6, v2
	v_add_u32_e32 v3, v1, v3
	v_mul_i32_i24_e32 v2, 64, v10
	v_ashrrev_i32_e32 v9, 6, v3
	v_sub_u32_e32 v2, v4, v2
	v_lshlrev_b32_e32 v3, 5, v9
	v_ashrrev_i16_sdwa v2, v5, sext(v2) dst_sel:DWORD dst_unused:UNUSED_PAD src0_sel:DWORD src1_sel:BYTE_0
	v_and_b32_e32 v3, 32, v3
	v_bfe_i32 v11, v2, 0, 16
	v_add_u32_e32 v2, v3, v11
	v_lshlrev_b32_e32 v3, 3, v9
	v_and_b32_e32 v3, -16, v3
	s_add_u32 s38, s68, 0xc900000
	v_add_u32_e32 v3, v10, v3
	s_addc_u32 s39, s69, 0
	s_ashr_i32 s10, s2, 6
	v_lshlrev_b32_e32 v4, 7, v3
	s_ashr_i32 s3, s2, 8
	s_lshl_b32 s40, s10, 10
	v_lshl_add_u32 v134, v2, 1, v4
	s_add_u32 s41, s68, 0x1b900000
	v_mad_u64_u32 v[136:137], s[4:5], v3, s6, v[134:135]
	s_addc_u32 s42, s69, 0
	s_lshr_b32 s4, s70, 30
	s_add_i32 s4, s70, s4
	s_ashr_i32 s22, s4, 2
	s_sub_i32 s4, s63, s22
	s_lshl_b32 s4, s4, 2
	s_add_i32 s24, s4, s70
	s_ashr_i32 s23, s22, 31
	s_ashr_i32 s25, s24, 31
	s_lshl_b64 s[4:5], s[22:23], 20
	s_lshl_b64 s[6:7], s[24:25], 20
	s_add_u32 s28, s38, s6
	s_addc_u32 s29, s39, s7
	s_add_i32 s25, s40, 0
	s_add_i32 m0, s25, 0x10000
	v_mov_b32_e32 v139, 0
	global_load_lds_dwordx4 v134, s[28:29]
	s_add_i32 m0, s25, 0x12000
	s_add_u32 s6, s28, 0x4000
	global_load_lds_dwordx4 v130, s[28:29]
	s_addc_u32 s7, s29, 0
	s_add_i32 m0, s25, 0x14000
	v_mov_b32_e32 v137, v139
	global_load_lds_dwordx4 v134, s[6:7]
	s_add_i32 m0, s25, 0x16000
	s_add_u32 s26, s41, s4
	s_addc_u32 s27, s42, s5
	s_add_i32 s43, s25, 0x2000
	global_load_lds_dwordx4 v130, s[6:7]
	s_mov_b32 m0, s25
	s_add_u32 s4, s26, 0x80000
	global_load_lds_dwordx4 v136, s[26:27]
	s_mov_b32 m0, s43
	s_addc_u32 s5, s27, 0
	s_add_i32 s44, s25, 0x4000
	global_load_lds_dwordx4 v132, s[26:27]
	s_mov_b32 m0, s44
	s_add_i32 s45, s25, 0x6000
	global_load_lds_dwordx4 v136, s[4:5]
	s_mov_b32 m0, s45
	v_mov_b32_e32 v133, v139
	global_load_lds_dwordx4 v132, s[4:5]
	s_cmp_eq_u32 s3, 1
	s_mov_b32 s46, 0
	v_mov_b32_e32 v135, v139
	v_mov_b32_e32 v131, v139
	s_mov_b64 s[4:5], 0x4000
	v_lshl_add_u64 v[2:3], s[26:27], 0, v[136:137]
	s_cselect_b64 s[6:7], -1, 0
	s_cmp_lg_u32 s3, 1
	v_lshl_add_u64 v[4:5], s[26:27], 0, v[132:133]
	s_cbranch_scc1 .LBB0_2257
	s_barrier

;     __host__ __device__ bool next(int r, Unit& u) const {
;         const int gidx = 4 * x + (i >> 3);
;         if (r == 0) { u.pm = gidx; u.pn = i & 7; u.k0 = 0; u.nt = ntf; u.part = 0; return true; }
;         if (r == 1) { const int part = gidx & 3; u.pm = 32 + (gidx >> 2); u.pn = i & 7; u.nt = ntf >> 2; u.k0 = part * (ntf >> 2) * BK; u.part = part; return true; }
;         return false;
;     }
; template <int L> __device__ __forceinline__ void do_layer(const Args& a, LAS unsigned char* lds, const XcdBarrier& bar, int G, int b) {
;     ...
;     { pg8::Gemm g{H, (const bf16_t*)(ws + WS_WF2) + (size_t)L * FF * D, FF, FF}; pg8::SplitOrder S; S.init(FF, b);
;       EpiRes E{Z, PS}; pg8::gemm_phase<EpiRes, pg8::SplitOrder, true>(lds, g, S, E); }
.LBB0_2319:
	s_or_b64 exec, exec, s[4:5]
	s_mov_b64 s[4:5], exec
	v_mbcnt_lo_u32_b32 v1, s4, 0
	v_mbcnt_hi_u32_b32 v1, s5, v1
	v_cmp_eq_u32_e32 vcc, 0, v1
	s_and_saveexec_b64 s[10:11], vcc
	s_cbranch_execz .LBB0_2321
	s_bcnt1_i32_b64 s4, s[4:5]
	v_mov_b32_e32 v1, 0x2000
	v_mov_b32_e32 v2, s4
	global_atomic_add v1, v2, s[6:7] offset:1024
.LBB0_2321:
	s_or_b64 exec, exec, s[10:11]
	s_waitcnt vmcnt(0)
	buffer_inv sc1
	s_waitcnt vmcnt(0)
.LBB0_2322:
	s_or_b64 exec, exec, s[2:3]
	v_mov_b32_e32 v4, v0
	s_waitcnt lgkmcnt(0)
	s_barrier
	s_add_u32 s46, s68, 0x14900000
	v_bfe_i32 v3, v4, 27, 1
	v_lshlrev_b32_e32 v1, 4, v4
	v_lshrrev_b32_e32 v3, 22, v3
	v_add_u32_e32 v3, v1, v3
	v_and_b32_e32 v3, 0xfffffc00, v3
	v_sub_u32_e32 v3, v1, v3
	v_lshrrev_b32_e32 v5, 4, v3
	v_bitop3_b32 v5, v5, v3, 32 bitop3:0x6c
	v_ashrrev_i32_e32 v3, 31, v3
	v_lshrrev_b32_e32 v3, 26, v3
	v_ashrrev_i32_e32 v2, 31, v4
	v_add_u32_e32 v3, v5, v3
	v_lshrrev_b32_e32 v2, 26, v2
	v_ashrrev_i32_e32 v3, 6, v3
	v_add_u32_e32 v2, v4, v2
	v_mul_i32_i24_e32 v8, 64, v3
	v_ashrrev_i32_e32 v2, 6, v2
	v_sub_u32_e32 v5, v5, v8
	v_mov_b32_e32 v8, 1
	v_lshlrev_b32_e32 v6, 3, v2
	v_lshlrev_b32_e32 v7, 5, v2
	v_ashrrev_i16_sdwa v5, v8, sext(v5) dst_sel:DWORD dst_unused:UNUSED_PAD src0_sel:DWORD src1_sel:BYTE_0
	v_and_b32_e32 v6, 0x1fffff0, v6
	v_and_b32_e32 v7, 32, v7
	v_bfe_i32 v5, v5, 0, 16
	v_add_u32_e32 v7, v7, v5
	v_add_lshl_u32 v6, v3, v6, 7
	v_add_u32_e32 v1, 0x2000, v1
	v_lshl_add_u32 v130, v7, 1, v6
	v_ashrrev_i32_e32 v6, 31, v1
	v_lshrrev_b32_e32 v6, 22, v6
	v_add_u32_e32 v6, v1, v6
	v_ashrrev_i32_e32 v6, 10, v6
	v_mul_i32_i24_e32 v7, 0x400, v6
	v_sub_u32_e32 v1, v1, v7
	v_lshrrev_b32_e32 v7, 4, v1
	v_bitop3_b32 v1, v7, v1, 32 bitop3:0x6c
	v_lshlrev_b32_e32 v7, 3, v6
	v_and_b32_e32 v9, 0x1fffff0, v7
	v_ashrrev_i32_e32 v7, 31, v1
	v_readfirstlane_b32 s2, v4
	v_lshrrev_b32_e32 v7, 26, v7
	s_addc_u32 s47, s69, 0
	s_ashr_i32 s4, s2, 6
	v_add_u32_e32 v10, v1, v7
	v_ashrrev_i32_e32 v7, 6, v10
	v_and_b32_e32 v10, 0xc0, v10
	s_ashr_i32 s3, s2, 8
	s_lshl_b32 s48, s4, 10
	v_readlane_b32 s5, v252, 16
	v_sub_u32_e32 v1, v1, v10
	s_add_u32 s38, s46, s5
	v_lshlrev_b32_e32 v11, 5, v6
	v_ashrrev_i16_sdwa v1, v8, sext(v1) dst_sel:DWORD dst_unused:UNUSED_PAD src0_sel:DWORD src1_sel:BYTE_0
	s_addc_u32 s39, s47, 0
	s_add_i32 s49, s48, 0
	v_and_b32_e32 v11, 32, v11
	v_bfe_i32 v8, v1, 0, 16
	s_add_i32 m0, s49, 0x10000
	v_add_u32_e32 v1, v11, v8
	v_add_lshl_u32 v9, v7, v9, 7
	global_load_lds_dwordx4 v130, s[38:39]
	s_add_i32 m0, s49, 0x12000
	v_lshl_add_u32 v132, v1, 1, v9
	s_add_u32 s6, s38, 0x4000
	global_load_lds_dwordx4 v132, s[38:39]
	s_addc_u32 s7, s39, 0
	s_add_i32 m0, s49, 0x14000
	v_mov_b32_e32 v131, 0
	global_load_lds_dwordx4 v130, s[6:7]
	s_add_i32 m0, s49, 0x16000
	s_mov_b32 s55, 0
	global_load_lds_dwordx4 v132, s[6:7]
	v_readlane_b32 s6, v252, 17
	v_readlane_b32 s7, v252, 18
	s_add_u32 s40, s1, s6
	s_addc_u32 s41, s33, s7
	s_add_i32 s50, s49, 0x2000
	s_mov_b32 m0, s49
	s_add_u32 s6, s40, 0x4000
	global_load_lds_dwordx4 v130, s[40:41]
	s_mov_b32 m0, s50
	s_addc_u32 s7, s41, 0
	s_add_i32 s51, s49, 0x4000
	global_load_lds_dwordx4 v132, s[40:41]
	s_mov_b32 m0, s51
	s_add_i32 s52, s49, 0x6000
	global_load_lds_dwordx4 v130, s[6:7]
	s_mov_b32 m0, s52
	s_cmp_eq_u32 s3, 1
	global_load_lds_dwordx4 v132, s[6:7]
	s_cselect_b64 s[10:11], -1, 0
	s_cmp_lg_u32 s3, 1
	v_mov_b32_e32 v133, v131
	s_cbranch_scc1 .LBB0_2324
	s_barrier

; __device__ __forceinline__ void ph_ln(const Args& a, int L, int which, bool final_, bool split, bool wr_x, bool res_inputs, int nblk, int b) {
;     unsigned char* ws = a.ws; const bf16_t* P = (const bf16_t*)(ws + WS_SCR + SCR_PART);
;     const bf16_t* Z = (const bf16_t*)(ws + WS_Z); float* Xo = final_ ? a.out : (float*)(ws + WS_X); bf16_t* XB = (bf16_t*)(ws + WS_XB);
;     auto lo = [](unsigned w) -> float { return __builtin_bit_cast(float, w << 16); }; auto hi = [](unsigned w) -> float { return __builtin_bit_cast(float, w & 0xffff0000u); };
;     const float* gam = a.in[which ? 26 : 24] + (size_t)L * D; const float* bet = a.in[which ? 27 : 25] + (size_t)L * D;
;     const int tid = tid_fresh(); const int lane = tid & 63, gw = b * 8 + (tid >> 6), ngw = nblk * 8;
;     f32x4 gg[4][2], bb[4][2];
; #pragma unroll
;     for (int j = 0; j < 4; ++j)
; #pragma unroll
;         for (int h = 0; h < 2; ++h) { gg[j][h] = *(const f32x4*)(gam + 512 * j + 8 * lane + 4 * h); bb[j][h] = *(const f32x4*)(bet + 512 * j + 8 * lane + 4 * h); }
;     u32x4 zc[4], xc[4];
;     auto ldrow = [&](int r) { const u32x4* zr = (const u32x4*)(Z + (size_t)r * D) + lane;
; #pragma unroll
;         for (int j = 0; j < 4; ++j) zc[j] = zr[64 * j];
;         if (!res_inputs) { const u32x4* xr = (const u32x4*)(XB + (size_t)r * D) + lane;
; #pragma unroll
;             for (int j = 0; j < 4; ++j) xc[j] = xr[64 * j]; } };
;     if (gw < M) ldrow(gw);
;     for (int r = gw; r < M; r += ngw) {
;         float v[4][8];
; #pragma unroll
;         for (int j = 0; j < 4; ++j)
; #pragma unroll
;             for (int e = 0; e < 4; ++e) { v[j][2 * e] = lo(zc[j][e]); v[j][2 * e + 1] = hi(zc[j][e]); }
;         if (!res_inputs) {
; #pragma unroll
;             for (int j = 0; j < 4; ++j)
; #pragma unroll
;                 for (int e = 0; e < 4; ++e) { v[j][2 * e] += ALPHA * lo(xc[j][e]); v[j][2 * e + 1] += ALPHA * hi(xc[j][e]); } }
;         if (r + ngw < M) ldrow(r + ngw);
;         if (split && r >= MP) {
; #pragma unroll
;             for (int p = 0; p < 3; ++p) { const u32x4* pr = (const u32x4*)(P + ((size_t)p * MS + (r - MP)) * D) + lane;
; #pragma unroll
;                 for (int j = 0; j < 4; ++j) { const u32x4 w = pr[64 * j];
; #pragma unroll
;                     for (int e = 0; e < 4; ++e) { v[j][2 * e] += lo(w[e]); v[j][2 * e + 1] += hi(w[e]); } } } }
.LBB0_2383:
	s_or_b64 exec, exec, s[0:1]
	s_mov_b64 s[0:1], exec
	v_mbcnt_lo_u32_b32 v1, s0, 0
	v_mbcnt_hi_u32_b32 v1, s1, v1
	v_cmp_eq_u32_e32 vcc, 0, v1
	s_and_saveexec_b64 s[6:7], vcc
	s_cbranch_execz .LBB0_2385
	s_bcnt1_i32_b64 s0, s[0:1]
	v_mov_b32_e32 v1, 0x2000
	v_mov_b32_e32 v2, s0
	global_atomic_add v1, v2, s[4:5] offset:1024
.LBB0_2385:
	s_or_b64 exec, exec, s[6:7]
	s_waitcnt vmcnt(0)
	buffer_inv sc1
	s_waitcnt vmcnt(0)
.LBB0_2386:
	s_or_b64 exec, exec, s[2:3]
	s_waitcnt lgkmcnt(0)
	s_barrier
	s_movk_i32 s11, 0x2800
	v_ashrrev_i32_e32 v64, 6, v0
	v_add_u32_e32 v152, s94, v64
	v_cmp_gt_i32_e32 vcc, s11, v152
	s_and_saveexec_b64 s[0:1], vcc
	s_cbranch_execz .LBB0_2393
	s_load_dwordx4 s[0:3], s[86:87], 0xd0
	v_and_b32_e32 v58, 63, v0
	v_mov_b32_e32 v129, 0
	v_lshlrev_b32_e32 v128, 5, v58
	s_mov_b64 s[4:5], 0x7800
	s_waitcnt lgkmcnt(0)
	v_lshl_add_u64 v[40:41], s[2:3], 0, v[128:129]
	v_add_co_u32_e32 v12, vcc, 0x7000, v40
	v_lshl_add_u64 v[54:55], s[0:1], 0, v[128:129]
	s_nop 0
	v_addc_co_u32_e32 v13, vcc, 0, v41, vcc
	v_add_co_u32_e32 v46, vcc, 0x7000, v54
	s_mov_b64 s[0:1], 0x7000
	s_nop 0
	v_addc_co_u32_e32 v47, vcc, 0, v55, vcc
	v_lshl_add_u64 v[14:15], v[40:41], 0, s[0:1]
	v_lshl_add_u64 v[48:49], v[54:55], 0, s[0:1]
	s_movk_i32 s0, 0x6000
	s_mov_b64 s[2:3], 0x6000
	v_add_co_u32_e32 v56, vcc, s0, v40
	v_lshl_add_u64 v[52:53], v[40:41], 0, s[2:3]
	v_lshl_add_u64 v[42:43], v[40:41], 0, s[4:5]
	v_lshl_add_u64 v[44:45], v[54:55], 0, s[4:5]
	v_addc_co_u32_e32 v57, vcc, 0, v41, vcc
	v_ashrrev_i32_e32 v153, 31, v152
	v_readlane_b32 s4, v252, 19
	v_lshl_add_u64 v[66:67], v[54:55], 0, s[2:3]
	global_load_dwordx4 v[0:3], v[12:13], off offset:2048
	global_load_dwordx4 v[4:7], v[12:13], off
	global_load_dwordx4 v[8:11], v[14:15], off offset:16
	s_nop 0
	global_load_dwordx4 v[12:15], v[46:47], off offset:2048
	global_load_dwordx4 v[16:19], v[46:47], off
	global_load_dwordx4 v[20:23], v[48:49], off offset:16
	global_load_dwordx4 v[24:27], v[42:43], off offset:16
	global_load_dwordx4 v[28:31], v[52:53], off offset:2064
	global_load_dwordx4 v[32:35], v[44:45], off offset:16
	global_load_dwordx4 v[36:39], v[66:67], off offset:2064
	s_nop 0
	global_load_dwordx4 v[40:43], v[56:57], off
	global_load_dwordx4 v[44:47], v[52:53], off offset:2048
	global_load_dwordx4 v[48:51], v[52:53], off offset:16
	v_lshlrev_b64 v[52:53], 12, v[152:153]
	v_readlane_b32 s6, v252, 21
	v_readlane_b32 s7, v252, 22
	v_lshlrev_b32_e32 v70, 4, v58
	v_mov_b32_e32 v71, v129
	v_lshl_add_u64 v[52:53], s[6:7], 0, v[52:53]
	v_add_co_u32_e32 v68, vcc, s0, v54
	v_lshl_add_u64 v[52:53], v[52:53], 0, v[70:71]
	s_mov_b64 s[0:1], 0x1e100000
	v_addc_co_u32_e32 v69, vcc, 0, v55, vcc
	v_lshl_add_u64 v[54:55], v[52:53], 0, s[0:1]
	s_mov_b32 s0, 0x1e100000
	v_add_co_u32_e32 v56, vcc, s0, v52
	s_mov_b64 s[0:1], 0x1b900000
	s_nop 0
	v_addc_co_u32_e32 v57, vcc, 0, v53, vcc
	global_load_dwordx4 v[112:115], v[54:55], off offset:1024
	global_load_dwordx4 v[104:107], v[54:55], off offset:2048
	global_load_dwordx4 v[120:123], v[56:57], off
	global_load_dwordx4 v[96:99], v[54:55], off offset:3072
	v_lshl_add_u64 v[72:73], v[52:53], 0, s[0:1]
	s_mov_b32 s0, 0x1b900000
	v_add_co_u32_e32 v74, vcc, s0, v52
	v_ashrrev_i32_e32 v65, 31, v64
	s_nop 0
	v_addc_co_u32_e32 v75, vcc, 0, v53, vcc
	global_load_dwordx4 v[124:127], v[74:75], off
	global_load_dwordx4 v[100:103], v[72:73], off offset:3072
	global_load_dwordx4 v[116:119], v[72:73], off offset:1024
	global_load_dwordx4 v[108:111], v[72:73], off offset:2048
	global_load_dwordx4 v[52:55], v[68:69], off
	global_load_dwordx4 v[56:59], v[66:67], off offset:2048
	global_load_dwordx4 v[60:63], v[66:67], off offset:16
	s_ashr_i32 s95, s94, 31
	v_lshl_add_u64 v[64:65], v[64:65], 0, s[94:95]
	v_lshlrev_b64 v[64:65], 13, v[64:65]
	v_readlane_b32 s5, v252, 20
	v_lshl_add_u64 v[66:67], s[6:7], 0, v[70:71]
	s_mov_b64 s[0:1], 0x3c900000
	v_or_b32_e32 v64, v64, v128
	v_lshl_add_u64 v[130:131], v[66:67], 0, s[0:1]
	v_lshl_add_u64 v[64:65], s[4:5], 0, v[64:65]
	s_mov_b64 s[0:1], 0x1000
	v_lshl_add_u64 v[132:133], v[64:65], 0, s[0:1]
	v_add_u32_e32 v64, s74, v152
	v_ashrrev_i32_e32 v65, 31, v64
	v_lshlrev_b64 v[64:65], 12, v[64:65]
	v_or_b32_e32 v64, v64, v70
	v_lshl_add_u64 v[64:65], s[6:7], 0, v[64:65]
	s_mov_b64 s[0:1], 0x1e100c00
	s_ashr_i32 s75, s74, 31
	v_lshl_add_u64 v[134:135], v[64:65], 0, s[0:1]
	s_lshl_b64 s[4:5], s[74:75], 13
	s_lshl_b64 s[6:7], s[74:75], 12
	s_mov_b64 s[8:9], 0
	s_movk_i32 s12, 0x27ff
	s_mov_b32 s10, 0x3fd744fd
	s_movk_i32 s13, 0x1fff
	s_mov_b32 s14, 0x800000
	s_mov_b32 s15, 0x1000000
	v_mov_b32_e32 v153, 0x3727c5ac
	s_mov_b32 s16, 0xf800000
	v_mov_b32_e32 v154, 0x260
	s_waitcnt vmcnt(10)
	v_mov_b64_e32 v[72:73], v[112:113]
	s_waitcnt vmcnt(9)
	v_mov_b64_e32 v[68:69], v[104:105]
	s_waitcnt vmcnt(8)
	v_mov_b64_e32 v[76:77], v[120:121]
	s_waitcnt vmcnt(7)
	v_mov_b64_e32 v[64:65], v[96:97]
	v_mov_b64_e32 v[66:67], v[98:99]
	s_waitcnt vmcnt(6)
	v_mov_b64_e32 v[92:93], v[124:125]
	s_waitcnt vmcnt(5)
	v_mov_b64_e32 v[80:81], v[100:101]
	s_waitcnt vmcnt(4)
	v_mov_b64_e32 v[88:89], v[116:117]
	s_waitcnt vmcnt(3)
	v_mov_b64_e32 v[84:85], v[108:109]
	v_mov_b64_e32 v[70:71], v[106:107]
	v_mov_b64_e32 v[74:75], v[114:115]
	v_mov_b64_e32 v[78:79], v[122:123]
	v_mov_b64_e32 v[82:83], v[102:103]
	v_mov_b64_e32 v[86:87], v[110:111]
	v_mov_b64_e32 v[90:91], v[118:119]
	v_mov_b64_e32 v[94:95], v[126:127]
	s_branch .LBB0_2389
